# combined: v42 + idx_select row-pair hop via permlane16_swap + snake dealing of idx units + post-epilogue wait skip + global_* epilogue accesses
# speedup vs baseline: 1.0112x; 1.0038x over previous
; __device__ __forceinline__ void idx_unit(unsigned char* lds, const bf16_t* P, int b, int qb16, unsigned* bits) {
;     int tid_o = threadIdx.x; asm volatile("" : "+v"(tid_o));
;     const int tid = tid_o, lane = tid & 63, wid = __builtin_amdgcn_readfirstlane(tid >> 6), r32 = lane & 31, hi = lane >> 5;
;     unsigned short* sc = (unsigned short*)lds;
;     float* wl = (float*)(lds + 131072);
;     const int t0 = qb16 * 16; const size_t tokb = (size_t)b * SEQ, tok0 = tokb + t0;
;     const int nscan = ((t0 + 16 + 511) >> 9) << 9;
;     const int ncomp = ((t0 + 16 + 31) / 32);
;     const int nblk = ncomp;
;     if (tid < 128) wl[tid] = bf2f(P[(tok0 + (tid >> 3)) * PW + P_IW + (tid & 7)]) * (0.35355339059327373f * 0.125f);
; __global__ void __launch_bounds__(512, 2) fwd_kernel(Args a) {
;     ...
;         for (int it = cb_; it < 4096; it += G) idx_unit(lds, P, it & 15, it >> 4, BITS);
.LBB0_394:
	s_and_b32 s8, s76, -16
	s_bitcmp1_b32 s76, 8
	s_cselect_b32 s0, 0xf0, 0
	s_xor_b32 s8, s8, s0
	s_lshl_b32 s0, s76, 12
	s_and_b32 s64, s0, 0xf000
	s_ashr_i32 s0, s8, 31
	s_add_u32 s70, s64, s8
	v_mov_b32_e32 v182, v228
	s_addc_u32 s71, 0, s0
	s_movk_i32 s0, 0x80
	s_nop 0
	v_readfirstlane_b32 s4, v182
	v_cmp_gt_i32_e32 vcc, s0, v182
	s_and_saveexec_b64 s[0:1], vcc
	s_cbranch_execz .LBB0_396
	v_ashrrev_i32_e32 v2, 3, v182
	v_ashrrev_i32_e32 v3, 31, v2
	v_lshl_add_u64 v[2:3], s[70:71], 0, v[2:3]
	v_mov_b64_e32 v[4:5], s[46:47]
	v_and_b32_e32 v0, 7, v182
	v_mad_u64_u32 v[4:5], s[6:7], v2, s37, v[4:5]
	v_mad_i32_i24 v5, v3, s37, v5
	v_lshlrev_b32_e32 v0, 1, v0
	v_lshl_add_u64 v[2:3], v[4:5], 0, v[0:1]
	v_add_co_u32_e32 v2, vcc, 0x1000, v2
	s_nop 1
	v_addc_co_u32_e32 v3, vcc, 0, v3, vcc
	global_load_ushort v0, v[2:3], off offset:1152
	v_lshl_add_u32 v2, v182, 2, 0
	v_add_u32_e32 v2, 0x20000, v2
	s_waitcnt vmcnt(0)
	v_lshlrev_b32_e32 v0, 16, v0
	v_mul_f32_e32 v0, 0x3d3504f3, v0
	ds_write_b32 v2, v0

; __device__ __forceinline__ int red32(int v) {
;     v += __builtin_amdgcn_mov_dpp(v, 0xB1, 0xf, 0xf, true);
;     v += __builtin_amdgcn_mov_dpp(v, 0x4E, 0xf, 0xf, true);
;     v += __builtin_amdgcn_mov_dpp(v, 0x141, 0xf, 0xf, true);
;     v += __builtin_amdgcn_mov_dpp(v, 0x140, 0xf, 0xf, true);
;     v += __builtin_amdgcn_ds_swizzle(v, 0x401F);
;     return v;
; }
; template <int NCH>
; __device__ __forceinline__ void idx_select(const unsigned short* sc, unsigned* bits, size_t tok0, int tid) {
;     ...
; #pragma unroll 1
;     for (int it = 0; it < 16; ++it) { const unsigned mid = (lo + hi_ + 1u) >> 1, mid2 = mid | (mid << 16);
;         unsigned c2a = 0u, c2b = 0u;
; #pragma unroll
;         for (int i = 0; i < 4 * NCH; i += 2) { pk_cnt_lt(c2a, kw[i], mid2, one2); pk_cnt_lt(c2b, kw[i + 1], mid2, one2); }
;         int cnt = 8 * NCH - (int)((c2a & 0xFFFFu) + (c2a >> 16) + (c2b & 0xFFFFu) + (c2b >> 16));
;         cnt = red32(cnt);
;         if (cnt >= 256) lo = mid; else hi_ = mid - 1u;
;         if (cnt == 256) hi_ = mid;
;         if (__all(lo == hi_)) break; }
.LBB0_417:
	v_add3_u32 v60, v0, v59, 1
	v_lshrrev_b32_e32 v60, 1, v60
	v_mov_b32_e32 v62, 0
	v_lshl_or_b32 v61, v60, 16, v60
	s_waitcnt lgkmcnt(13)
	v_pk_sub_u16 v63, v61, v6 clamp
	v_pk_min_u16 v63, v63, v235
	v_pk_add_u16 v62, v62, v63
	s_nop 0
	v_mov_b32_e32 v63, 0
	v_pk_sub_u16 v64, v61, v7 clamp
	v_pk_min_u16 v64, v64, v235
	v_pk_add_u16 v63, v63, v64
	v_pk_sub_u16 v64, v61, v8 clamp
	v_pk_min_u16 v64, v64, v235
	v_pk_add_u16 v62, v62, v64
	v_pk_sub_u16 v64, v61, v9 clamp
	v_pk_min_u16 v64, v64, v235
	v_pk_add_u16 v63, v63, v64
	s_waitcnt lgkmcnt(12)
	v_pk_sub_u16 v64, v61, v2 clamp
	v_pk_min_u16 v64, v64, v235
	v_pk_add_u16 v62, v62, v64
	v_pk_sub_u16 v64, v61, v3 clamp
	v_pk_min_u16 v64, v64, v235
	v_pk_add_u16 v63, v63, v64
	v_pk_sub_u16 v64, v61, v4 clamp
	v_pk_min_u16 v64, v64, v235
	v_pk_add_u16 v62, v62, v64
	v_pk_sub_u16 v64, v61, v5 clamp
	v_pk_min_u16 v64, v64, v235
	v_pk_add_u16 v63, v63, v64
	s_waitcnt lgkmcnt(11)
	v_pk_sub_u16 v64, v61, v54 clamp
	v_pk_min_u16 v64, v64, v235
	v_pk_add_u16 v62, v62, v64
	v_pk_sub_u16 v64, v61, v55 clamp
	v_pk_min_u16 v64, v64, v235
	v_pk_add_u16 v63, v63, v64
	v_pk_sub_u16 v64, v61, v56 clamp
	v_pk_min_u16 v64, v64, v235
	v_pk_add_u16 v62, v62, v64
	v_pk_sub_u16 v64, v61, v57 clamp
	v_pk_min_u16 v64, v64, v235
	v_pk_add_u16 v63, v63, v64
	s_waitcnt lgkmcnt(10)
	v_pk_sub_u16 v64, v61, v50 clamp
	v_pk_min_u16 v64, v64, v235
	v_pk_add_u16 v62, v62, v64
	v_pk_sub_u16 v64, v61, v51 clamp
	v_pk_min_u16 v64, v64, v235
	v_pk_add_u16 v63, v63, v64
	v_pk_sub_u16 v64, v61, v52 clamp
	v_pk_min_u16 v64, v64, v235
	v_pk_add_u16 v62, v62, v64
	v_pk_sub_u16 v64, v61, v53 clamp
	v_pk_min_u16 v64, v64, v235
	v_pk_add_u16 v63, v63, v64
	s_waitcnt lgkmcnt(9)
	v_pk_sub_u16 v64, v61, v46 clamp
	v_pk_min_u16 v64, v64, v235
	v_pk_add_u16 v62, v62, v64
	v_pk_sub_u16 v64, v61, v47 clamp
	v_pk_min_u16 v64, v64, v235
	v_pk_add_u16 v63, v63, v64
	v_pk_sub_u16 v64, v61, v48 clamp
	v_pk_min_u16 v64, v64, v235
	v_pk_add_u16 v62, v62, v64
	v_pk_sub_u16 v64, v61, v49 clamp
	v_pk_min_u16 v64, v64, v235
	v_pk_add_u16 v63, v63, v64
	s_waitcnt lgkmcnt(8)
	v_pk_sub_u16 v64, v61, v42 clamp
	v_pk_min_u16 v64, v64, v235
	v_pk_add_u16 v62, v62, v64
	v_pk_sub_u16 v64, v61, v43 clamp
	v_pk_min_u16 v64, v64, v235
	v_pk_add_u16 v63, v63, v64
	v_pk_sub_u16 v64, v61, v44 clamp
	v_pk_min_u16 v64, v64, v235
	v_pk_add_u16 v62, v62, v64
	v_pk_sub_u16 v64, v61, v45 clamp
	v_pk_min_u16 v64, v64, v235
	v_pk_add_u16 v63, v63, v64
	s_waitcnt lgkmcnt(7)
	v_pk_sub_u16 v64, v61, v38 clamp
	v_pk_min_u16 v64, v64, v235
	v_pk_add_u16 v62, v62, v64
	v_pk_sub_u16 v64, v61, v39 clamp
	v_pk_min_u16 v64, v64, v235
	v_pk_add_u16 v63, v63, v64
	v_pk_sub_u16 v64, v61, v40 clamp
	v_pk_min_u16 v64, v64, v235
	v_pk_add_u16 v62, v62, v64
	v_pk_sub_u16 v64, v61, v41 clamp
	v_pk_min_u16 v64, v64, v235
	v_pk_add_u16 v63, v63, v64
	s_waitcnt lgkmcnt(6)
	v_pk_sub_u16 v64, v61, v34 clamp
	v_pk_min_u16 v64, v64, v235
	v_pk_add_u16 v62, v62, v64
	v_pk_sub_u16 v64, v61, v35 clamp
	v_pk_min_u16 v64, v64, v235
	v_pk_add_u16 v63, v63, v64
	v_pk_sub_u16 v64, v61, v36 clamp
	v_pk_min_u16 v64, v64, v235
	v_pk_add_u16 v62, v62, v64
	v_pk_sub_u16 v64, v61, v37 clamp
	v_pk_min_u16 v64, v64, v235
	v_pk_add_u16 v63, v63, v64
	s_waitcnt lgkmcnt(5)
	v_pk_sub_u16 v64, v61, v30 clamp
	v_pk_min_u16 v64, v64, v235
	v_pk_add_u16 v62, v62, v64
	v_pk_sub_u16 v64, v61, v31 clamp
	v_pk_min_u16 v64, v64, v235
	v_pk_add_u16 v63, v63, v64
	v_pk_sub_u16 v64, v61, v32 clamp
	v_pk_min_u16 v64, v64, v235
	v_pk_add_u16 v62, v62, v64
	v_pk_sub_u16 v64, v61, v33 clamp
	v_pk_min_u16 v64, v64, v235
	v_pk_add_u16 v63, v63, v64
	s_waitcnt lgkmcnt(4)
	v_pk_sub_u16 v64, v61, v26 clamp
	v_pk_min_u16 v64, v64, v235
	v_pk_add_u16 v62, v62, v64
	v_pk_sub_u16 v64, v61, v27 clamp
	v_pk_min_u16 v64, v64, v235
	v_pk_add_u16 v63, v63, v64
	v_pk_sub_u16 v64, v61, v28 clamp
	v_pk_min_u16 v64, v64, v235
	v_pk_add_u16 v62, v62, v64
	v_pk_sub_u16 v64, v61, v29 clamp
	v_pk_min_u16 v64, v64, v235
	v_pk_add_u16 v63, v63, v64
	s_waitcnt lgkmcnt(3)
	v_pk_sub_u16 v64, v61, v22 clamp
	v_pk_min_u16 v64, v64, v235
	v_pk_add_u16 v62, v62, v64
	v_pk_sub_u16 v64, v61, v23 clamp
	v_pk_min_u16 v64, v64, v235
	v_pk_add_u16 v63, v63, v64
	v_pk_sub_u16 v64, v61, v24 clamp
	v_pk_min_u16 v64, v64, v235
	v_pk_add_u16 v62, v62, v64
	v_pk_sub_u16 v64, v61, v25 clamp
	v_pk_min_u16 v64, v64, v235
	v_pk_add_u16 v63, v63, v64
	s_waitcnt lgkmcnt(2)
	v_pk_sub_u16 v64, v61, v18 clamp
	v_pk_min_u16 v64, v64, v235
	v_pk_add_u16 v62, v62, v64
	v_pk_sub_u16 v64, v61, v19 clamp
	v_pk_min_u16 v64, v64, v235
	v_pk_add_u16 v63, v63, v64
	v_pk_sub_u16 v64, v61, v20 clamp
	v_pk_min_u16 v64, v64, v235
	v_pk_add_u16 v62, v62, v64
	v_pk_sub_u16 v64, v61, v21 clamp
	v_pk_min_u16 v64, v64, v235
	v_pk_add_u16 v63, v63, v64
	s_waitcnt lgkmcnt(1)
	v_pk_sub_u16 v64, v61, v14 clamp
	v_pk_min_u16 v64, v64, v235
	v_pk_add_u16 v62, v62, v64
	v_pk_sub_u16 v64, v61, v15 clamp
	v_pk_min_u16 v64, v64, v235
	v_pk_add_u16 v63, v63, v64
	v_pk_sub_u16 v64, v61, v16 clamp
	v_pk_min_u16 v64, v64, v235
	v_pk_add_u16 v62, v62, v64
	v_pk_sub_u16 v64, v61, v17 clamp
	v_pk_min_u16 v64, v64, v235
	v_pk_add_u16 v63, v63, v64
	s_waitcnt lgkmcnt(0)
	v_pk_sub_u16 v64, v61, v10 clamp
	v_pk_min_u16 v64, v64, v235
	v_pk_add_u16 v62, v62, v64
	v_pk_sub_u16 v64, v61, v11 clamp
	v_pk_min_u16 v64, v64, v235
	v_pk_add_u16 v63, v63, v64
	v_pk_sub_u16 v64, v61, v12 clamp
	v_pk_min_u16 v64, v64, v235
	v_pk_add_u16 v62, v62, v64
	v_pk_sub_u16 v64, v61, v13 clamp
	v_pk_min_u16 v64, v64, v235
	v_pk_add_u16 v63, v63, v64
	v_add_u32_sdwa v62, v62, v62 dst_sel:DWORD dst_unused:UNUSED_PAD src0_sel:WORD_1 src1_sel:WORD_0
	v_and_b32_e32 v61, 0xffff, v63
	v_lshrrev_b32_e32 v63, 16, v63
	v_add3_u32 v61, v62, v61, v63
	v_sub_u32_e32 v61, 0x70, v61
	s_nop 1
	v_add_u32_dpp v61, v61, v61 quad_perm:[1,0,3,2] row_mask:0xf bank_mask:0xf bound_ctrl:1
	s_nop 1
	v_add_u32_dpp v61, v61, v61 quad_perm:[2,3,0,1] row_mask:0xf bank_mask:0xf bound_ctrl:1
	s_nop 1
	v_add_u32_dpp v61, v61, v61 row_half_mirror row_mask:0xf bank_mask:0xf bound_ctrl:1
	s_nop 1
	v_add_u32_dpp v61, v61, v61 row_mirror row_mask:0xf bank_mask:0xf bound_ctrl:1
	v_mov_b32_e32 v62, v61
	s_nop 1
	v_permlane16_swap_b32_e32 v62, v61
	s_waitcnt lgkmcnt(0)
	v_add_u32_e32 v61, v61, v62
	v_cmp_lt_i32_e32 vcc, s88, v61
	v_add_u32_e32 v62, -1, v60
	s_nop 0
	v_cndmask_b32_e32 v59, v62, v59, vcc
	v_cndmask_b32_e32 v0, v0, v60, vcc
	v_cmp_eq_u32_e32 vcc, s33, v61
	s_nop 1
	v_cndmask_b32_e32 v59, v59, v60, vcc
	v_cmp_eq_u32_e32 vcc, v0, v59
	s_cmp_eq_u64 vcc, exec
	s_cselect_b64 s[0:1], -1, 0
	v_subrev_co_u32_e32 v58, vcc, 1, v58
	s_or_b64 s[0:1], s[0:1], vcc
	s_andn2_b64 vcc, exec, s[0:1]
	s_cbranch_vccnz .LBB0_417
; __device__ __forceinline__ unsigned pk_flag_gt(unsigned k2, unsigned T2, unsigned one2) { unsigned t; asm volatile("v_pk_sub_u16 %0, %1, %2 clamp\n\tv_pk_min_u16 %0, %0, %3" : "=&v"(t) : "v"(k2), "v"(T2), "v"(one2)); return t; }
; template <int NCH>
; __device__ __forceinline__ void idx_select(const unsigned short* sc, unsigned* bits, size_t tok0, int tid) {
;     ...
;     const unsigned T = lo, T2 = T | (T << 16);
;     unsigned gm[NCH], em[NCH]; int cgt = 0;
; #pragma unroll
;     for (int i = 0; i < NCH; ++i) { unsigned g8 = 0u, e8 = 0u;
; #pragma unroll
;         for (int w = 0; w < 4; ++w) { const unsigned g2 = pk_flag_gt(kw[4 * i + w], T2, one2), l2 = pk_flag_gt(T2, kw[4 * i + w], one2), e2 = one2 - g2 - l2;
;             g8 |= ((g2 | (g2 >> 15)) & 3u) << (2 * w); e8 |= ((e2 | (e2 >> 15)) & 3u) << (2 * w); }
;         gm[i] = g8; em[i] = e8; cgt += __builtin_popcount(g8); }
	v_lshl_or_b32 v0, v0, 16, v0
	v_pk_sub_u16 v58, v6, v0 clamp
	v_pk_min_u16 v58, v58, v235
	v_pk_sub_u16 v59, v0, v6 clamp
	v_pk_min_u16 v59, v59, v235
	v_and_b32_e32 v135, 32, v182
	v_add_u32_e32 v59, v58, v59
	v_sub_u32_e32 v59, 0x10001, v59
	v_lshrrev_b32_e32 v60, 15, v58
	v_bitop3_b32 v58, v60, 3, v58 bitop3:0xc8
	v_lshrrev_b32_e32 v60, 15, v59
	v_bitop3_b32 v59, v60, 3, v59 bitop3:0xc8
	v_pk_sub_u16 v60, v7, v0 clamp
	v_pk_min_u16 v60, v60, v235
	v_pk_sub_u16 v61, v0, v7 clamp
	v_pk_min_u16 v61, v61, v235
	v_cmp_eq_u32_e64 s[6:7], 0, v135
	v_lshrrev_b32_e32 v62, 15, v60
	v_add_u32_e32 v61, v60, v61
	v_or_b32_e32 v60, v62, v60
	v_sub_u32_e32 v61, 0x10001, v61
	v_lshlrev_b32_e32 v60, 2, v60
	v_and_or_b32 v58, v60, 12, v58
	v_lshrrev_b32_e32 v60, 15, v61
	v_or_b32_e32 v60, v60, v61
	v_lshlrev_b32_e32 v60, 2, v60
	v_and_or_b32 v59, v60, 12, v59
	v_pk_sub_u16 v60, v8, v0 clamp
	v_pk_min_u16 v60, v60, v235
	v_pk_sub_u16 v61, v0, v8 clamp
	v_pk_min_u16 v61, v61, v235
	v_cmp_ne_u32_e64 s[8:9], 0, v135
	v_add_u32_e32 v61, v60, v61
	v_sub_u32_e32 v61, 0x10001, v61
	v_lshrrev_b32_e32 v62, 15, v60
	v_or_b32_e32 v60, v62, v60
	v_lshrrev_b32_e32 v62, 15, v61
	v_or_b32_e32 v61, v62, v61
	v_pk_sub_u16 v62, v9, v0 clamp
	v_pk_min_u16 v62, v62, v235
	v_pk_sub_u16 v63, v0, v9 clamp
	v_pk_min_u16 v63, v63, v235
	v_lshlrev_b32_e32 v60, 4, v60
	v_lshrrev_b32_e32 v64, 15, v62
	v_add_u32_e32 v63, v62, v63
	v_or_b32_e32 v62, v64, v62
	v_lshlrev_b32_e32 v62, 6, v62
	v_and_b32_e32 v60, 48, v60
	v_sub_u32_e32 v63, 0x10001, v63
	v_and_b32_e32 v62, 0xc0, v62
	v_or3_b32 v126, v58, v60, v62
	v_lshrrev_b32_e32 v58, 15, v63
	v_or_b32_e32 v58, v58, v63
	v_lshlrev_b32_e32 v61, 4, v61
	v_lshlrev_b32_e32 v58, 6, v58
	v_and_b32_e32 v61, 48, v61
	v_and_b32_e32 v58, 0xc0, v58
	v_pk_sub_u16 v67, v2, v0 clamp
	v_pk_min_u16 v67, v67, v235
	v_pk_sub_u16 v127, v0, v2 clamp
	v_pk_min_u16 v127, v127, v235
	v_pk_sub_u16 v128, v3, v0 clamp
	v_pk_min_u16 v128, v128, v235
	v_pk_sub_u16 v129, v0, v3 clamp
	v_pk_min_u16 v129, v129, v235
	v_pk_sub_u16 v130, v4, v0 clamp
	v_pk_min_u16 v130, v130, v235
	v_pk_sub_u16 v131, v0, v4 clamp
	v_pk_min_u16 v131, v131, v235
	v_pk_sub_u16 v132, v5, v0 clamp
	v_pk_min_u16 v132, v132, v235
	v_pk_sub_u16 v133, v0, v5 clamp
	v_pk_min_u16 v133, v133, v235
	s_nop 0
	v_lshrrev_b32_e32 v60, 15, v128
	v_pk_sub_u16 v118, v54, v0 clamp
	v_pk_min_u16 v118, v118, v235
	v_pk_sub_u16 v119, v0, v54 clamp
	v_pk_min_u16 v119, v119, v235
	v_pk_sub_u16 v120, v55, v0 clamp
	v_pk_min_u16 v120, v120, v235
	v_pk_sub_u16 v121, v0, v55 clamp
	v_pk_min_u16 v121, v121, v235
	v_pk_sub_u16 v122, v56, v0 clamp
	v_pk_min_u16 v122, v122, v235
	v_pk_sub_u16 v123, v0, v56 clamp
	v_pk_min_u16 v123, v123, v235
	v_pk_sub_u16 v124, v57, v0 clamp
	v_pk_min_u16 v124, v124, v235
	v_pk_sub_u16 v125, v0, v57 clamp
	v_pk_min_u16 v125, v125, v235
	s_nop 0
	v_lshrrev_b32_e32 v55, 15, v120
	v_pk_sub_u16 v109, v50, v0 clamp
	v_pk_min_u16 v109, v109, v235
	v_pk_sub_u16 v110, v0, v50 clamp
	v_pk_min_u16 v110, v110, v235
	v_pk_sub_u16 v111, v51, v0 clamp
	v_pk_min_u16 v111, v111, v235
	v_pk_sub_u16 v112, v0, v51 clamp
	v_pk_min_u16 v112, v112, v235
	v_or3_b32 v134, v59, v61, v58
	v_lshrrev_b32_e32 v51, 15, v111
	v_lshrrev_b32_e32 v59, 15, v67
	v_or_b32_e32 v60, v60, v128
	v_lshrrev_b32_e32 v54, 15, v118
	v_or_b32_e32 v55, v55, v120
	v_lshrrev_b32_e32 v50, 15, v109
	v_or_b32_e32 v51, v51, v111
	v_bitop3_b32 v59, v59, 3, v67 bitop3:0xc8
	v_lshlrev_b32_e32 v60, 2, v60
	v_bitop3_b32 v54, v54, 3, v118 bitop3:0xc8
	v_lshlrev_b32_e32 v55, 2, v55
	v_bitop3_b32 v50, v50, 3, v109 bitop3:0xc8
	v_lshlrev_b32_e32 v51, 2, v51
	v_and_or_b32 v59, v60, 12, v59
	v_lshrrev_b32_e32 v60, 15, v130
	v_lshrrev_b32_e32 v61, 15, v132
	v_and_or_b32 v54, v55, 12, v54
	v_lshrrev_b32_e32 v55, 15, v122
	v_lshrrev_b32_e32 v56, 15, v124
	v_and_or_b32 v50, v51, 12, v50
	v_pk_sub_u16 v113, v52, v0 clamp
	v_pk_min_u16 v113, v113, v235
	v_pk_sub_u16 v114, v0, v52 clamp
	v_pk_min_u16 v114, v114, v235
	v_pk_sub_u16 v115, v53, v0 clamp
	v_pk_min_u16 v115, v115, v235
	v_or_b32_e32 v60, v60, v130
	v_lshrrev_b32_e32 v51, 15, v113
	v_lshrrev_b32_e32 v52, 15, v115
	v_or_b32_e32 v61, v61, v132
	v_or_b32_e32 v55, v55, v122
	v_or_b32_e32 v56, v56, v124
	v_or_b32_e32 v51, v51, v113
	v_or_b32_e32 v52, v52, v115
	v_lshlrev_b32_e32 v60, 4, v60
	v_lshlrev_b32_e32 v61, 6, v61
	v_lshlrev_b32_e32 v55, 4, v55
	v_lshlrev_b32_e32 v56, 6, v56
	v_lshlrev_b32_e32 v51, 4, v51
	v_lshlrev_b32_e32 v52, 6, v52
	v_and_b32_e32 v60, 48, v60
	v_and_b32_e32 v61, 0xc0, v61
	v_and_b32_e32 v55, 48, v55
	v_and_b32_e32 v56, 0xc0, v56
	v_and_b32_e32 v51, 48, v51
	v_pk_sub_u16 v116, v0, v53 clamp
	v_pk_min_u16 v116, v116, v235
	v_and_b32_e32 v52, 0xc0, v52
	v_pk_sub_u16 v100, v46, v0 clamp
	v_pk_min_u16 v100, v100, v235
	v_pk_sub_u16 v101, v0, v46 clamp
	v_pk_min_u16 v101, v101, v235
	v_pk_sub_u16 v102, v47, v0 clamp
	v_pk_min_u16 v102, v102, v235
	v_pk_sub_u16 v103, v0, v47 clamp
	v_pk_min_u16 v103, v103, v235
	v_pk_sub_u16 v104, v48, v0 clamp
	v_pk_min_u16 v104, v104, v235
	v_pk_sub_u16 v105, v0, v48 clamp
	v_pk_min_u16 v105, v105, v235
	v_pk_sub_u16 v106, v49, v0 clamp
	v_pk_min_u16 v106, v106, v235
	v_pk_sub_u16 v107, v0, v49 clamp
	v_pk_min_u16 v107, v107, v235
	s_nop 0
	v_lshrrev_b32_e32 v47, 15, v102
	v_pk_sub_u16 v91, v42, v0 clamp
	v_pk_min_u16 v91, v91, v235
	v_pk_sub_u16 v92, v0, v42 clamp
	v_pk_min_u16 v92, v92, v235
	v_pk_sub_u16 v93, v43, v0 clamp
	v_pk_min_u16 v93, v93, v235
	v_pk_sub_u16 v94, v0, v43 clamp
	v_pk_min_u16 v94, v94, v235
	v_bcnt_u32_b32 v58, v126, 0
	v_lshrrev_b32_e32 v43, 15, v93
	v_or3_b32 v117, v59, v60, v61
	v_or3_b32 v108, v54, v55, v56
	v_or3_b32 v99, v50, v51, v52
	v_lshrrev_b32_e32 v46, 15, v100
	v_or_b32_e32 v47, v47, v102
	v_lshrrev_b32_e32 v42, 15, v91
	v_or_b32_e32 v43, v43, v93
	v_pk_sub_u16 v95, v44, v0 clamp
	v_pk_min_u16 v95, v95, v235
	v_pk_sub_u16 v96, v0, v44 clamp
	v_pk_min_u16 v96, v96, v235
	v_pk_sub_u16 v97, v45, v0 clamp
	v_pk_min_u16 v97, v97, v235
	v_pk_sub_u16 v98, v0, v45 clamp
	v_pk_min_u16 v98, v98, v235
	v_pk_sub_u16 v82, v38, v0 clamp
	v_pk_min_u16 v82, v82, v235
	v_pk_sub_u16 v83, v0, v38 clamp
	v_pk_min_u16 v83, v83, v235
	v_pk_sub_u16 v84, v39, v0 clamp
	v_pk_min_u16 v84, v84, v235
	v_pk_sub_u16 v85, v0, v39 clamp
	v_pk_min_u16 v85, v85, v235
	v_pk_sub_u16 v86, v40, v0 clamp
	v_pk_min_u16 v86, v86, v235
	v_pk_sub_u16 v87, v0, v40 clamp
	v_pk_min_u16 v87, v87, v235
	v_pk_sub_u16 v88, v41, v0 clamp
	v_pk_min_u16 v88, v88, v235
	v_pk_sub_u16 v89, v0, v41 clamp
	v_pk_min_u16 v89, v89, v235
	s_nop 0
	v_lshrrev_b32_e32 v39, 15, v84
	s_waitcnt vmcnt(2)
; __device__ __forceinline__ unsigned pk_flag_gt(unsigned k2, unsigned T2, unsigned one2) { unsigned t; asm volatile("v_pk_sub_u16 %0, %1, %2 clamp\n\tv_pk_min_u16 %0, %0, %3" : "=&v"(t) : "v"(k2), "v"(T2), "v"(one2)); return t; }
; template <int NCH>
; __device__ __forceinline__ void idx_select(const unsigned short* sc, unsigned* bits, size_t tok0, int tid) {
;     ...
;     const unsigned T = lo, T2 = T | (T << 16);
;     unsigned gm[NCH], em[NCH]; int cgt = 0;
; #pragma unroll
;     for (int i = 0; i < NCH; ++i) { unsigned g8 = 0u, e8 = 0u;
; #pragma unroll
;         for (int w = 0; w < 4; ++w) { const unsigned g2 = pk_flag_gt(kw[4 * i + w], T2, one2), l2 = pk_flag_gt(T2, kw[4 * i + w], one2), e2 = one2 - g2 - l2;
;             g8 |= ((g2 | (g2 >> 15)) & 3u) << (2 * w); e8 |= ((e2 | (e2 >> 15)) & 3u) << (2 * w); }
;         gm[i] = g8; em[i] = e8; cgt += __builtin_popcount(g8); }
	v_pk_sub_u16 v73, v34, v0 clamp
	v_pk_min_u16 v73, v73, v235
	s_waitcnt vmcnt(1)
	v_pk_sub_u16 v74, v0, v34 clamp
	v_pk_min_u16 v74, v74, v235
	v_pk_sub_u16 v75, v35, v0 clamp
	v_pk_min_u16 v75, v75, v235
	v_pk_sub_u16 v76, v0, v35 clamp
	v_pk_min_u16 v76, v76, v235
	v_bcnt_u32_b32 v58, v117, v58
	v_lshrrev_b32_e32 v35, 15, v75
	v_bcnt_u32_b32 v54, v108, 0
	v_bcnt_u32_b32 v50, v99, 0
	v_bitop3_b32 v46, v46, 3, v100 bitop3:0xc8
	v_lshlrev_b32_e32 v47, 2, v47
	v_bitop3_b32 v42, v42, 3, v91 bitop3:0xc8
	v_lshlrev_b32_e32 v43, 2, v43
	v_lshrrev_b32_e32 v38, 15, v82
	v_or_b32_e32 v39, v39, v84
	v_lshrrev_b32_e32 v34, 15, v73
	v_or_b32_e32 v35, v35, v75
	v_add3_u32 v50, v58, v54, v50
	v_and_or_b32 v46, v47, 12, v46
	v_lshrrev_b32_e32 v47, 15, v104
	v_lshrrev_b32_e32 v48, 15, v106
	v_and_or_b32 v42, v43, 12, v42
	v_lshrrev_b32_e32 v43, 15, v95
	v_lshrrev_b32_e32 v44, 15, v97
	v_bitop3_b32 v38, v38, 3, v82 bitop3:0xc8
	v_lshlrev_b32_e32 v39, 2, v39
	v_bitop3_b32 v34, v34, 3, v73 bitop3:0xc8
	v_lshlrev_b32_e32 v35, 2, v35
	v_pk_sub_u16 v77, v36, v0 clamp
	v_pk_min_u16 v77, v77, v235
	s_waitcnt vmcnt(0)
	v_pk_sub_u16 v78, v0, v36 clamp
	v_pk_min_u16 v78, v78, v235
	v_pk_sub_u16 v79, v37, v0 clamp
	v_pk_min_u16 v79, v79, v235
	v_pk_sub_u16 v80, v0, v37 clamp
	v_pk_min_u16 v80, v80, v235
	v_pk_sub_u16 v61, v30, v0 clamp
	v_pk_min_u16 v61, v61, v235
	v_pk_sub_u16 v62, v0, v30 clamp
	v_pk_min_u16 v62, v62, v235
	v_pk_sub_u16 v63, v31, v0 clamp
	v_pk_min_u16 v63, v63, v235
	v_pk_sub_u16 v64, v0, v31 clamp
	v_pk_min_u16 v64, v64, v235
	v_pk_sub_u16 v65, v32, v0 clamp
	v_pk_min_u16 v65, v65, v235
	v_pk_sub_u16 v69, v0, v32 clamp
	v_pk_min_u16 v69, v69, v235
	v_pk_sub_u16 v70, v33, v0 clamp
	v_pk_min_u16 v70, v70, v235
	v_pk_sub_u16 v71, v0, v33 clamp
	v_pk_min_u16 v71, v71, v235
	s_nop 0
	v_lshrrev_b32_e32 v31, 15, v63
	v_pk_sub_u16 v52, v26, v0 clamp
	v_pk_min_u16 v52, v52, v235
	v_pk_sub_u16 v53, v0, v26 clamp
	v_pk_min_u16 v53, v53, v235
	v_pk_sub_u16 v54, v27, v0 clamp
	v_pk_min_u16 v54, v54, v235
	v_pk_sub_u16 v55, v0, v27 clamp
	v_pk_min_u16 v55, v55, v235
	v_or_b32_e32 v47, v47, v104
	v_lshrrev_b32_e32 v27, 15, v54
	v_or_b32_e32 v48, v48, v106
	v_or_b32_e32 v43, v43, v95
	v_or_b32_e32 v44, v44, v97
	v_and_or_b32 v38, v39, 12, v38
	v_lshrrev_b32_e32 v39, 15, v86
	v_lshrrev_b32_e32 v40, 15, v88
	v_and_or_b32 v34, v35, 12, v34
	v_lshrrev_b32_e32 v35, 15, v77
	v_lshrrev_b32_e32 v36, 15, v79
	v_lshrrev_b32_e32 v30, 15, v61
	v_or_b32_e32 v31, v31, v63
	v_lshrrev_b32_e32 v26, 15, v52
	v_or_b32_e32 v27, v27, v54
	v_lshlrev_b32_e32 v47, 4, v47
	v_lshlrev_b32_e32 v48, 6, v48
	v_lshlrev_b32_e32 v43, 4, v43
	v_lshlrev_b32_e32 v44, 6, v44
	v_or_b32_e32 v39, v39, v86
	v_or_b32_e32 v40, v40, v88
	v_or_b32_e32 v35, v35, v77
	v_or_b32_e32 v36, v36, v79
	v_bitop3_b32 v30, v30, 3, v61 bitop3:0xc8
	v_lshlrev_b32_e32 v31, 2, v31
	v_bitop3_b32 v26, v26, 3, v52 bitop3:0xc8
	v_lshlrev_b32_e32 v27, 2, v27
	v_and_b32_e32 v47, 48, v47
	v_and_b32_e32 v48, 0xc0, v48
	v_and_b32_e32 v43, 48, v43
	v_and_b32_e32 v44, 0xc0, v44
	v_lshlrev_b32_e32 v39, 4, v39
	v_lshlrev_b32_e32 v40, 6, v40
	v_lshlrev_b32_e32 v35, 4, v35
	v_lshlrev_b32_e32 v36, 6, v36
	v_and_or_b32 v30, v31, 12, v30
	v_lshrrev_b32_e32 v31, 15, v65
	v_lshrrev_b32_e32 v32, 15, v70
	v_and_or_b32 v26, v27, 12, v26
	v_pk_sub_u16 v56, v28, v0 clamp
	v_pk_min_u16 v56, v56, v235
	v_pk_sub_u16 v57, v0, v28 clamp
	v_pk_min_u16 v57, v57, v235
	v_pk_sub_u16 v58, v29, v0 clamp
	v_pk_min_u16 v58, v58, v235
	v_or3_b32 v90, v46, v47, v48
	v_lshrrev_b32_e32 v27, 15, v56
	v_lshrrev_b32_e32 v28, 15, v58
	v_or3_b32 v81, v42, v43, v44
	v_and_b32_e32 v39, 48, v39
	v_and_b32_e32 v40, 0xc0, v40
	v_and_b32_e32 v35, 48, v35
	v_and_b32_e32 v36, 0xc0, v36
	v_or_b32_e32 v31, v31, v65
	v_or_b32_e32 v32, v32, v70
	v_or_b32_e32 v27, v27, v56
	v_or_b32_e32 v28, v28, v58
	v_bcnt_u32_b32 v46, v90, 0
	v_bcnt_u32_b32 v42, v81, 0
	v_or3_b32 v72, v38, v39, v40
	v_or3_b32 v60, v34, v35, v36
	v_lshlrev_b32_e32 v31, 4, v31
	v_lshlrev_b32_e32 v32, 6, v32
	v_lshlrev_b32_e32 v27, 4, v27
	v_lshlrev_b32_e32 v28, 6, v28
	v_add3_u32 v42, v50, v46, v42
	v_bcnt_u32_b32 v38, v72, 0
	v_bcnt_u32_b32 v34, v60, 0
	v_and_b32_e32 v31, 48, v31
	v_and_b32_e32 v32, 0xc0, v32
	v_and_b32_e32 v27, 48, v27
	v_and_b32_e32 v28, 0xc0, v28
	v_add3_u32 v34, v42, v38, v34
	v_or3_b32 v51, v30, v31, v32
	v_or3_b32 v42, v26, v27, v28
	v_bcnt_u32_b32 v30, v51, 0
	v_bcnt_u32_b32 v26, v42, 0
	v_pk_sub_u16 v59, v0, v29 clamp
	v_pk_min_u16 v59, v59, v235
	v_add3_u32 v26, v34, v30, v26
	v_pk_sub_u16 v43, v22, v0 clamp
	v_pk_min_u16 v43, v43, v235
	v_pk_sub_u16 v44, v0, v22 clamp
	v_pk_min_u16 v44, v44, v235
	v_pk_sub_u16 v45, v23, v0 clamp
	v_pk_min_u16 v45, v45, v235
	v_pk_sub_u16 v46, v0, v23 clamp
	v_pk_min_u16 v46, v46, v235
	v_pk_sub_u16 v47, v24, v0 clamp
	v_pk_min_u16 v47, v47, v235
	v_pk_sub_u16 v48, v0, v24 clamp
	v_pk_min_u16 v48, v48, v235
	v_pk_sub_u16 v49, v25, v0 clamp
	v_pk_min_u16 v49, v49, v235
	v_pk_sub_u16 v50, v0, v25 clamp
	v_pk_min_u16 v50, v50, v235
	s_nop 0
	v_lshrrev_b32_e32 v23, 15, v45
	v_pk_sub_u16 v33, v18, v0 clamp
	v_pk_min_u16 v33, v33, v235
	v_pk_sub_u16 v34, v0, v18 clamp
	v_pk_min_u16 v34, v34, v235
	v_pk_sub_u16 v35, v19, v0 clamp
	v_pk_min_u16 v35, v35, v235
	v_pk_sub_u16 v36, v0, v19 clamp
	v_pk_min_u16 v36, v36, v235
	v_lshrrev_b32_e32 v22, 15, v43
	v_lshrrev_b32_e32 v19, 15, v35
	v_or_b32_e32 v23, v23, v45
	v_lshrrev_b32_e32 v18, 15, v33
	v_or_b32_e32 v19, v19, v35
	v_bitop3_b32 v22, v22, 3, v43 bitop3:0xc8
	v_lshlrev_b32_e32 v23, 2, v23
	v_bitop3_b32 v18, v18, 3, v33 bitop3:0xc8
	v_lshlrev_b32_e32 v19, 2, v19
	v_and_or_b32 v22, v23, 12, v22
; __device__ __forceinline__ int red32(int v) {
;     v += __builtin_amdgcn_mov_dpp(v, 0xB1, 0xf, 0xf, true);
;     v += __builtin_amdgcn_mov_dpp(v, 0x4E, 0xf, 0xf, true);
;     v += __builtin_amdgcn_mov_dpp(v, 0x141, 0xf, 0xf, true);
;     v += __builtin_amdgcn_mov_dpp(v, 0x140, 0xf, 0xf, true);
;     v += __builtin_amdgcn_ds_swizzle(v, 0x401F);
;     return v;
; }
; __device__ __forceinline__ unsigned ltu(unsigned a, unsigned b) { unsigned d; asm volatile("v_sub_u32 %0, %1, %2\n\tv_lshrrev_b32 %0, 31, %0" : "=v"(d) : "v"(a), "v"(b)); return d; }
; __device__ __forceinline__ unsigned pk_flag_gt(unsigned k2, unsigned T2, unsigned one2) { unsigned t; asm volatile("v_pk_sub_u16 %0, %1, %2 clamp\n\tv_pk_min_u16 %0, %0, %3" : "=&v"(t) : "v"(k2), "v"(T2), "v"(one2)); return t; }
; __device__ __forceinline__ int scan32_incl(int x, int lane) {
;     x += __builtin_amdgcn_update_dpp(0, x, 0x111, 0xf, 0xf, true);
;     x += __builtin_amdgcn_update_dpp(0, x, 0x112, 0xf, 0xf, true);
; template <int NCH>
; __device__ __forceinline__ void idx_select(const unsigned short* sc, unsigned* bits, size_t tok0, int tid) {
;     ...
;     const unsigned T = lo, T2 = T | (T << 16);
;     unsigned gm[NCH], em[NCH]; int cgt = 0;
; #pragma unroll
;     for (int i = 0; i < NCH; ++i) { unsigned g8 = 0u, e8 = 0u;
; #pragma unroll
;         for (int w = 0; w < 4; ++w) { const unsigned g2 = pk_flag_gt(kw[4 * i + w], T2, one2), l2 = pk_flag_gt(T2, kw[4 * i + w], one2), e2 = one2 - g2 - l2;
;             g8 |= ((g2 | (g2 >> 15)) & 3u) << (2 * w); e8 |= ((e2 | (e2 >> 15)) & 3u) << (2 * w); }
;         gm[i] = g8; em[i] = e8; cgt += __builtin_popcount(g8); }
;     const int need = 256 - red32(cgt);
;     int carry = 0;
;     unsigned char* brow = (unsigned char*)(bits + (tok0 + row) * 128);
; #pragma unroll
;     for (int i = 0; i < NCH; ++i) { const int ec = __builtin_popcount(em[i]); const int incl = scan32_incl(ec, lane);
;         const int quota = need - carry - (incl - ec);
;         unsigned se = (quota >= ec) ? em[i] : 0u;
;         if (__any(quota > 0 && quota < ec)) { unsigned m = em[i], r = 0u;
; #pragma unroll
;             for (int t = 0; t < 8; ++t) { const unsigned b = m & (0u - m); if (t < quota) r |= b; m ^= b; }
;             if (quota > 0 && quota < ec) se = r; }
;         carry += (lane & 32) ? __builtin_amdgcn_readlane(incl, 63) : __builtin_amdgcn_readlane(incl, 31);
	v_lshrrev_b32_e32 v23, 15, v47
	v_lshrrev_b32_e32 v24, 15, v49
	v_and_or_b32 v18, v19, 12, v18
	v_pk_sub_u16 v37, v20, v0 clamp
	v_pk_min_u16 v37, v37, v235
	v_pk_sub_u16 v38, v0, v20 clamp
	v_pk_min_u16 v38, v38, v235
	v_pk_sub_u16 v39, v21, v0 clamp
	v_pk_min_u16 v39, v39, v235
	v_or_b32_e32 v23, v23, v47
	v_lshrrev_b32_e32 v19, 15, v37
	v_lshrrev_b32_e32 v20, 15, v39
	v_or_b32_e32 v24, v24, v49
	v_or_b32_e32 v19, v19, v37
	v_or_b32_e32 v20, v20, v39
	v_lshlrev_b32_e32 v23, 4, v23
	v_lshlrev_b32_e32 v24, 6, v24
	v_lshlrev_b32_e32 v19, 4, v19
	v_lshlrev_b32_e32 v20, 6, v20
	v_and_b32_e32 v23, 48, v23
	v_and_b32_e32 v24, 0xc0, v24
	v_and_b32_e32 v19, 48, v19
	v_and_b32_e32 v20, 0xc0, v20
	v_or3_b32 v32, v22, v23, v24
	v_or3_b32 v23, v18, v19, v20
	v_bcnt_u32_b32 v22, v32, 0
	v_bcnt_u32_b32 v18, v23, 0
	v_pk_sub_u16 v40, v0, v21 clamp
	v_pk_min_u16 v40, v40, v235
	v_add3_u32 v41, v26, v22, v18
	v_pk_sub_u16 v24, v14, v0 clamp
	v_pk_min_u16 v24, v24, v235
	v_pk_sub_u16 v25, v0, v14 clamp
	v_pk_min_u16 v25, v25, v235
	v_pk_sub_u16 v26, v15, v0 clamp
	v_pk_min_u16 v26, v26, v235
	v_pk_sub_u16 v27, v0, v15 clamp
	v_pk_min_u16 v27, v27, v235
	v_pk_sub_u16 v28, v16, v0 clamp
	v_pk_min_u16 v28, v28, v235
	v_pk_sub_u16 v29, v0, v16 clamp
	v_pk_min_u16 v29, v29, v235
	s_nop 0
	v_lshrrev_b32_e32 v14, 15, v24
	v_lshrrev_b32_e32 v15, 15, v26
	v_or_b32_e32 v15, v15, v26
	v_bitop3_b32 v14, v14, 3, v24 bitop3:0xc8
	v_lshlrev_b32_e32 v15, 2, v15
	v_and_or_b32 v14, v15, 12, v14
	v_lshrrev_b32_e32 v15, 15, v28
	v_pk_sub_u16 v30, v17, v0 clamp
	v_pk_min_u16 v30, v30, v235
	v_or_b32_e32 v15, v15, v28
	v_lshrrev_b32_e32 v16, 15, v30
	v_or_b32_e32 v16, v16, v30
	v_lshlrev_b32_e32 v15, 4, v15
	v_lshlrev_b32_e32 v16, 6, v16
	v_and_b32_e32 v15, 48, v15
	v_and_b32_e32 v16, 0xc0, v16
	v_pk_sub_u16 v31, v0, v17 clamp
	v_pk_min_u16 v31, v31, v235
	v_or3_b32 v14, v14, v15, v16
	v_pk_sub_u16 v15, v10, v0 clamp
	v_pk_min_u16 v15, v15, v235
	v_pk_sub_u16 v16, v0, v10 clamp
	v_pk_min_u16 v16, v16, v235
	v_pk_sub_u16 v17, v11, v0 clamp
	v_pk_min_u16 v17, v17, v235
	v_pk_sub_u16 v18, v0, v11 clamp
	v_pk_min_u16 v18, v18, v235
	v_pk_sub_u16 v19, v12, v0 clamp
	v_pk_min_u16 v19, v19, v235
	v_pk_sub_u16 v20, v0, v12 clamp
	v_pk_min_u16 v20, v20, v235
	s_nop 0
	v_lshrrev_b32_e32 v10, 15, v15
	v_lshrrev_b32_e32 v11, 15, v17
	v_or_b32_e32 v11, v11, v17
	v_bitop3_b32 v10, v10, 3, v15 bitop3:0xc8
	v_lshlrev_b32_e32 v11, 2, v11
	v_and_or_b32 v10, v11, 12, v10
	v_lshrrev_b32_e32 v11, 15, v19
	v_pk_sub_u16 v21, v13, v0 clamp
	v_pk_min_u16 v21, v21, v235
	v_pk_sub_u16 v22, v0, v13 clamp
	v_pk_min_u16 v22, v22, v235
	v_or_b32_e32 v11, v11, v19
	v_lshrrev_b32_e32 v0, 15, v21
	v_or_b32_e32 v0, v0, v21
	v_lshlrev_b32_e32 v11, 4, v11
	v_lshlrev_b32_e32 v0, 6, v0
	v_and_b32_e32 v11, 48, v11
	v_and_b32_e32 v0, 0xc0, v0
	v_or3_b32 v0, v10, v11, v0
	v_bcnt_u32_b32 v136, v14, 0
	v_bcnt_u32_b32 v10, v0, 0
	v_add3_u32 v10, v41, v136, v10
	v_and_b32_e32 v12, 16, v182
	v_cmp_eq_u32_e64 s[4:5], 0, v12
	v_add_u32_dpp v10, v10, v10 quad_perm:[1,0,3,2] row_mask:0xf bank_mask:0xf bound_ctrl:1
	v_bcnt_u32_b32 v12, v134, 0
	v_bfe_i32 v13, v182, 4, 1
	v_add_u32_dpp v10, v10, v10 quad_perm:[2,3,0,1] row_mask:0xf bank_mask:0xf bound_ctrl:1
	s_nop 1
	v_add_u32_dpp v10, v10, v10 row_half_mirror row_mask:0xf bank_mask:0xf bound_ctrl:1
	s_nop 1
	v_add_u32_dpp v10, v10, v10 row_mirror row_mask:0xf bank_mask:0xf bound_ctrl:1
	v_mov_b32_e32 v11, v10
	s_nop 1
	v_permlane16_swap_b32_e32 v11, v10
	s_waitcnt lgkmcnt(0)
	v_add_u32_e32 v41, v10, v11
	v_mov_b32_dpp v10, v12 row_shr:1 row_mask:0xf bank_mask:0xf bound_ctrl:1
	v_bcnt_u32_b32 v10, v134, v10
	s_nop 1
	v_add_u32_dpp v10, v10, v10 row_shr:2 row_mask:0xf bank_mask:0xf bound_ctrl:1
	s_nop 1
	v_add_u32_dpp v10, v10, v10 row_shr:4 row_mask:0xf bank_mask:0xf bound_ctrl:1
	s_nop 1
	v_add_u32_dpp v10, v10, v10 row_shr:8 row_mask:0xf bank_mask:0xf bound_ctrl:1
	s_nop 0
	v_readlane_b32 s0, v10, 15
	v_readlane_b32 s1, v10, 47
	s_nop 0
	v_mov_b32_e32 v136, s0
	v_mov_b32_e32 v11, s1
	v_cndmask_b32_e64 v11, v11, v136, s[6:7]
	v_and_b32_e32 v11, v13, v11
	v_add_u32_e32 v10, v11, v10
	v_or_b32_e32 v11, 0x100, v12
	v_add_u32_e32 v13, v41, v10
	v_sub_u32_e32 v11, v11, v13
	v_cmp_lt_i32_e64 s[0:1], v11, v12
	v_cmp_lt_i32_e64 s[10:11], 0, v11
	s_and_b64 vcc, s[10:11], s[0:1]
	v_cndmask_b32_e64 v12, v134, 0, s[0:1]
	s_cbranch_vccz .LBB0_420
	v_sub_u32_e32 v13, 0, v134
	v_and_b32_e32 v135, v134, v13
	v_bitop3_b32 v13, v134, v134, v13 bitop3:0x6c
	v_sub_u32_e32 v137, 0, v13
	v_cndmask_b32_e64 v136, 0, v135, s[10:11]
	v_bitop3_b32 v138, v135, v137, v134 bitop3:0x48
	v_cmp_lt_i32_e32 vcc, 1, v11
	v_bitop3_b32 v135, v135, v134, v137 bitop3:0x14
	v_sub_u32_e32 v137, 0, v135
	v_cndmask_b32_e32 v139, 0, v138, vcc
	v_or_b32_e32 v136, v139, v136
	v_bitop3_b32 v139, v138, v137, v13 bitop3:0x48
	v_bitop3_b32 v13, v138, v13, v137 bitop3:0x14
	v_sub_u32_e32 v137, 0, v13
	v_bitop3_b32 v138, v139, v137, v135 bitop3:0x48
	v_bitop3_b32 v135, v139, v135, v137 bitop3:0x14
	v_cmp_lt_i32_e32 vcc, 2, v11
	v_sub_u32_e32 v137, 0, v135
	s_nop 0
	v_cndmask_b32_e32 v140, 0, v139, vcc
	v_bitop3_b32 v139, v138, v137, v13 bitop3:0x48
	v_bitop3_b32 v13, v138, v13, v137 bitop3:0x14
	v_cmp_lt_i32_e32 vcc, 3, v11
	v_sub_u32_e32 v137, 0, v13
	s_nop 0
	v_cndmask_b32_e32 v141, 0, v138, vcc
	v_bitop3_b32 v138, v139, v137, v135 bitop3:0x48
	v_bitop3_b32 v135, v139, v135, v137 bitop3:0x14
	v_cmp_lt_i32_e32 vcc, 4, v11
	v_sub_u32_e32 v137, 0, v135
	v_or3_b32 v136, v136, v140, v141
	v_cndmask_b32_e32 v140, 0, v139, vcc
	v_cmp_lt_i32_e32 vcc, 5, v11
	v_bitop3_b32 v139, v138, v137, v13 bitop3:0x48
	v_bitop3_b32 v13, v138, v13, v137 bitop3:0x14
	v_cndmask_b32_e32 v141, 0, v138, vcc
	v_cmp_lt_i32_e32 vcc, 6, v11
	v_sub_u32_e32 v13, 0, v13
	v_or3_b32 v136, v136, v140, v141
	v_cndmask_b32_e32 v140, 0, v139, vcc
	v_bitop3_b32 v13, v139, v13, v135 bitop3:0x48
	v_cmp_lt_i32_e32 vcc, 7, v11
	s_nop 1
	v_cndmask_b32_e32 v11, 0, v13, vcc
	v_or3_b32 v11, v136, v140, v11
	v_cndmask_b32_e64 v11, v134, v11, s[0:1]
	v_cndmask_b32_e64 v12, v12, v11, s[10:11]

; __device__ __forceinline__ int red32(int v) {
;     v += __builtin_amdgcn_mov_dpp(v, 0xB1, 0xf, 0xf, true);
;     v += __builtin_amdgcn_mov_dpp(v, 0x4E, 0xf, 0xf, true);
;     v += __builtin_amdgcn_mov_dpp(v, 0x141, 0xf, 0xf, true);
;     v += __builtin_amdgcn_mov_dpp(v, 0x140, 0xf, 0xf, true);
;     v += __builtin_amdgcn_ds_swizzle(v, 0x401F);
;     return v;
; }
; template <int NCH>
; __device__ __forceinline__ void idx_select(const unsigned short* sc, unsigned* bits, size_t tok0, int tid) {
;     ...
; #pragma unroll 1
;     for (int it = 0; it < 16; ++it) { const unsigned mid = (lo + hi_ + 1u) >> 1, mid2 = mid | (mid << 16);
;         unsigned c2a = 0u, c2b = 0u;
; #pragma unroll
;         for (int i = 0; i < 4 * NCH; i += 2) { pk_cnt_lt(c2a, kw[i], mid2, one2); pk_cnt_lt(c2b, kw[i + 1], mid2, one2); }
;         int cnt = 8 * NCH - (int)((c2a & 0xFFFFu) + (c2a >> 16) + (c2b & 0xFFFFu) + (c2b >> 16));
;         cnt = red32(cnt);
;         if (cnt >= 256) lo = mid; else hi_ = mid - 1u;
;         if (cnt == 256) hi_ = mid;
;         if (__all(lo == hi_)) break; }
.LBB0_504:
	v_add3_u32 v52, v0, v51, 1
	v_lshrrev_b32_e32 v52, 1, v52
	v_mov_b32_e32 v54, 0
	v_lshl_or_b32 v53, v52, 16, v52
	s_waitcnt lgkmcnt(11)
	v_pk_sub_u16 v55, v53, v6 clamp
	v_pk_min_u16 v55, v55, v235
	v_pk_add_u16 v54, v54, v55
	s_nop 0
	v_mov_b32_e32 v55, 0
	v_pk_sub_u16 v56, v53, v7 clamp
	v_pk_min_u16 v56, v56, v235
	v_pk_add_u16 v55, v55, v56
	v_pk_sub_u16 v56, v53, v8 clamp
	v_pk_min_u16 v56, v56, v235
	v_pk_add_u16 v54, v54, v56
	v_pk_sub_u16 v56, v53, v9 clamp
	v_pk_min_u16 v56, v56, v235
	v_pk_add_u16 v55, v55, v56
	s_waitcnt lgkmcnt(10)
	v_pk_sub_u16 v56, v53, v2 clamp
	v_pk_min_u16 v56, v56, v235
	v_pk_add_u16 v54, v54, v56
	v_pk_sub_u16 v56, v53, v3 clamp
	v_pk_min_u16 v56, v56, v235
	v_pk_add_u16 v55, v55, v56
	v_pk_sub_u16 v56, v53, v4 clamp
	v_pk_min_u16 v56, v56, v235
	v_pk_add_u16 v54, v54, v56
	v_pk_sub_u16 v56, v53, v5 clamp
	v_pk_min_u16 v56, v56, v235
	v_pk_add_u16 v55, v55, v56
	s_waitcnt lgkmcnt(9)
	v_pk_sub_u16 v56, v53, v46 clamp
	v_pk_min_u16 v56, v56, v235
	v_pk_add_u16 v54, v54, v56
	v_pk_sub_u16 v56, v53, v47 clamp
	v_pk_min_u16 v56, v56, v235
	v_pk_add_u16 v55, v55, v56
	v_pk_sub_u16 v56, v53, v48 clamp
	v_pk_min_u16 v56, v56, v235
	v_pk_add_u16 v54, v54, v56
	v_pk_sub_u16 v56, v53, v49 clamp
	v_pk_min_u16 v56, v56, v235
	v_pk_add_u16 v55, v55, v56
	s_waitcnt lgkmcnt(8)
	v_pk_sub_u16 v56, v53, v42 clamp
	v_pk_min_u16 v56, v56, v235
	v_pk_add_u16 v54, v54, v56
	v_pk_sub_u16 v56, v53, v43 clamp
	v_pk_min_u16 v56, v56, v235
	v_pk_add_u16 v55, v55, v56
	v_pk_sub_u16 v56, v53, v44 clamp
	v_pk_min_u16 v56, v56, v235
	v_pk_add_u16 v54, v54, v56
	v_pk_sub_u16 v56, v53, v45 clamp
	v_pk_min_u16 v56, v56, v235
	v_pk_add_u16 v55, v55, v56
	s_waitcnt lgkmcnt(7)
	v_pk_sub_u16 v56, v53, v38 clamp
	v_pk_min_u16 v56, v56, v235
	v_pk_add_u16 v54, v54, v56
	v_pk_sub_u16 v56, v53, v39 clamp
	v_pk_min_u16 v56, v56, v235
	v_pk_add_u16 v55, v55, v56
	v_pk_sub_u16 v56, v53, v40 clamp
	v_pk_min_u16 v56, v56, v235
	v_pk_add_u16 v54, v54, v56
	v_pk_sub_u16 v56, v53, v41 clamp
	v_pk_min_u16 v56, v56, v235
	v_pk_add_u16 v55, v55, v56
	s_waitcnt lgkmcnt(6)
	v_pk_sub_u16 v56, v53, v34 clamp
	v_pk_min_u16 v56, v56, v235
	v_pk_add_u16 v54, v54, v56
	v_pk_sub_u16 v56, v53, v35 clamp
	v_pk_min_u16 v56, v56, v235
	v_pk_add_u16 v55, v55, v56
	v_pk_sub_u16 v56, v53, v36 clamp
	v_pk_min_u16 v56, v56, v235
	v_pk_add_u16 v54, v54, v56
	v_pk_sub_u16 v56, v53, v37 clamp
	v_pk_min_u16 v56, v56, v235
	v_pk_add_u16 v55, v55, v56
	s_waitcnt lgkmcnt(5)
	v_pk_sub_u16 v56, v53, v30 clamp
	v_pk_min_u16 v56, v56, v235
	v_pk_add_u16 v54, v54, v56
	v_pk_sub_u16 v56, v53, v31 clamp
	v_pk_min_u16 v56, v56, v235
	v_pk_add_u16 v55, v55, v56
	v_pk_sub_u16 v56, v53, v32 clamp
	v_pk_min_u16 v56, v56, v235
	v_pk_add_u16 v54, v54, v56
	v_pk_sub_u16 v56, v53, v33 clamp
	v_pk_min_u16 v56, v56, v235
	v_pk_add_u16 v55, v55, v56
	s_waitcnt lgkmcnt(4)
	v_pk_sub_u16 v56, v53, v26 clamp
	v_pk_min_u16 v56, v56, v235
	v_pk_add_u16 v54, v54, v56
	v_pk_sub_u16 v56, v53, v27 clamp
	v_pk_min_u16 v56, v56, v235
	v_pk_add_u16 v55, v55, v56
	v_pk_sub_u16 v56, v53, v28 clamp
	v_pk_min_u16 v56, v56, v235
	v_pk_add_u16 v54, v54, v56
	v_pk_sub_u16 v56, v53, v29 clamp
	v_pk_min_u16 v56, v56, v235
	v_pk_add_u16 v55, v55, v56
	s_waitcnt lgkmcnt(3)
	v_pk_sub_u16 v56, v53, v22 clamp
	v_pk_min_u16 v56, v56, v235
	v_pk_add_u16 v54, v54, v56
	v_pk_sub_u16 v56, v53, v23 clamp
	v_pk_min_u16 v56, v56, v235
	v_pk_add_u16 v55, v55, v56
	v_pk_sub_u16 v56, v53, v24 clamp
	v_pk_min_u16 v56, v56, v235
	v_pk_add_u16 v54, v54, v56
	v_pk_sub_u16 v56, v53, v25 clamp
	v_pk_min_u16 v56, v56, v235
	v_pk_add_u16 v55, v55, v56
	s_waitcnt lgkmcnt(2)
	v_pk_sub_u16 v56, v53, v18 clamp
	v_pk_min_u16 v56, v56, v235
	v_pk_add_u16 v54, v54, v56
	v_pk_sub_u16 v56, v53, v19 clamp
	v_pk_min_u16 v56, v56, v235
	v_pk_add_u16 v55, v55, v56
	v_pk_sub_u16 v56, v53, v20 clamp
	v_pk_min_u16 v56, v56, v235
	v_pk_add_u16 v54, v54, v56
	v_pk_sub_u16 v56, v53, v21 clamp
	v_pk_min_u16 v56, v56, v235
	v_pk_add_u16 v55, v55, v56
	s_waitcnt lgkmcnt(1)
	v_pk_sub_u16 v56, v53, v14 clamp
	v_pk_min_u16 v56, v56, v235
	v_pk_add_u16 v54, v54, v56
	v_pk_sub_u16 v56, v53, v15 clamp
	v_pk_min_u16 v56, v56, v235
	v_pk_add_u16 v55, v55, v56
	v_pk_sub_u16 v56, v53, v16 clamp
	v_pk_min_u16 v56, v56, v235
	v_pk_add_u16 v54, v54, v56
	v_pk_sub_u16 v56, v53, v17 clamp
	v_pk_min_u16 v56, v56, v235
	v_pk_add_u16 v55, v55, v56
	s_waitcnt lgkmcnt(0)
	v_pk_sub_u16 v56, v53, v10 clamp
	v_pk_min_u16 v56, v56, v235
	v_pk_add_u16 v54, v54, v56
	v_pk_sub_u16 v56, v53, v11 clamp
	v_pk_min_u16 v56, v56, v235
	v_pk_add_u16 v55, v55, v56
	v_pk_sub_u16 v56, v53, v12 clamp
	v_pk_min_u16 v56, v56, v235
	v_pk_add_u16 v54, v54, v56
	v_pk_sub_u16 v56, v53, v13 clamp
	v_pk_min_u16 v56, v56, v235
	v_pk_add_u16 v55, v55, v56
	v_add_u32_sdwa v54, v54, v54 dst_sel:DWORD dst_unused:UNUSED_PAD src0_sel:WORD_1 src1_sel:WORD_0
	v_and_b32_e32 v53, 0xffff, v55
	v_lshrrev_b32_e32 v55, 16, v55
	v_add3_u32 v53, v54, v53, v55
	v_sub_u32_e32 v53, 0x60, v53
	s_nop 1
	v_add_u32_dpp v53, v53, v53 quad_perm:[1,0,3,2] row_mask:0xf bank_mask:0xf bound_ctrl:1
	s_nop 1
	v_add_u32_dpp v53, v53, v53 quad_perm:[2,3,0,1] row_mask:0xf bank_mask:0xf bound_ctrl:1
	s_nop 1
	v_add_u32_dpp v53, v53, v53 row_half_mirror row_mask:0xf bank_mask:0xf bound_ctrl:1
	s_nop 1
	v_add_u32_dpp v53, v53, v53 row_mirror row_mask:0xf bank_mask:0xf bound_ctrl:1
	v_mov_b32_e32 v54, v53
	s_nop 1
	v_permlane16_swap_b32_e32 v54, v53
	s_waitcnt lgkmcnt(0)
	v_add_u32_e32 v53, v53, v54
	v_cmp_lt_i32_e32 vcc, s88, v53
	v_add_u32_e32 v54, -1, v52
	s_nop 0
	v_cndmask_b32_e32 v51, v54, v51, vcc
	v_cndmask_b32_e32 v0, v0, v52, vcc
	v_cmp_eq_u32_e32 vcc, s33, v53
	s_nop 1
	v_cndmask_b32_e32 v51, v51, v52, vcc
	v_cmp_eq_u32_e32 vcc, v0, v51
	s_cmp_eq_u64 vcc, exec
	s_cselect_b64 s[0:1], -1, 0
	v_subrev_co_u32_e32 v50, vcc, 1, v50
	s_or_b64 s[0:1], s[0:1], vcc
	s_andn2_b64 vcc, exec, s[0:1]
	s_cbranch_vccnz .LBB0_504
; __device__ __forceinline__ unsigned pk_flag_gt(unsigned k2, unsigned T2, unsigned one2) { unsigned t; asm volatile("v_pk_sub_u16 %0, %1, %2 clamp\n\tv_pk_min_u16 %0, %0, %3" : "=&v"(t) : "v"(k2), "v"(T2), "v"(one2)); return t; }
; template <int NCH>
; __device__ __forceinline__ void idx_select(const unsigned short* sc, unsigned* bits, size_t tok0, int tid) {
;     ...
;     const unsigned T = lo, T2 = T | (T << 16);
;     unsigned gm[NCH], em[NCH]; int cgt = 0;
; #pragma unroll
;     for (int i = 0; i < NCH; ++i) { unsigned g8 = 0u, e8 = 0u;
; #pragma unroll
;         for (int w = 0; w < 4; ++w) { const unsigned g2 = pk_flag_gt(kw[4 * i + w], T2, one2), l2 = pk_flag_gt(T2, kw[4 * i + w], one2), e2 = one2 - g2 - l2;
;             g8 |= ((g2 | (g2 >> 15)) & 3u) << (2 * w); e8 |= ((e2 | (e2 >> 15)) & 3u) << (2 * w); }
;         gm[i] = g8; em[i] = e8; cgt += __builtin_popcount(g8); }
	v_lshl_or_b32 v0, v0, 16, v0
	v_pk_sub_u16 v50, v6, v0 clamp
	v_pk_min_u16 v50, v50, v235
	v_pk_sub_u16 v51, v0, v6 clamp
	v_pk_min_u16 v51, v51, v235
	v_and_b32_e32 v117, 32, v182
	v_add_u32_e32 v51, v50, v51
	v_sub_u32_e32 v51, 0x10001, v51
	v_lshrrev_b32_e32 v52, 15, v50
	v_bitop3_b32 v50, v52, 3, v50 bitop3:0xc8
	v_lshrrev_b32_e32 v52, 15, v51
	v_bitop3_b32 v51, v52, 3, v51 bitop3:0xc8
	v_pk_sub_u16 v52, v7, v0 clamp
	v_pk_min_u16 v52, v52, v235
	v_pk_sub_u16 v53, v0, v7 clamp
	v_pk_min_u16 v53, v53, v235
	v_cmp_eq_u32_e64 s[6:7], 0, v117
	v_lshrrev_b32_e32 v54, 15, v52
	v_add_u32_e32 v53, v52, v53
	v_or_b32_e32 v52, v54, v52
	v_sub_u32_e32 v53, 0x10001, v53
	v_lshlrev_b32_e32 v52, 2, v52
	v_and_or_b32 v50, v52, 12, v50
	v_lshrrev_b32_e32 v52, 15, v53
	v_or_b32_e32 v52, v52, v53
	v_lshlrev_b32_e32 v52, 2, v52
	v_and_or_b32 v51, v52, 12, v51
	v_pk_sub_u16 v52, v8, v0 clamp
	v_pk_min_u16 v52, v52, v235
	v_pk_sub_u16 v53, v0, v8 clamp
	v_pk_min_u16 v53, v53, v235
	v_cmp_ne_u32_e64 s[8:9], 0, v117
	v_add_u32_e32 v53, v52, v53
	v_sub_u32_e32 v53, 0x10001, v53
	v_lshrrev_b32_e32 v54, 15, v52
	v_or_b32_e32 v52, v54, v52
	v_lshrrev_b32_e32 v54, 15, v53
	v_or_b32_e32 v53, v54, v53
	v_pk_sub_u16 v54, v9, v0 clamp
	v_pk_min_u16 v54, v54, v235
	v_pk_sub_u16 v55, v0, v9 clamp
	v_pk_min_u16 v55, v55, v235
	v_lshlrev_b32_e32 v52, 4, v52
	v_lshrrev_b32_e32 v56, 15, v54
	v_add_u32_e32 v55, v54, v55
	v_or_b32_e32 v54, v56, v54
	v_lshlrev_b32_e32 v54, 6, v54
	v_and_b32_e32 v52, 48, v52
	v_sub_u32_e32 v55, 0x10001, v55
	v_and_b32_e32 v54, 0xc0, v54
	v_or3_b32 v108, v50, v52, v54
	v_lshrrev_b32_e32 v50, 15, v55
	v_or_b32_e32 v50, v50, v55
	v_lshlrev_b32_e32 v53, 4, v53
	v_lshlrev_b32_e32 v50, 6, v50
	v_and_b32_e32 v53, 48, v53
	v_and_b32_e32 v50, 0xc0, v50
	v_pk_sub_u16 v67, v2, v0 clamp
	v_pk_min_u16 v67, v67, v235
	v_pk_sub_u16 v109, v0, v2 clamp
	v_pk_min_u16 v109, v109, v235
	v_pk_sub_u16 v110, v3, v0 clamp
	v_pk_min_u16 v110, v110, v235
	v_or3_b32 v116, v51, v53, v50
	v_lshrrev_b32_e32 v52, 15, v110
	v_lshrrev_b32_e32 v51, 15, v67
	v_or_b32_e32 v52, v52, v110
	v_bitop3_b32 v51, v51, 3, v67 bitop3:0xc8
	v_lshlrev_b32_e32 v52, 2, v52
	v_pk_sub_u16 v111, v0, v3 clamp
	v_pk_min_u16 v111, v111, v235
	v_and_or_b32 v51, v52, 12, v51
	v_pk_sub_u16 v112, v4, v0 clamp
	v_pk_min_u16 v112, v112, v235
	v_pk_sub_u16 v113, v0, v4 clamp
	v_pk_min_u16 v113, v113, v235
	v_pk_sub_u16 v114, v5, v0 clamp
	v_pk_min_u16 v114, v114, v235
	v_pk_sub_u16 v115, v0, v5 clamp
	v_pk_min_u16 v115, v115, v235
	v_pk_sub_u16 v100, v46, v0 clamp
	v_pk_min_u16 v100, v100, v235
	v_pk_sub_u16 v101, v0, v46 clamp
	v_pk_min_u16 v101, v101, v235
	s_nop 0
	v_lshrrev_b32_e32 v52, 15, v112
	v_lshrrev_b32_e32 v53, 15, v114
	v_or_b32_e32 v52, v52, v112
	v_or_b32_e32 v53, v53, v114
	v_pk_sub_u16 v102, v47, v0 clamp
	v_pk_min_u16 v102, v102, v235
	v_pk_sub_u16 v103, v0, v47 clamp
	v_pk_min_u16 v103, v103, v235
	v_pk_sub_u16 v104, v48, v0 clamp
	v_pk_min_u16 v104, v104, v235
	v_pk_sub_u16 v105, v0, v48 clamp
	v_pk_min_u16 v105, v105, v235
	v_pk_sub_u16 v106, v49, v0 clamp
	v_pk_min_u16 v106, v106, v235
	v_pk_sub_u16 v107, v0, v49 clamp
	v_pk_min_u16 v107, v107, v235
	s_nop 0
	v_lshrrev_b32_e32 v47, 15, v102
	v_pk_sub_u16 v91, v42, v0 clamp
	v_pk_min_u16 v91, v91, v235
	v_pk_sub_u16 v92, v0, v42 clamp
	v_pk_min_u16 v92, v92, v235
	v_pk_sub_u16 v93, v43, v0 clamp
	v_pk_min_u16 v93, v93, v235
	v_pk_sub_u16 v94, v0, v43 clamp
	v_pk_min_u16 v94, v94, v235
	v_lshlrev_b32_e32 v52, 4, v52
	v_lshrrev_b32_e32 v43, 15, v93
	v_lshlrev_b32_e32 v53, 6, v53
	v_lshrrev_b32_e32 v46, 15, v100
	v_or_b32_e32 v47, v47, v102
	v_lshrrev_b32_e32 v42, 15, v91
	v_or_b32_e32 v43, v43, v93
	v_pk_sub_u16 v95, v44, v0 clamp
	v_pk_min_u16 v95, v95, v235
	v_pk_sub_u16 v96, v0, v44 clamp
	v_pk_min_u16 v96, v96, v235
	v_pk_sub_u16 v97, v45, v0 clamp
	v_pk_min_u16 v97, v97, v235
	v_pk_sub_u16 v98, v0, v45 clamp
	v_pk_min_u16 v98, v98, v235
	v_pk_sub_u16 v82, v38, v0 clamp
	v_pk_min_u16 v82, v82, v235
	v_pk_sub_u16 v83, v0, v38 clamp
	v_pk_min_u16 v83, v83, v235
	v_pk_sub_u16 v84, v39, v0 clamp
	v_pk_min_u16 v84, v84, v235
	v_pk_sub_u16 v85, v0, v39 clamp
	v_pk_min_u16 v85, v85, v235
	v_pk_sub_u16 v86, v40, v0 clamp
	v_pk_min_u16 v86, v86, v235
	v_pk_sub_u16 v87, v0, v40 clamp
	v_pk_min_u16 v87, v87, v235
	v_pk_sub_u16 v88, v41, v0 clamp
	v_pk_min_u16 v88, v88, v235
	v_pk_sub_u16 v89, v0, v41 clamp
	v_pk_min_u16 v89, v89, v235
	s_nop 0
	v_lshrrev_b32_e32 v39, 15, v84
	s_waitcnt vmcnt(2)
	v_pk_sub_u16 v73, v34, v0 clamp
	v_pk_min_u16 v73, v73, v235
	s_waitcnt vmcnt(1)
	v_pk_sub_u16 v74, v0, v34 clamp
	v_pk_min_u16 v74, v74, v235
	v_pk_sub_u16 v75, v35, v0 clamp
	v_pk_min_u16 v75, v75, v235
	v_pk_sub_u16 v76, v0, v35 clamp
	v_pk_min_u16 v76, v76, v235
	v_and_b32_e32 v52, 48, v52
	v_lshrrev_b32_e32 v35, 15, v75
	v_and_b32_e32 v53, 0xc0, v53
	v_bitop3_b32 v46, v46, 3, v100 bitop3:0xc8
	v_lshlrev_b32_e32 v47, 2, v47
	v_bitop3_b32 v42, v42, 3, v91 bitop3:0xc8
	v_lshlrev_b32_e32 v43, 2, v43
	v_lshrrev_b32_e32 v38, 15, v82
	v_or_b32_e32 v39, v39, v84
	v_lshrrev_b32_e32 v34, 15, v73
	v_or_b32_e32 v35, v35, v75
	v_or3_b32 v99, v51, v52, v53
	v_and_or_b32 v46, v47, 12, v46
	v_lshrrev_b32_e32 v47, 15, v104
	v_lshrrev_b32_e32 v48, 15, v106
	v_and_or_b32 v42, v43, 12, v42
	v_lshrrev_b32_e32 v43, 15, v95
	v_lshrrev_b32_e32 v44, 15, v97
	v_bitop3_b32 v38, v38, 3, v82 bitop3:0xc8
	v_lshlrev_b32_e32 v39, 2, v39
	v_bitop3_b32 v34, v34, 3, v73 bitop3:0xc8
	v_lshlrev_b32_e32 v35, 2, v35
	v_pk_sub_u16 v77, v36, v0 clamp
	v_pk_min_u16 v77, v77, v235
	s_waitcnt vmcnt(0)
; __device__ __forceinline__ unsigned pk_flag_gt(unsigned k2, unsigned T2, unsigned one2) { unsigned t; asm volatile("v_pk_sub_u16 %0, %1, %2 clamp\n\tv_pk_min_u16 %0, %0, %3" : "=&v"(t) : "v"(k2), "v"(T2), "v"(one2)); return t; }
; template <int NCH>
; __device__ __forceinline__ void idx_select(const unsigned short* sc, unsigned* bits, size_t tok0, int tid) {
;     ...
;     for (int i = 0; i < NCH; ++i) { unsigned g8 = 0u, e8 = 0u;
; #pragma unroll
;         for (int w = 0; w < 4; ++w) { const unsigned g2 = pk_flag_gt(kw[4 * i + w], T2, one2), l2 = pk_flag_gt(T2, kw[4 * i + w], one2), e2 = one2 - g2 - l2;
;             g8 |= ((g2 | (g2 >> 15)) & 3u) << (2 * w); e8 |= ((e2 | (e2 >> 15)) & 3u) << (2 * w); }
;         gm[i] = g8; em[i] = e8; cgt += __builtin_popcount(g8); }
	v_pk_sub_u16 v78, v0, v36 clamp
	v_pk_min_u16 v78, v78, v235
	v_pk_sub_u16 v79, v37, v0 clamp
	v_pk_min_u16 v79, v79, v235
	v_pk_sub_u16 v80, v0, v37 clamp
	v_pk_min_u16 v80, v80, v235
	v_pk_sub_u16 v61, v30, v0 clamp
	v_pk_min_u16 v61, v61, v235
	v_pk_sub_u16 v62, v0, v30 clamp
	v_pk_min_u16 v62, v62, v235
	v_pk_sub_u16 v63, v31, v0 clamp
	v_pk_min_u16 v63, v63, v235
	v_pk_sub_u16 v64, v0, v31 clamp
	v_pk_min_u16 v64, v64, v235
	v_pk_sub_u16 v65, v32, v0 clamp
	v_pk_min_u16 v65, v65, v235
	v_pk_sub_u16 v69, v0, v32 clamp
	v_pk_min_u16 v69, v69, v235
	v_pk_sub_u16 v70, v33, v0 clamp
	v_pk_min_u16 v70, v70, v235
	v_pk_sub_u16 v71, v0, v33 clamp
	v_pk_min_u16 v71, v71, v235
	s_nop 0
	v_lshrrev_b32_e32 v31, 15, v63
	v_pk_sub_u16 v52, v26, v0 clamp
	v_pk_min_u16 v52, v52, v235
	v_pk_sub_u16 v53, v0, v26 clamp
	v_pk_min_u16 v53, v53, v235
	v_pk_sub_u16 v54, v27, v0 clamp
	v_pk_min_u16 v54, v54, v235
	v_pk_sub_u16 v55, v0, v27 clamp
	v_pk_min_u16 v55, v55, v235
	v_or_b32_e32 v47, v47, v104
	v_lshrrev_b32_e32 v27, 15, v54
	v_or_b32_e32 v48, v48, v106
	v_or_b32_e32 v43, v43, v95
	v_or_b32_e32 v44, v44, v97
	v_and_or_b32 v38, v39, 12, v38
	v_lshrrev_b32_e32 v39, 15, v86
	v_lshrrev_b32_e32 v40, 15, v88
	v_and_or_b32 v34, v35, 12, v34
	v_lshrrev_b32_e32 v35, 15, v77
	v_lshrrev_b32_e32 v36, 15, v79
	v_lshrrev_b32_e32 v30, 15, v61
	v_or_b32_e32 v31, v31, v63
	v_lshrrev_b32_e32 v26, 15, v52
	v_or_b32_e32 v27, v27, v54
	v_lshlrev_b32_e32 v47, 4, v47
	v_lshlrev_b32_e32 v48, 6, v48
	v_lshlrev_b32_e32 v43, 4, v43
	v_lshlrev_b32_e32 v44, 6, v44
	v_or_b32_e32 v39, v39, v86
	v_or_b32_e32 v40, v40, v88
	v_or_b32_e32 v35, v35, v77
	v_or_b32_e32 v36, v36, v79
	v_bitop3_b32 v30, v30, 3, v61 bitop3:0xc8
	v_lshlrev_b32_e32 v31, 2, v31
	v_bitop3_b32 v26, v26, 3, v52 bitop3:0xc8
	v_lshlrev_b32_e32 v27, 2, v27
	v_and_b32_e32 v47, 48, v47
	v_and_b32_e32 v48, 0xc0, v48
	v_and_b32_e32 v43, 48, v43
	v_and_b32_e32 v44, 0xc0, v44
	v_lshlrev_b32_e32 v39, 4, v39
	v_lshlrev_b32_e32 v40, 6, v40
	v_lshlrev_b32_e32 v35, 4, v35
	v_lshlrev_b32_e32 v36, 6, v36
	v_and_or_b32 v30, v31, 12, v30
	v_lshrrev_b32_e32 v31, 15, v65
	v_lshrrev_b32_e32 v32, 15, v70
	v_and_or_b32 v26, v27, 12, v26
	v_pk_sub_u16 v56, v28, v0 clamp
	v_pk_min_u16 v56, v56, v235
	v_pk_sub_u16 v57, v0, v28 clamp
	v_pk_min_u16 v57, v57, v235
	v_pk_sub_u16 v58, v29, v0 clamp
	v_pk_min_u16 v58, v58, v235
	v_bcnt_u32_b32 v50, v108, 0
	v_lshrrev_b32_e32 v27, 15, v56
	v_lshrrev_b32_e32 v28, 15, v58
	v_or3_b32 v90, v46, v47, v48
	v_or3_b32 v81, v42, v43, v44
	v_and_b32_e32 v39, 48, v39
	v_and_b32_e32 v40, 0xc0, v40
	v_and_b32_e32 v35, 48, v35
	v_and_b32_e32 v36, 0xc0, v36
	v_or_b32_e32 v31, v31, v65
	v_or_b32_e32 v32, v32, v70
	v_or_b32_e32 v27, v27, v56
	v_or_b32_e32 v28, v28, v58
	v_bcnt_u32_b32 v50, v99, v50
	v_bcnt_u32_b32 v46, v90, 0
	v_bcnt_u32_b32 v42, v81, 0
	v_or3_b32 v72, v38, v39, v40
	v_or3_b32 v60, v34, v35, v36
	v_lshlrev_b32_e32 v31, 4, v31
	v_lshlrev_b32_e32 v32, 6, v32
	v_lshlrev_b32_e32 v27, 4, v27
	v_lshlrev_b32_e32 v28, 6, v28
	v_add3_u32 v42, v50, v46, v42
	v_bcnt_u32_b32 v38, v72, 0
	v_bcnt_u32_b32 v34, v60, 0
	v_and_b32_e32 v31, 48, v31
	v_and_b32_e32 v32, 0xc0, v32
	v_and_b32_e32 v27, 48, v27
	v_and_b32_e32 v28, 0xc0, v28
	v_add3_u32 v34, v42, v38, v34
	v_or3_b32 v51, v30, v31, v32
	v_or3_b32 v42, v26, v27, v28
	v_bcnt_u32_b32 v30, v51, 0
	v_bcnt_u32_b32 v26, v42, 0
	v_pk_sub_u16 v59, v0, v29 clamp
	v_pk_min_u16 v59, v59, v235
	v_add3_u32 v26, v34, v30, v26
	v_pk_sub_u16 v43, v22, v0 clamp
	v_pk_min_u16 v43, v43, v235
	v_pk_sub_u16 v44, v0, v22 clamp
	v_pk_min_u16 v44, v44, v235
	v_pk_sub_u16 v45, v23, v0 clamp
	v_pk_min_u16 v45, v45, v235
	v_pk_sub_u16 v46, v0, v23 clamp
	v_pk_min_u16 v46, v46, v235
	v_pk_sub_u16 v47, v24, v0 clamp
	v_pk_min_u16 v47, v47, v235
	v_pk_sub_u16 v48, v0, v24 clamp
	v_pk_min_u16 v48, v48, v235
	v_pk_sub_u16 v49, v25, v0 clamp
	v_pk_min_u16 v49, v49, v235
	v_pk_sub_u16 v50, v0, v25 clamp
	v_pk_min_u16 v50, v50, v235
	s_nop 0
	v_lshrrev_b32_e32 v23, 15, v45
	v_pk_sub_u16 v33, v18, v0 clamp
	v_pk_min_u16 v33, v33, v235
	v_pk_sub_u16 v34, v0, v18 clamp
	v_pk_min_u16 v34, v34, v235
	v_pk_sub_u16 v35, v19, v0 clamp
	v_pk_min_u16 v35, v35, v235
	v_pk_sub_u16 v36, v0, v19 clamp
	v_pk_min_u16 v36, v36, v235
	v_lshrrev_b32_e32 v22, 15, v43
	v_lshrrev_b32_e32 v19, 15, v35
	v_or_b32_e32 v23, v23, v45
	v_lshrrev_b32_e32 v18, 15, v33
	v_or_b32_e32 v19, v19, v35
	v_bitop3_b32 v22, v22, 3, v43 bitop3:0xc8
	v_lshlrev_b32_e32 v23, 2, v23
	v_bitop3_b32 v18, v18, 3, v33 bitop3:0xc8
	v_lshlrev_b32_e32 v19, 2, v19
	v_and_or_b32 v22, v23, 12, v22
	v_lshrrev_b32_e32 v23, 15, v47
	v_lshrrev_b32_e32 v24, 15, v49
	v_and_or_b32 v18, v19, 12, v18
	v_pk_sub_u16 v37, v20, v0 clamp
	v_pk_min_u16 v37, v37, v235
	v_pk_sub_u16 v38, v0, v20 clamp
	v_pk_min_u16 v38, v38, v235
	v_pk_sub_u16 v39, v21, v0 clamp
	v_pk_min_u16 v39, v39, v235
	v_or_b32_e32 v23, v23, v47
	v_lshrrev_b32_e32 v19, 15, v37
	v_lshrrev_b32_e32 v20, 15, v39
	v_or_b32_e32 v24, v24, v49
	v_or_b32_e32 v19, v19, v37
	v_or_b32_e32 v20, v20, v39
	v_lshlrev_b32_e32 v23, 4, v23
	v_lshlrev_b32_e32 v24, 6, v24
	v_lshlrev_b32_e32 v19, 4, v19
	v_lshlrev_b32_e32 v20, 6, v20
	v_and_b32_e32 v23, 48, v23
	v_and_b32_e32 v24, 0xc0, v24
	v_and_b32_e32 v19, 48, v19
	v_and_b32_e32 v20, 0xc0, v20
	v_or3_b32 v32, v22, v23, v24
	v_or3_b32 v23, v18, v19, v20
; __device__ __forceinline__ int red32(int v) {
;     v += __builtin_amdgcn_mov_dpp(v, 0xB1, 0xf, 0xf, true);
;     v += __builtin_amdgcn_mov_dpp(v, 0x4E, 0xf, 0xf, true);
;     v += __builtin_amdgcn_mov_dpp(v, 0x141, 0xf, 0xf, true);
;     v += __builtin_amdgcn_mov_dpp(v, 0x140, 0xf, 0xf, true);
;     v += __builtin_amdgcn_ds_swizzle(v, 0x401F);
;     return v;
; }
; __device__ __forceinline__ unsigned ltu(unsigned a, unsigned b) { unsigned d; asm volatile("v_sub_u32 %0, %1, %2\n\tv_lshrrev_b32 %0, 31, %0" : "=v"(d) : "v"(a), "v"(b)); return d; }
; __device__ __forceinline__ unsigned pk_flag_gt(unsigned k2, unsigned T2, unsigned one2) { unsigned t; asm volatile("v_pk_sub_u16 %0, %1, %2 clamp\n\tv_pk_min_u16 %0, %0, %3" : "=&v"(t) : "v"(k2), "v"(T2), "v"(one2)); return t; }
; __device__ __forceinline__ int scan32_incl(int x, int lane) {
;     x += __builtin_amdgcn_update_dpp(0, x, 0x111, 0xf, 0xf, true);
;     x += __builtin_amdgcn_update_dpp(0, x, 0x112, 0xf, 0xf, true);
; template <int NCH>
; __device__ __forceinline__ void idx_select(const unsigned short* sc, unsigned* bits, size_t tok0, int tid) {
;     ...
;     for (int i = 0; i < NCH; ++i) { unsigned g8 = 0u, e8 = 0u;
; #pragma unroll
;         for (int w = 0; w < 4; ++w) { const unsigned g2 = pk_flag_gt(kw[4 * i + w], T2, one2), l2 = pk_flag_gt(T2, kw[4 * i + w], one2), e2 = one2 - g2 - l2;
;             g8 |= ((g2 | (g2 >> 15)) & 3u) << (2 * w); e8 |= ((e2 | (e2 >> 15)) & 3u) << (2 * w); }
;         gm[i] = g8; em[i] = e8; cgt += __builtin_popcount(g8); }
;     const int need = 256 - red32(cgt);
;     int carry = 0;
;     unsigned char* brow = (unsigned char*)(bits + (tok0 + row) * 128);
; #pragma unroll
;     for (int i = 0; i < NCH; ++i) { const int ec = __builtin_popcount(em[i]); const int incl = scan32_incl(ec, lane);
;         const int quota = need - carry - (incl - ec);
;         unsigned se = (quota >= ec) ? em[i] : 0u;
;         if (__any(quota > 0 && quota < ec)) { unsigned m = em[i], r = 0u;
; #pragma unroll
;             for (int t = 0; t < 8; ++t) { const unsigned b = m & (0u - m); if (t < quota) r |= b; m ^= b; }
;             if (quota > 0 && quota < ec) se = r; }
;         carry += (lane & 32) ? __builtin_amdgcn_readlane(incl, 63) : __builtin_amdgcn_readlane(incl, 31);
;         brow[i * 32 + j] = (unsigned char)(gm[i] | se); }
	v_bcnt_u32_b32 v22, v32, 0
	v_bcnt_u32_b32 v18, v23, 0
	v_pk_sub_u16 v40, v0, v21 clamp
	v_pk_min_u16 v40, v40, v235
	v_add3_u32 v41, v26, v22, v18
	v_pk_sub_u16 v24, v14, v0 clamp
	v_pk_min_u16 v24, v24, v235
	v_pk_sub_u16 v25, v0, v14 clamp
	v_pk_min_u16 v25, v25, v235
	v_pk_sub_u16 v26, v15, v0 clamp
	v_pk_min_u16 v26, v26, v235
	v_pk_sub_u16 v27, v0, v15 clamp
	v_pk_min_u16 v27, v27, v235
	v_pk_sub_u16 v28, v16, v0 clamp
	v_pk_min_u16 v28, v28, v235
	v_pk_sub_u16 v29, v0, v16 clamp
	v_pk_min_u16 v29, v29, v235
	s_nop 0
	v_lshrrev_b32_e32 v14, 15, v24
	v_lshrrev_b32_e32 v15, 15, v26
	v_or_b32_e32 v15, v15, v26
	v_bitop3_b32 v14, v14, 3, v24 bitop3:0xc8
	v_lshlrev_b32_e32 v15, 2, v15
	v_and_or_b32 v14, v15, 12, v14
	v_lshrrev_b32_e32 v15, 15, v28
	v_pk_sub_u16 v30, v17, v0 clamp
	v_pk_min_u16 v30, v30, v235
	v_or_b32_e32 v15, v15, v28
	v_lshrrev_b32_e32 v16, 15, v30
	v_or_b32_e32 v16, v16, v30
	v_lshlrev_b32_e32 v15, 4, v15
	v_lshlrev_b32_e32 v16, 6, v16
	v_and_b32_e32 v15, 48, v15
	v_and_b32_e32 v16, 0xc0, v16
	v_pk_sub_u16 v31, v0, v17 clamp
	v_pk_min_u16 v31, v31, v235
	v_or3_b32 v14, v14, v15, v16
	v_pk_sub_u16 v15, v10, v0 clamp
	v_pk_min_u16 v15, v15, v235
	v_pk_sub_u16 v16, v0, v10 clamp
	v_pk_min_u16 v16, v16, v235
	v_pk_sub_u16 v17, v11, v0 clamp
	v_pk_min_u16 v17, v17, v235
	v_pk_sub_u16 v18, v0, v11 clamp
	v_pk_min_u16 v18, v18, v235
	v_pk_sub_u16 v19, v12, v0 clamp
	v_pk_min_u16 v19, v19, v235
	v_pk_sub_u16 v20, v0, v12 clamp
	v_pk_min_u16 v20, v20, v235
	s_nop 0
	v_lshrrev_b32_e32 v10, 15, v15
	v_lshrrev_b32_e32 v11, 15, v17
	v_or_b32_e32 v11, v11, v17
	v_bitop3_b32 v10, v10, 3, v15 bitop3:0xc8
	v_lshlrev_b32_e32 v11, 2, v11
	v_and_or_b32 v10, v11, 12, v10
	v_lshrrev_b32_e32 v11, 15, v19
	v_pk_sub_u16 v21, v13, v0 clamp
	v_pk_min_u16 v21, v21, v235
	v_pk_sub_u16 v22, v0, v13 clamp
	v_pk_min_u16 v22, v22, v235
	v_or_b32_e32 v11, v11, v19
	v_lshrrev_b32_e32 v0, 15, v21
	v_or_b32_e32 v0, v0, v21
	v_lshlrev_b32_e32 v11, 4, v11
	v_lshlrev_b32_e32 v0, 6, v0
	v_and_b32_e32 v11, 48, v11
	v_and_b32_e32 v0, 0xc0, v0
	v_or3_b32 v0, v10, v11, v0
	v_bcnt_u32_b32 v118, v14, 0
	v_bcnt_u32_b32 v10, v0, 0
	v_add3_u32 v10, v41, v118, v10
	v_and_b32_e32 v12, 16, v182
	v_cmp_eq_u32_e64 s[4:5], 0, v12
	v_add_u32_dpp v10, v10, v10 quad_perm:[1,0,3,2] row_mask:0xf bank_mask:0xf bound_ctrl:1
	v_bcnt_u32_b32 v12, v116, 0
	v_bfe_i32 v13, v182, 4, 1
	v_add_u32_dpp v10, v10, v10 quad_perm:[2,3,0,1] row_mask:0xf bank_mask:0xf bound_ctrl:1
	s_nop 1
	v_add_u32_dpp v10, v10, v10 row_half_mirror row_mask:0xf bank_mask:0xf bound_ctrl:1
	s_nop 1
	v_add_u32_dpp v10, v10, v10 row_mirror row_mask:0xf bank_mask:0xf bound_ctrl:1
	v_mov_b32_e32 v11, v10
	s_nop 1
	v_permlane16_swap_b32_e32 v11, v10
	s_waitcnt lgkmcnt(0)
	v_add_u32_e32 v41, v10, v11
	v_mov_b32_dpp v10, v12 row_shr:1 row_mask:0xf bank_mask:0xf bound_ctrl:1
	v_bcnt_u32_b32 v10, v116, v10
	s_nop 1
	v_add_u32_dpp v10, v10, v10 row_shr:2 row_mask:0xf bank_mask:0xf bound_ctrl:1
	s_nop 1
	v_add_u32_dpp v10, v10, v10 row_shr:4 row_mask:0xf bank_mask:0xf bound_ctrl:1
	s_nop 1
	v_add_u32_dpp v10, v10, v10 row_shr:8 row_mask:0xf bank_mask:0xf bound_ctrl:1
	s_nop 0
	v_readlane_b32 s0, v10, 15
	v_readlane_b32 s1, v10, 47
	s_nop 0
	v_mov_b32_e32 v118, s0
	v_mov_b32_e32 v11, s1
	v_cndmask_b32_e64 v11, v11, v118, s[6:7]
	v_and_b32_e32 v11, v13, v11
	v_add_u32_e32 v10, v11, v10
	v_or_b32_e32 v11, 0x100, v12
	v_add_u32_e32 v13, v41, v10
	v_sub_u32_e32 v11, v11, v13
	v_cmp_lt_i32_e64 s[0:1], v11, v12
	v_cmp_lt_i32_e64 s[10:11], 0, v11
	s_and_b64 vcc, s[10:11], s[0:1]
	v_cndmask_b32_e64 v12, v116, 0, s[0:1]
	s_cbranch_vccz .LBB0_507
	v_sub_u32_e32 v13, 0, v116
	v_and_b32_e32 v117, v116, v13
	v_bitop3_b32 v13, v116, v116, v13 bitop3:0x6c
	v_sub_u32_e32 v119, 0, v13
	v_cndmask_b32_e64 v118, 0, v117, s[10:11]
	v_bitop3_b32 v120, v117, v119, v116 bitop3:0x48
	v_cmp_lt_i32_e32 vcc, 1, v11
	v_bitop3_b32 v117, v117, v116, v119 bitop3:0x14
	v_sub_u32_e32 v119, 0, v117
	v_cndmask_b32_e32 v121, 0, v120, vcc
	v_or_b32_e32 v118, v121, v118
	v_bitop3_b32 v121, v120, v119, v13 bitop3:0x48
	v_bitop3_b32 v13, v120, v13, v119 bitop3:0x14
	v_sub_u32_e32 v119, 0, v13
	v_bitop3_b32 v120, v121, v119, v117 bitop3:0x48
	v_bitop3_b32 v117, v121, v117, v119 bitop3:0x14
	v_cmp_lt_i32_e32 vcc, 2, v11
	v_sub_u32_e32 v119, 0, v117
	s_nop 0
	v_cndmask_b32_e32 v122, 0, v121, vcc
	v_bitop3_b32 v121, v120, v119, v13 bitop3:0x48
	v_bitop3_b32 v13, v120, v13, v119 bitop3:0x14
	v_cmp_lt_i32_e32 vcc, 3, v11
	v_sub_u32_e32 v119, 0, v13
	s_nop 0
	v_cndmask_b32_e32 v123, 0, v120, vcc
	v_bitop3_b32 v120, v121, v119, v117 bitop3:0x48
	v_bitop3_b32 v117, v121, v117, v119 bitop3:0x14
	v_cmp_lt_i32_e32 vcc, 4, v11
	v_sub_u32_e32 v119, 0, v117
	v_or3_b32 v118, v118, v122, v123
	v_cndmask_b32_e32 v122, 0, v121, vcc
	v_cmp_lt_i32_e32 vcc, 5, v11
	v_bitop3_b32 v121, v120, v119, v13 bitop3:0x48
	v_bitop3_b32 v13, v120, v13, v119 bitop3:0x14
	v_cndmask_b32_e32 v123, 0, v120, vcc
	v_cmp_lt_i32_e32 vcc, 6, v11
	v_sub_u32_e32 v13, 0, v13
	v_or3_b32 v118, v118, v122, v123
	v_cndmask_b32_e32 v122, 0, v121, vcc
	v_bitop3_b32 v13, v121, v13, v117 bitop3:0x48
	v_cmp_lt_i32_e32 vcc, 7, v11
	s_nop 1
	v_cndmask_b32_e32 v11, 0, v13, vcc
	v_or3_b32 v11, v118, v122, v11
	v_cndmask_b32_e64 v11, v116, v11, s[0:1]
	v_cndmask_b32_e64 v12, v12, v11, s[10:11]

; __device__ __forceinline__ void pk_cnt_lt(unsigned& acc, unsigned k2, unsigned mid2, unsigned one2) {
;     unsigned t; asm volatile("v_pk_sub_u16 %0, %2, %3 clamp\n\tv_pk_min_u16 %0, %0, %4\n\tv_pk_add_u16 %1, %1, %0" : "=&v"(t), "+v"(acc) : "v"(mid2), "v"(k2), "v"(one2));
; }
; __device__ __forceinline__ int red32(int v) {
;     v += __builtin_amdgcn_mov_dpp(v, 0xB1, 0xf, 0xf, true);
;     v += __builtin_amdgcn_mov_dpp(v, 0x4E, 0xf, 0xf, true);
;     v += __builtin_amdgcn_mov_dpp(v, 0x141, 0xf, 0xf, true);
;     v += __builtin_amdgcn_mov_dpp(v, 0x140, 0xf, 0xf, true);
;     v += __builtin_amdgcn_ds_swizzle(v, 0x401F);
;     return v;
; }
; template <int NCH>
; __device__ __forceinline__ void idx_select(const unsigned short* sc, unsigned* bits, size_t tok0, int tid) {
;     ...
; #pragma unroll 1
;     for (int it = 0; it < 16; ++it) { const unsigned mid = (lo + hi_ + 1u) >> 1, mid2 = mid | (mid << 16);
;         unsigned c2a = 0u, c2b = 0u;
; #pragma unroll
;         for (int i = 0; i < 4 * NCH; i += 2) { pk_cnt_lt(c2a, kw[i], mid2, one2); pk_cnt_lt(c2b, kw[i + 1], mid2, one2); }
;         int cnt = 8 * NCH - (int)((c2a & 0xFFFFu) + (c2a >> 16) + (c2b & 0xFFFFu) + (c2b >> 16));
;         cnt = red32(cnt);
;         if (cnt >= 256) lo = mid; else hi_ = mid - 1u;
;         if (cnt == 256) hi_ = mid;
;         if (__all(lo == hi_)) break; }
.LBB0_578:
	v_add3_u32 v44, v0, v43, 1
	v_lshrrev_b32_e32 v44, 1, v44
	v_mov_b32_e32 v46, 0
	v_lshl_or_b32 v45, v44, 16, v44
	s_waitcnt lgkmcnt(9)
	v_pk_sub_u16 v47, v45, v6 clamp
	v_pk_min_u16 v47, v47, v235
	v_pk_add_u16 v46, v46, v47
	s_nop 0
	v_mov_b32_e32 v47, 0
	v_pk_sub_u16 v48, v45, v7 clamp
	v_pk_min_u16 v48, v48, v235
	v_pk_add_u16 v47, v47, v48
	v_pk_sub_u16 v48, v45, v8 clamp
	v_pk_min_u16 v48, v48, v235
	v_pk_add_u16 v46, v46, v48
	v_pk_sub_u16 v48, v45, v9 clamp
	v_pk_min_u16 v48, v48, v235
	v_pk_add_u16 v47, v47, v48
	s_waitcnt lgkmcnt(8)
	v_pk_sub_u16 v48, v45, v2 clamp
	v_pk_min_u16 v48, v48, v235
	v_pk_add_u16 v46, v46, v48
	v_pk_sub_u16 v48, v45, v3 clamp
	v_pk_min_u16 v48, v48, v235
	v_pk_add_u16 v47, v47, v48
	v_pk_sub_u16 v48, v45, v4 clamp
	v_pk_min_u16 v48, v48, v235
	v_pk_add_u16 v46, v46, v48
	v_pk_sub_u16 v48, v45, v5 clamp
	v_pk_min_u16 v48, v48, v235
	v_pk_add_u16 v47, v47, v48
	s_waitcnt lgkmcnt(7)
	v_pk_sub_u16 v48, v45, v38 clamp
	v_pk_min_u16 v48, v48, v235
	v_pk_add_u16 v46, v46, v48
	v_pk_sub_u16 v48, v45, v39 clamp
	v_pk_min_u16 v48, v48, v235
	v_pk_add_u16 v47, v47, v48
	v_pk_sub_u16 v48, v45, v40 clamp
	v_pk_min_u16 v48, v48, v235
	v_pk_add_u16 v46, v46, v48
	v_pk_sub_u16 v48, v45, v41 clamp
	v_pk_min_u16 v48, v48, v235
	v_pk_add_u16 v47, v47, v48
	s_waitcnt lgkmcnt(6)
	v_pk_sub_u16 v48, v45, v34 clamp
	v_pk_min_u16 v48, v48, v235
	v_pk_add_u16 v46, v46, v48
	v_pk_sub_u16 v48, v45, v35 clamp
	v_pk_min_u16 v48, v48, v235
	v_pk_add_u16 v47, v47, v48
	v_pk_sub_u16 v48, v45, v36 clamp
	v_pk_min_u16 v48, v48, v235
	v_pk_add_u16 v46, v46, v48
	v_pk_sub_u16 v48, v45, v37 clamp
	v_pk_min_u16 v48, v48, v235
	v_pk_add_u16 v47, v47, v48
	s_waitcnt lgkmcnt(5)
	v_pk_sub_u16 v48, v45, v30 clamp
	v_pk_min_u16 v48, v48, v235
	v_pk_add_u16 v46, v46, v48
	v_pk_sub_u16 v48, v45, v31 clamp
	v_pk_min_u16 v48, v48, v235
	v_pk_add_u16 v47, v47, v48
	v_pk_sub_u16 v48, v45, v32 clamp
	v_pk_min_u16 v48, v48, v235
	v_pk_add_u16 v46, v46, v48
	v_pk_sub_u16 v48, v45, v33 clamp
	v_pk_min_u16 v48, v48, v235
	v_pk_add_u16 v47, v47, v48
	s_waitcnt lgkmcnt(4)
	v_pk_sub_u16 v48, v45, v26 clamp
	v_pk_min_u16 v48, v48, v235
	v_pk_add_u16 v46, v46, v48
	v_pk_sub_u16 v48, v45, v27 clamp
	v_pk_min_u16 v48, v48, v235
	v_pk_add_u16 v47, v47, v48
	v_pk_sub_u16 v48, v45, v28 clamp
	v_pk_min_u16 v48, v48, v235
	v_pk_add_u16 v46, v46, v48
	v_pk_sub_u16 v48, v45, v29 clamp
	v_pk_min_u16 v48, v48, v235
	v_pk_add_u16 v47, v47, v48
	s_waitcnt lgkmcnt(3)
	v_pk_sub_u16 v48, v45, v22 clamp
	v_pk_min_u16 v48, v48, v235
	v_pk_add_u16 v46, v46, v48
	v_pk_sub_u16 v48, v45, v23 clamp
	v_pk_min_u16 v48, v48, v235
	v_pk_add_u16 v47, v47, v48
	v_pk_sub_u16 v48, v45, v24 clamp
	v_pk_min_u16 v48, v48, v235
	v_pk_add_u16 v46, v46, v48
	v_pk_sub_u16 v48, v45, v25 clamp
	v_pk_min_u16 v48, v48, v235
	v_pk_add_u16 v47, v47, v48
	s_waitcnt lgkmcnt(2)
	v_pk_sub_u16 v48, v45, v18 clamp
	v_pk_min_u16 v48, v48, v235
	v_pk_add_u16 v46, v46, v48
	v_pk_sub_u16 v48, v45, v19 clamp
	v_pk_min_u16 v48, v48, v235
	v_pk_add_u16 v47, v47, v48
	v_pk_sub_u16 v48, v45, v20 clamp
	v_pk_min_u16 v48, v48, v235
	v_pk_add_u16 v46, v46, v48
	v_pk_sub_u16 v48, v45, v21 clamp
	v_pk_min_u16 v48, v48, v235
	v_pk_add_u16 v47, v47, v48
	s_waitcnt lgkmcnt(1)
	v_pk_sub_u16 v48, v45, v14 clamp
	v_pk_min_u16 v48, v48, v235
	v_pk_add_u16 v46, v46, v48
	v_pk_sub_u16 v48, v45, v15 clamp
	v_pk_min_u16 v48, v48, v235
	v_pk_add_u16 v47, v47, v48
	v_pk_sub_u16 v48, v45, v16 clamp
	v_pk_min_u16 v48, v48, v235
	v_pk_add_u16 v46, v46, v48
	v_pk_sub_u16 v48, v45, v17 clamp
	v_pk_min_u16 v48, v48, v235
	v_pk_add_u16 v47, v47, v48
	s_waitcnt lgkmcnt(0)
	v_pk_sub_u16 v48, v45, v10 clamp
	v_pk_min_u16 v48, v48, v235
	v_pk_add_u16 v46, v46, v48
	v_pk_sub_u16 v48, v45, v11 clamp
	v_pk_min_u16 v48, v48, v235
	v_pk_add_u16 v47, v47, v48
	v_pk_sub_u16 v48, v45, v12 clamp
	v_pk_min_u16 v48, v48, v235
	v_pk_add_u16 v46, v46, v48
	v_pk_sub_u16 v48, v45, v13 clamp
	v_pk_min_u16 v48, v48, v235
	v_pk_add_u16 v47, v47, v48
	v_add_u32_sdwa v46, v46, v46 dst_sel:DWORD dst_unused:UNUSED_PAD src0_sel:WORD_1 src1_sel:WORD_0
	v_and_b32_e32 v45, 0xffff, v47
	v_lshrrev_b32_e32 v47, 16, v47
	v_add3_u32 v45, v46, v45, v47
	v_sub_u32_e32 v45, 0x50, v45
	s_nop 1
	v_add_u32_dpp v45, v45, v45 quad_perm:[1,0,3,2] row_mask:0xf bank_mask:0xf bound_ctrl:1
	s_nop 1
	v_add_u32_dpp v45, v45, v45 quad_perm:[2,3,0,1] row_mask:0xf bank_mask:0xf bound_ctrl:1
	s_nop 1
	v_add_u32_dpp v45, v45, v45 row_half_mirror row_mask:0xf bank_mask:0xf bound_ctrl:1
	s_nop 1
	v_add_u32_dpp v45, v45, v45 row_mirror row_mask:0xf bank_mask:0xf bound_ctrl:1
	v_mov_b32_e32 v46, v45
	s_nop 1
	v_permlane16_swap_b32_e32 v46, v45
	s_waitcnt lgkmcnt(0)
	v_add_u32_e32 v45, v45, v46
	v_cmp_lt_i32_e32 vcc, s88, v45
	v_add_u32_e32 v46, -1, v44
	s_nop 0
	v_cndmask_b32_e32 v43, v46, v43, vcc
	v_cndmask_b32_e32 v0, v0, v44, vcc
	v_cmp_eq_u32_e32 vcc, s33, v45
	s_nop 1
	v_cndmask_b32_e32 v43, v43, v44, vcc
	v_cmp_eq_u32_e32 vcc, v0, v43
	s_cmp_eq_u64 vcc, exec
	s_cselect_b64 s[0:1], -1, 0
	v_subrev_co_u32_e32 v42, vcc, 1, v42
	s_or_b64 s[0:1], s[0:1], vcc
	s_andn2_b64 vcc, exec, s[0:1]
	s_cbranch_vccnz .LBB0_578
; __device__ __forceinline__ unsigned pk_flag_gt(unsigned k2, unsigned T2, unsigned one2) { unsigned t; asm volatile("v_pk_sub_u16 %0, %1, %2 clamp\n\tv_pk_min_u16 %0, %0, %3" : "=&v"(t) : "v"(k2), "v"(T2), "v"(one2)); return t; }
; template <int NCH>
; __device__ __forceinline__ void idx_select(const unsigned short* sc, unsigned* bits, size_t tok0, int tid) {
;     ...
;     const unsigned T = lo, T2 = T | (T << 16);
;     unsigned gm[NCH], em[NCH]; int cgt = 0;
; #pragma unroll
;     for (int i = 0; i < NCH; ++i) { unsigned g8 = 0u, e8 = 0u;
; #pragma unroll
;         for (int w = 0; w < 4; ++w) { const unsigned g2 = pk_flag_gt(kw[4 * i + w], T2, one2), l2 = pk_flag_gt(T2, kw[4 * i + w], one2), e2 = one2 - g2 - l2;
;             g8 |= ((g2 | (g2 >> 15)) & 3u) << (2 * w); e8 |= ((e2 | (e2 >> 15)) & 3u) << (2 * w); }
;         gm[i] = g8; em[i] = e8; cgt += __builtin_popcount(g8); }
	v_lshl_or_b32 v0, v0, 16, v0
	v_pk_sub_u16 v42, v6, v0 clamp
	v_pk_min_u16 v42, v42, v235
	v_pk_sub_u16 v43, v0, v6 clamp
	v_pk_min_u16 v43, v43, v235
	v_and_b32_e32 v99, 32, v182
	v_add_u32_e32 v43, v42, v43
	v_sub_u32_e32 v43, 0x10001, v43
	v_lshrrev_b32_e32 v44, 15, v42
	v_bitop3_b32 v42, v44, 3, v42 bitop3:0xc8
	v_lshrrev_b32_e32 v44, 15, v43
	v_bitop3_b32 v43, v44, 3, v43 bitop3:0xc8
	v_pk_sub_u16 v44, v7, v0 clamp
	v_pk_min_u16 v44, v44, v235
	v_pk_sub_u16 v45, v0, v7 clamp
	v_pk_min_u16 v45, v45, v235
	v_cmp_eq_u32_e64 s[6:7], 0, v99
	v_lshrrev_b32_e32 v46, 15, v44
	v_add_u32_e32 v45, v44, v45
	v_or_b32_e32 v44, v46, v44
	v_sub_u32_e32 v45, 0x10001, v45
	v_lshlrev_b32_e32 v44, 2, v44
	v_and_or_b32 v42, v44, 12, v42
	v_lshrrev_b32_e32 v44, 15, v45
	v_or_b32_e32 v44, v44, v45
	v_lshlrev_b32_e32 v44, 2, v44
	v_and_or_b32 v43, v44, 12, v43
	v_pk_sub_u16 v44, v8, v0 clamp
	v_pk_min_u16 v44, v44, v235
	v_pk_sub_u16 v45, v0, v8 clamp
	v_pk_min_u16 v45, v45, v235
	v_cmp_ne_u32_e64 s[8:9], 0, v99
	v_add_u32_e32 v45, v44, v45
	v_sub_u32_e32 v45, 0x10001, v45
	v_lshrrev_b32_e32 v46, 15, v44
	v_or_b32_e32 v44, v46, v44
	v_lshrrev_b32_e32 v46, 15, v45
	v_or_b32_e32 v45, v46, v45
	v_pk_sub_u16 v46, v9, v0 clamp
	v_pk_min_u16 v46, v46, v235
	v_pk_sub_u16 v47, v0, v9 clamp
	v_pk_min_u16 v47, v47, v235
	v_lshlrev_b32_e32 v44, 4, v44
	v_lshrrev_b32_e32 v48, 15, v46
	v_add_u32_e32 v47, v46, v47
	v_or_b32_e32 v46, v48, v46
	v_lshlrev_b32_e32 v46, 6, v46
	v_and_b32_e32 v44, 48, v44
	v_sub_u32_e32 v47, 0x10001, v47
	v_and_b32_e32 v46, 0xc0, v46
	v_or3_b32 v90, v42, v44, v46
	v_lshrrev_b32_e32 v42, 15, v47
	v_or_b32_e32 v42, v42, v47
	v_lshlrev_b32_e32 v45, 4, v45
	v_lshlrev_b32_e32 v42, 6, v42
	v_and_b32_e32 v45, 48, v45
	v_and_b32_e32 v42, 0xc0, v42
	v_pk_sub_u16 v67, v2, v0 clamp
	v_pk_min_u16 v67, v67, v235
	v_pk_sub_u16 v91, v0, v2 clamp
	v_pk_min_u16 v91, v91, v235
	v_pk_sub_u16 v92, v3, v0 clamp
	v_pk_min_u16 v92, v92, v235
	v_pk_sub_u16 v93, v0, v3 clamp
	v_pk_min_u16 v93, v93, v235
	v_pk_sub_u16 v94, v4, v0 clamp
	v_pk_min_u16 v94, v94, v235
	v_pk_sub_u16 v95, v0, v4 clamp
	v_pk_min_u16 v95, v95, v235
	v_pk_sub_u16 v96, v5, v0 clamp
	v_pk_min_u16 v96, v96, v235
	v_pk_sub_u16 v97, v0, v5 clamp
	v_pk_min_u16 v97, v97, v235
	s_nop 0
	v_lshrrev_b32_e32 v44, 15, v92
	v_pk_sub_u16 v82, v38, v0 clamp
	v_pk_min_u16 v82, v82, v235
	v_pk_sub_u16 v83, v0, v38 clamp
	v_pk_min_u16 v83, v83, v235
	v_pk_sub_u16 v84, v39, v0 clamp
	v_pk_min_u16 v84, v84, v235
	v_pk_sub_u16 v85, v0, v39 clamp
	v_pk_min_u16 v85, v85, v235
	v_pk_sub_u16 v86, v40, v0 clamp
	v_pk_min_u16 v86, v86, v235
	v_pk_sub_u16 v87, v0, v40 clamp
	v_pk_min_u16 v87, v87, v235
	v_pk_sub_u16 v88, v41, v0 clamp
	v_pk_min_u16 v88, v88, v235
	v_pk_sub_u16 v89, v0, v41 clamp
	v_pk_min_u16 v89, v89, v235
	s_nop 0
	v_lshrrev_b32_e32 v39, 15, v84
	s_waitcnt vmcnt(2)
	v_pk_sub_u16 v73, v34, v0 clamp
	v_pk_min_u16 v73, v73, v235
	s_waitcnt vmcnt(1)
	v_pk_sub_u16 v74, v0, v34 clamp
	v_pk_min_u16 v74, v74, v235
	v_pk_sub_u16 v75, v35, v0 clamp
	v_pk_min_u16 v75, v75, v235
	v_pk_sub_u16 v76, v0, v35 clamp
	v_pk_min_u16 v76, v76, v235
	v_or3_b32 v98, v43, v45, v42
	v_lshrrev_b32_e32 v35, 15, v75
	v_lshrrev_b32_e32 v43, 15, v67
	v_or_b32_e32 v44, v44, v92
	v_lshrrev_b32_e32 v38, 15, v82
	v_or_b32_e32 v39, v39, v84
	v_lshrrev_b32_e32 v34, 15, v73
	v_or_b32_e32 v35, v35, v75
	v_bitop3_b32 v43, v43, 3, v67 bitop3:0xc8
	v_lshlrev_b32_e32 v44, 2, v44
	v_bitop3_b32 v38, v38, 3, v82 bitop3:0xc8
	v_lshlrev_b32_e32 v39, 2, v39
	v_bitop3_b32 v34, v34, 3, v73 bitop3:0xc8
	v_lshlrev_b32_e32 v35, 2, v35
	v_pk_sub_u16 v77, v36, v0 clamp
	v_pk_min_u16 v77, v77, v235
	s_waitcnt vmcnt(0)
	v_pk_sub_u16 v78, v0, v36 clamp
	v_pk_min_u16 v78, v78, v235
	v_pk_sub_u16 v79, v37, v0 clamp
	v_pk_min_u16 v79, v79, v235
	v_pk_sub_u16 v80, v0, v37 clamp
	v_pk_min_u16 v80, v80, v235
	v_pk_sub_u16 v61, v30, v0 clamp
	v_pk_min_u16 v61, v61, v235
	v_pk_sub_u16 v62, v0, v30 clamp
	v_pk_min_u16 v62, v62, v235
	v_pk_sub_u16 v63, v31, v0 clamp
	v_pk_min_u16 v63, v63, v235
	v_pk_sub_u16 v64, v0, v31 clamp
	v_pk_min_u16 v64, v64, v235
	v_pk_sub_u16 v65, v32, v0 clamp
	v_pk_min_u16 v65, v65, v235
	v_pk_sub_u16 v69, v0, v32 clamp
	v_pk_min_u16 v69, v69, v235
	v_pk_sub_u16 v70, v33, v0 clamp
	v_pk_min_u16 v70, v70, v235
	v_pk_sub_u16 v71, v0, v33 clamp
	v_pk_min_u16 v71, v71, v235
	s_nop 0
	v_lshrrev_b32_e32 v31, 15, v63
	v_pk_sub_u16 v52, v26, v0 clamp
	v_pk_min_u16 v52, v52, v235
	v_pk_sub_u16 v53, v0, v26 clamp
	v_pk_min_u16 v53, v53, v235
	v_pk_sub_u16 v54, v27, v0 clamp
	v_pk_min_u16 v54, v54, v235
	v_pk_sub_u16 v55, v0, v27 clamp
	v_pk_min_u16 v55, v55, v235
	v_and_or_b32 v43, v44, 12, v43
	v_lshrrev_b32_e32 v27, 15, v54
	v_lshrrev_b32_e32 v44, 15, v94
	v_lshrrev_b32_e32 v45, 15, v96
	v_and_or_b32 v38, v39, 12, v38
	v_lshrrev_b32_e32 v39, 15, v86
	v_lshrrev_b32_e32 v40, 15, v88
	v_and_or_b32 v34, v35, 12, v34
	v_lshrrev_b32_e32 v35, 15, v77
	v_lshrrev_b32_e32 v36, 15, v79
	v_lshrrev_b32_e32 v30, 15, v61
	v_or_b32_e32 v31, v31, v63
	v_lshrrev_b32_e32 v26, 15, v52
	v_or_b32_e32 v27, v27, v54
	v_or_b32_e32 v44, v44, v94
	v_or_b32_e32 v45, v45, v96
	v_or_b32_e32 v39, v39, v86
	v_or_b32_e32 v40, v40, v88
	v_or_b32_e32 v35, v35, v77
	v_or_b32_e32 v36, v36, v79
	v_bitop3_b32 v30, v30, 3, v61 bitop3:0xc8
	v_lshlrev_b32_e32 v31, 2, v31
	v_bitop3_b32 v26, v26, 3, v52 bitop3:0xc8
	v_lshlrev_b32_e32 v27, 2, v27
	v_lshlrev_b32_e32 v44, 4, v44
	v_lshlrev_b32_e32 v45, 6, v45
	v_lshlrev_b32_e32 v39, 4, v39
	v_lshlrev_b32_e32 v40, 6, v40
	v_lshlrev_b32_e32 v35, 4, v35
	v_lshlrev_b32_e32 v36, 6, v36
	v_and_or_b32 v30, v31, 12, v30
	v_lshrrev_b32_e32 v31, 15, v65
; __device__ __forceinline__ int red32(int v) {
;     v += __builtin_amdgcn_mov_dpp(v, 0xB1, 0xf, 0xf, true);
;     v += __builtin_amdgcn_mov_dpp(v, 0x4E, 0xf, 0xf, true);
;     v += __builtin_amdgcn_mov_dpp(v, 0x141, 0xf, 0xf, true);
;     v += __builtin_amdgcn_mov_dpp(v, 0x140, 0xf, 0xf, true);
;     v += __builtin_amdgcn_ds_swizzle(v, 0x401F);
;     return v;
; }
; __device__ __forceinline__ unsigned ltu(unsigned a, unsigned b) { unsigned d; asm volatile("v_sub_u32 %0, %1, %2\n\tv_lshrrev_b32 %0, 31, %0" : "=v"(d) : "v"(a), "v"(b)); return d; }
; __device__ __forceinline__ unsigned pk_flag_gt(unsigned k2, unsigned T2, unsigned one2) { unsigned t; asm volatile("v_pk_sub_u16 %0, %1, %2 clamp\n\tv_pk_min_u16 %0, %0, %3" : "=&v"(t) : "v"(k2), "v"(T2), "v"(one2)); return t; }
; __device__ __forceinline__ int scan32_incl(int x, int lane) {
;     x += __builtin_amdgcn_update_dpp(0, x, 0x111, 0xf, 0xf, true);
;     x += __builtin_amdgcn_update_dpp(0, x, 0x112, 0xf, 0xf, true);
;     x += __builtin_amdgcn_update_dpp(0, x, 0x114, 0xf, 0xf, true);
;     x += __builtin_amdgcn_update_dpp(0, x, 0x118, 0xf, 0xf, true);
;     const int r15 = __builtin_amdgcn_readlane(x, 15), r47 = __builtin_amdgcn_readlane(x, 47);
;     x += (lane & 16) ? ((lane & 32) ? r47 : r15) : 0;
;     return x;
; }
; template <int NCH>
; __device__ __forceinline__ void idx_select(const unsigned short* sc, unsigned* bits, size_t tok0, int tid) {
;     ...
;     for (int i = 0; i < NCH; ++i) { unsigned g8 = 0u, e8 = 0u;
; #pragma unroll
;         for (int w = 0; w < 4; ++w) { const unsigned g2 = pk_flag_gt(kw[4 * i + w], T2, one2), l2 = pk_flag_gt(T2, kw[4 * i + w], one2), e2 = one2 - g2 - l2;
;             g8 |= ((g2 | (g2 >> 15)) & 3u) << (2 * w); e8 |= ((e2 | (e2 >> 15)) & 3u) << (2 * w); }
;         gm[i] = g8; em[i] = e8; cgt += __builtin_popcount(g8); }
;     const int need = 256 - red32(cgt);
;     int carry = 0;
;     unsigned char* brow = (unsigned char*)(bits + (tok0 + row) * 128);
; #pragma unroll
;     for (int i = 0; i < NCH; ++i) { const int ec = __builtin_popcount(em[i]); const int incl = scan32_incl(ec, lane);
;         const int quota = need - carry - (incl - ec);
;         unsigned se = (quota >= ec) ? em[i] : 0u;
	v_lshrrev_b32_e32 v32, 15, v70
	v_and_or_b32 v26, v27, 12, v26
	v_pk_sub_u16 v56, v28, v0 clamp
	v_pk_min_u16 v56, v56, v235
	v_pk_sub_u16 v57, v0, v28 clamp
	v_pk_min_u16 v57, v57, v235
	v_pk_sub_u16 v58, v29, v0 clamp
	v_pk_min_u16 v58, v58, v235
	v_and_b32_e32 v44, 48, v44
	v_lshrrev_b32_e32 v27, 15, v56
	v_lshrrev_b32_e32 v28, 15, v58
	v_and_b32_e32 v45, 0xc0, v45
	v_and_b32_e32 v39, 48, v39
	v_and_b32_e32 v40, 0xc0, v40
	v_and_b32_e32 v35, 48, v35
	v_and_b32_e32 v36, 0xc0, v36
	v_or_b32_e32 v31, v31, v65
	v_or_b32_e32 v32, v32, v70
	v_or_b32_e32 v27, v27, v56
	v_or_b32_e32 v28, v28, v58
	v_bcnt_u32_b32 v42, v90, 0
	v_or3_b32 v81, v43, v44, v45
	v_or3_b32 v72, v38, v39, v40
	v_or3_b32 v60, v34, v35, v36
	v_lshlrev_b32_e32 v31, 4, v31
	v_lshlrev_b32_e32 v32, 6, v32
	v_lshlrev_b32_e32 v27, 4, v27
	v_lshlrev_b32_e32 v28, 6, v28
	v_bcnt_u32_b32 v42, v81, v42
	v_bcnt_u32_b32 v38, v72, 0
	v_bcnt_u32_b32 v34, v60, 0
	v_and_b32_e32 v31, 48, v31
	v_and_b32_e32 v32, 0xc0, v32
	v_and_b32_e32 v27, 48, v27
	v_and_b32_e32 v28, 0xc0, v28
	v_add3_u32 v34, v42, v38, v34
	v_or3_b32 v51, v30, v31, v32
	v_or3_b32 v42, v26, v27, v28
	v_bcnt_u32_b32 v30, v51, 0
	v_bcnt_u32_b32 v26, v42, 0
	v_pk_sub_u16 v59, v0, v29 clamp
	v_pk_min_u16 v59, v59, v235
	v_add3_u32 v26, v34, v30, v26
	v_pk_sub_u16 v43, v22, v0 clamp
	v_pk_min_u16 v43, v43, v235
	v_pk_sub_u16 v44, v0, v22 clamp
	v_pk_min_u16 v44, v44, v235
	v_pk_sub_u16 v45, v23, v0 clamp
	v_pk_min_u16 v45, v45, v235
	v_pk_sub_u16 v46, v0, v23 clamp
	v_pk_min_u16 v46, v46, v235
	v_pk_sub_u16 v47, v24, v0 clamp
	v_pk_min_u16 v47, v47, v235
	v_pk_sub_u16 v48, v0, v24 clamp
	v_pk_min_u16 v48, v48, v235
	v_pk_sub_u16 v49, v25, v0 clamp
	v_pk_min_u16 v49, v49, v235
	v_pk_sub_u16 v50, v0, v25 clamp
	v_pk_min_u16 v50, v50, v235
	s_nop 0
	v_lshrrev_b32_e32 v23, 15, v45
	v_pk_sub_u16 v33, v18, v0 clamp
	v_pk_min_u16 v33, v33, v235
	v_pk_sub_u16 v34, v0, v18 clamp
	v_pk_min_u16 v34, v34, v235
	v_pk_sub_u16 v35, v19, v0 clamp
	v_pk_min_u16 v35, v35, v235
	v_pk_sub_u16 v36, v0, v19 clamp
	v_pk_min_u16 v36, v36, v235
	v_lshrrev_b32_e32 v22, 15, v43
	v_lshrrev_b32_e32 v19, 15, v35
	v_or_b32_e32 v23, v23, v45
	v_lshrrev_b32_e32 v18, 15, v33
	v_or_b32_e32 v19, v19, v35
	v_bitop3_b32 v22, v22, 3, v43 bitop3:0xc8
	v_lshlrev_b32_e32 v23, 2, v23
	v_bitop3_b32 v18, v18, 3, v33 bitop3:0xc8
	v_lshlrev_b32_e32 v19, 2, v19
	v_and_or_b32 v22, v23, 12, v22
	v_lshrrev_b32_e32 v23, 15, v47
	v_lshrrev_b32_e32 v24, 15, v49
	v_and_or_b32 v18, v19, 12, v18
	v_pk_sub_u16 v37, v20, v0 clamp
	v_pk_min_u16 v37, v37, v235
	v_pk_sub_u16 v38, v0, v20 clamp
	v_pk_min_u16 v38, v38, v235
	v_pk_sub_u16 v39, v21, v0 clamp
	v_pk_min_u16 v39, v39, v235
	v_or_b32_e32 v23, v23, v47
	v_lshrrev_b32_e32 v19, 15, v37
	v_lshrrev_b32_e32 v20, 15, v39
	v_or_b32_e32 v24, v24, v49
	v_or_b32_e32 v19, v19, v37
	v_or_b32_e32 v20, v20, v39
	v_lshlrev_b32_e32 v23, 4, v23
	v_lshlrev_b32_e32 v24, 6, v24
	v_lshlrev_b32_e32 v19, 4, v19
	v_lshlrev_b32_e32 v20, 6, v20
	v_and_b32_e32 v23, 48, v23
	v_and_b32_e32 v24, 0xc0, v24
	v_and_b32_e32 v19, 48, v19
	v_and_b32_e32 v20, 0xc0, v20
	v_or3_b32 v32, v22, v23, v24
	v_or3_b32 v23, v18, v19, v20
	v_bcnt_u32_b32 v22, v32, 0
	v_bcnt_u32_b32 v18, v23, 0
	v_pk_sub_u16 v40, v0, v21 clamp
	v_pk_min_u16 v40, v40, v235
	v_add3_u32 v41, v26, v22, v18
	v_pk_sub_u16 v24, v14, v0 clamp
	v_pk_min_u16 v24, v24, v235
	v_pk_sub_u16 v25, v0, v14 clamp
	v_pk_min_u16 v25, v25, v235
	v_pk_sub_u16 v26, v15, v0 clamp
	v_pk_min_u16 v26, v26, v235
	v_pk_sub_u16 v27, v0, v15 clamp
	v_pk_min_u16 v27, v27, v235
	v_pk_sub_u16 v28, v16, v0 clamp
	v_pk_min_u16 v28, v28, v235
	v_pk_sub_u16 v29, v0, v16 clamp
	v_pk_min_u16 v29, v29, v235
	s_nop 0
	v_lshrrev_b32_e32 v14, 15, v24
	v_lshrrev_b32_e32 v15, 15, v26
	v_or_b32_e32 v15, v15, v26
	v_bitop3_b32 v14, v14, 3, v24 bitop3:0xc8
	v_lshlrev_b32_e32 v15, 2, v15
	v_and_or_b32 v14, v15, 12, v14
	v_lshrrev_b32_e32 v15, 15, v28
	v_pk_sub_u16 v30, v17, v0 clamp
	v_pk_min_u16 v30, v30, v235
	v_or_b32_e32 v15, v15, v28
	v_lshrrev_b32_e32 v16, 15, v30
	v_or_b32_e32 v16, v16, v30
	v_lshlrev_b32_e32 v15, 4, v15
	v_lshlrev_b32_e32 v16, 6, v16
	v_and_b32_e32 v15, 48, v15
	v_and_b32_e32 v16, 0xc0, v16
	v_pk_sub_u16 v31, v0, v17 clamp
	v_pk_min_u16 v31, v31, v235
	v_or3_b32 v14, v14, v15, v16
	v_pk_sub_u16 v15, v10, v0 clamp
	v_pk_min_u16 v15, v15, v235
	v_pk_sub_u16 v16, v0, v10 clamp
	v_pk_min_u16 v16, v16, v235
	v_pk_sub_u16 v17, v11, v0 clamp
	v_pk_min_u16 v17, v17, v235
	v_pk_sub_u16 v18, v0, v11 clamp
	v_pk_min_u16 v18, v18, v235
	v_pk_sub_u16 v19, v12, v0 clamp
	v_pk_min_u16 v19, v19, v235
	v_pk_sub_u16 v20, v0, v12 clamp
	v_pk_min_u16 v20, v20, v235
	s_nop 0
	v_lshrrev_b32_e32 v10, 15, v15
	v_lshrrev_b32_e32 v11, 15, v17
	v_or_b32_e32 v11, v11, v17
	v_bitop3_b32 v10, v10, 3, v15 bitop3:0xc8
	v_lshlrev_b32_e32 v11, 2, v11
	v_and_or_b32 v10, v11, 12, v10
	v_lshrrev_b32_e32 v11, 15, v19
	v_pk_sub_u16 v21, v13, v0 clamp
	v_pk_min_u16 v21, v21, v235
	v_pk_sub_u16 v22, v0, v13 clamp
	v_pk_min_u16 v22, v22, v235
	v_or_b32_e32 v11, v11, v19
	v_lshrrev_b32_e32 v0, 15, v21
	v_or_b32_e32 v0, v0, v21
	v_lshlrev_b32_e32 v11, 4, v11
	v_lshlrev_b32_e32 v0, 6, v0
	v_and_b32_e32 v11, 48, v11
	v_and_b32_e32 v0, 0xc0, v0
	v_or3_b32 v0, v10, v11, v0
	v_bcnt_u32_b32 v100, v14, 0
	v_bcnt_u32_b32 v10, v0, 0
	v_add3_u32 v10, v41, v100, v10
	v_and_b32_e32 v12, 16, v182
	v_cmp_eq_u32_e64 s[4:5], 0, v12
	v_add_u32_dpp v10, v10, v10 quad_perm:[1,0,3,2] row_mask:0xf bank_mask:0xf bound_ctrl:1
	v_bcnt_u32_b32 v12, v98, 0
	v_bfe_i32 v13, v182, 4, 1
	v_add_u32_dpp v10, v10, v10 quad_perm:[2,3,0,1] row_mask:0xf bank_mask:0xf bound_ctrl:1
	s_nop 1
	v_add_u32_dpp v10, v10, v10 row_half_mirror row_mask:0xf bank_mask:0xf bound_ctrl:1
	s_nop 1
	v_add_u32_dpp v10, v10, v10 row_mirror row_mask:0xf bank_mask:0xf bound_ctrl:1
	v_mov_b32_e32 v11, v10
	s_nop 1
	v_permlane16_swap_b32_e32 v11, v10
	s_waitcnt lgkmcnt(0)
	v_add_u32_e32 v41, v10, v11
	v_mov_b32_dpp v10, v12 row_shr:1 row_mask:0xf bank_mask:0xf bound_ctrl:1
	v_bcnt_u32_b32 v10, v98, v10
	s_nop 1
	v_add_u32_dpp v10, v10, v10 row_shr:2 row_mask:0xf bank_mask:0xf bound_ctrl:1
	s_nop 1
	v_add_u32_dpp v10, v10, v10 row_shr:4 row_mask:0xf bank_mask:0xf bound_ctrl:1
	s_nop 1
	v_add_u32_dpp v10, v10, v10 row_shr:8 row_mask:0xf bank_mask:0xf bound_ctrl:1
	s_nop 0
	v_readlane_b32 s0, v10, 15
	v_readlane_b32 s1, v10, 47
	s_nop 0
	v_mov_b32_e32 v100, s0
	v_mov_b32_e32 v11, s1
	v_cndmask_b32_e64 v11, v11, v100, s[6:7]
	v_and_b32_e32 v11, v13, v11
	v_add_u32_e32 v10, v11, v10
	v_or_b32_e32 v11, 0x100, v12
	v_add_u32_e32 v13, v41, v10
	v_sub_u32_e32 v11, v11, v13
	v_cmp_lt_i32_e64 s[0:1], v11, v12
	v_cmp_lt_i32_e64 s[10:11], 0, v11
	s_and_b64 vcc, s[10:11], s[0:1]
	v_cndmask_b32_e64 v12, v98, 0, s[0:1]
	s_cbranch_vccz .LBB0_581
; template <int NCH>
; __device__ __forceinline__ void idx_select(const unsigned short* sc, unsigned* bits, size_t tok0, int tid) {
;     ...
;         if (__any(quota > 0 && quota < ec)) { unsigned m = em[i], r = 0u;
; #pragma unroll
;             for (int t = 0; t < 8; ++t) { const unsigned b = m & (0u - m); if (t < quota) r |= b; m ^= b; }
;             if (quota > 0 && quota < ec) se = r; }
	v_sub_u32_e32 v13, 0, v98
	v_and_b32_e32 v99, v98, v13
	v_bitop3_b32 v13, v98, v98, v13 bitop3:0x6c
	v_sub_u32_e32 v101, 0, v13
	v_cndmask_b32_e64 v100, 0, v99, s[10:11]
	v_bitop3_b32 v102, v99, v101, v98 bitop3:0x48
	v_cmp_lt_i32_e32 vcc, 1, v11
	v_bitop3_b32 v99, v99, v98, v101 bitop3:0x14
	v_sub_u32_e32 v101, 0, v99
	v_cndmask_b32_e32 v103, 0, v102, vcc
	v_or_b32_e32 v100, v103, v100
	v_bitop3_b32 v103, v102, v101, v13 bitop3:0x48
	v_bitop3_b32 v13, v102, v13, v101 bitop3:0x14
	v_sub_u32_e32 v101, 0, v13
	v_bitop3_b32 v102, v103, v101, v99 bitop3:0x48
	v_bitop3_b32 v99, v103, v99, v101 bitop3:0x14
	v_cmp_lt_i32_e32 vcc, 2, v11
	v_sub_u32_e32 v101, 0, v99
	s_nop 0
	v_cndmask_b32_e32 v104, 0, v103, vcc
	v_bitop3_b32 v103, v102, v101, v13 bitop3:0x48
	v_bitop3_b32 v13, v102, v13, v101 bitop3:0x14
	v_cmp_lt_i32_e32 vcc, 3, v11
	v_sub_u32_e32 v101, 0, v13
	s_nop 0
	v_cndmask_b32_e32 v105, 0, v102, vcc
	v_bitop3_b32 v102, v103, v101, v99 bitop3:0x48
	v_bitop3_b32 v99, v103, v99, v101 bitop3:0x14
	v_cmp_lt_i32_e32 vcc, 4, v11
	v_sub_u32_e32 v101, 0, v99
	v_or3_b32 v100, v100, v104, v105
	v_cndmask_b32_e32 v104, 0, v103, vcc
	v_cmp_lt_i32_e32 vcc, 5, v11
	v_bitop3_b32 v103, v102, v101, v13 bitop3:0x48
	v_bitop3_b32 v13, v102, v13, v101 bitop3:0x14
	v_cndmask_b32_e32 v105, 0, v102, vcc
	v_cmp_lt_i32_e32 vcc, 6, v11
	v_sub_u32_e32 v13, 0, v13
	v_or3_b32 v100, v100, v104, v105
	v_cndmask_b32_e32 v104, 0, v103, vcc
	v_bitop3_b32 v13, v103, v13, v99 bitop3:0x48
	v_cmp_lt_i32_e32 vcc, 7, v11
	s_nop 1
	v_cndmask_b32_e32 v11, 0, v13, vcc
	v_or3_b32 v11, v100, v104, v11
	v_cndmask_b32_e64 v11, v98, v11, s[0:1]
	v_cndmask_b32_e64 v12, v12, v11, s[10:11]

; __device__ __forceinline__ void pk_cnt_lt(unsigned& acc, unsigned k2, unsigned mid2, unsigned one2) {
;     unsigned t; asm volatile("v_pk_sub_u16 %0, %2, %3 clamp\n\tv_pk_min_u16 %0, %0, %4\n\tv_pk_add_u16 %1, %1, %0" : "=&v"(t), "+v"(acc) : "v"(mid2), "v"(k2), "v"(one2));
; }
; __device__ __forceinline__ int red32(int v) {
;     v += __builtin_amdgcn_mov_dpp(v, 0xB1, 0xf, 0xf, true);
;     v += __builtin_amdgcn_mov_dpp(v, 0x4E, 0xf, 0xf, true);
;     v += __builtin_amdgcn_mov_dpp(v, 0x141, 0xf, 0xf, true);
;     v += __builtin_amdgcn_mov_dpp(v, 0x140, 0xf, 0xf, true);
;     v += __builtin_amdgcn_ds_swizzle(v, 0x401F);
;     return v;
; }
; template <int NCH>
; __device__ __forceinline__ void idx_select(const unsigned short* sc, unsigned* bits, size_t tok0, int tid) {
;     ...
; #pragma unroll 1
;     for (int it = 0; it < 16; ++it) { const unsigned mid = (lo + hi_ + 1u) >> 1, mid2 = mid | (mid << 16);
;         unsigned c2a = 0u, c2b = 0u;
; #pragma unroll
;         for (int i = 0; i < 4 * NCH; i += 2) { pk_cnt_lt(c2a, kw[i], mid2, one2); pk_cnt_lt(c2b, kw[i + 1], mid2, one2); }
;         int cnt = 8 * NCH - (int)((c2a & 0xFFFFu) + (c2a >> 16) + (c2b & 0xFFFFu) + (c2b >> 16));
;         cnt = red32(cnt);
;         if (cnt >= 256) lo = mid; else hi_ = mid - 1u;
;         if (cnt == 256) hi_ = mid;
;         if (__all(lo == hi_)) break; }
.LBB0_640:
	v_add3_u32 v36, v0, v35, 1
	v_lshrrev_b32_e32 v36, 1, v36
	v_mov_b32_e32 v38, 0
	v_lshl_or_b32 v37, v36, 16, v36
	s_waitcnt lgkmcnt(7)
	v_pk_sub_u16 v39, v37, v6 clamp
	v_pk_min_u16 v39, v39, v235
	v_pk_add_u16 v38, v38, v39
	s_nop 0
	v_mov_b32_e32 v39, 0
	v_pk_sub_u16 v40, v37, v7 clamp
	v_pk_min_u16 v40, v40, v235
	v_pk_add_u16 v39, v39, v40
	v_pk_sub_u16 v40, v37, v8 clamp
	v_pk_min_u16 v40, v40, v235
	v_pk_add_u16 v38, v38, v40
	v_pk_sub_u16 v40, v37, v9 clamp
	v_pk_min_u16 v40, v40, v235
	v_pk_add_u16 v39, v39, v40
	s_waitcnt lgkmcnt(6)
	v_pk_sub_u16 v40, v37, v2 clamp
	v_pk_min_u16 v40, v40, v235
	v_pk_add_u16 v38, v38, v40
	v_pk_sub_u16 v40, v37, v3 clamp
	v_pk_min_u16 v40, v40, v235
	v_pk_add_u16 v39, v39, v40
	v_pk_sub_u16 v40, v37, v4 clamp
	v_pk_min_u16 v40, v40, v235
	v_pk_add_u16 v38, v38, v40
	v_pk_sub_u16 v40, v37, v5 clamp
	v_pk_min_u16 v40, v40, v235
	v_pk_add_u16 v39, v39, v40
	s_waitcnt lgkmcnt(5)
	v_pk_sub_u16 v40, v37, v30 clamp
	v_pk_min_u16 v40, v40, v235
	v_pk_add_u16 v38, v38, v40
	v_pk_sub_u16 v40, v37, v31 clamp
	v_pk_min_u16 v40, v40, v235
	v_pk_add_u16 v39, v39, v40
	v_pk_sub_u16 v40, v37, v32 clamp
	v_pk_min_u16 v40, v40, v235
	v_pk_add_u16 v38, v38, v40
	v_pk_sub_u16 v40, v37, v33 clamp
	v_pk_min_u16 v40, v40, v235
	v_pk_add_u16 v39, v39, v40
	s_waitcnt lgkmcnt(4)
	v_pk_sub_u16 v40, v37, v26 clamp
	v_pk_min_u16 v40, v40, v235
	v_pk_add_u16 v38, v38, v40
	v_pk_sub_u16 v40, v37, v27 clamp
	v_pk_min_u16 v40, v40, v235
	v_pk_add_u16 v39, v39, v40
	v_pk_sub_u16 v40, v37, v28 clamp
	v_pk_min_u16 v40, v40, v235
	v_pk_add_u16 v38, v38, v40
	v_pk_sub_u16 v40, v37, v29 clamp
	v_pk_min_u16 v40, v40, v235
	v_pk_add_u16 v39, v39, v40
	s_waitcnt lgkmcnt(3)
	v_pk_sub_u16 v40, v37, v22 clamp
	v_pk_min_u16 v40, v40, v235
	v_pk_add_u16 v38, v38, v40
	v_pk_sub_u16 v40, v37, v23 clamp
	v_pk_min_u16 v40, v40, v235
	v_pk_add_u16 v39, v39, v40
	v_pk_sub_u16 v40, v37, v24 clamp
	v_pk_min_u16 v40, v40, v235
	v_pk_add_u16 v38, v38, v40
	v_pk_sub_u16 v40, v37, v25 clamp
	v_pk_min_u16 v40, v40, v235
	v_pk_add_u16 v39, v39, v40
	s_waitcnt lgkmcnt(2)
	v_pk_sub_u16 v40, v37, v18 clamp
	v_pk_min_u16 v40, v40, v235
	v_pk_add_u16 v38, v38, v40
	v_pk_sub_u16 v40, v37, v19 clamp
	v_pk_min_u16 v40, v40, v235
	v_pk_add_u16 v39, v39, v40
	v_pk_sub_u16 v40, v37, v20 clamp
	v_pk_min_u16 v40, v40, v235
	v_pk_add_u16 v38, v38, v40
	v_pk_sub_u16 v40, v37, v21 clamp
	v_pk_min_u16 v40, v40, v235
	v_pk_add_u16 v39, v39, v40
	s_waitcnt lgkmcnt(1)
	v_pk_sub_u16 v40, v37, v14 clamp
	v_pk_min_u16 v40, v40, v235
	v_pk_add_u16 v38, v38, v40
	v_pk_sub_u16 v40, v37, v15 clamp
	v_pk_min_u16 v40, v40, v235
	v_pk_add_u16 v39, v39, v40
	v_pk_sub_u16 v40, v37, v16 clamp
	v_pk_min_u16 v40, v40, v235
	v_pk_add_u16 v38, v38, v40
	v_pk_sub_u16 v40, v37, v17 clamp
	v_pk_min_u16 v40, v40, v235
	v_pk_add_u16 v39, v39, v40
	s_waitcnt lgkmcnt(0)
	v_pk_sub_u16 v40, v37, v10 clamp
	v_pk_min_u16 v40, v40, v235
	v_pk_add_u16 v38, v38, v40
	v_pk_sub_u16 v40, v37, v11 clamp
	v_pk_min_u16 v40, v40, v235
	v_pk_add_u16 v39, v39, v40
	v_pk_sub_u16 v40, v37, v12 clamp
	v_pk_min_u16 v40, v40, v235
	v_pk_add_u16 v38, v38, v40
	v_pk_sub_u16 v40, v37, v13 clamp
	v_pk_min_u16 v40, v40, v235
	v_pk_add_u16 v39, v39, v40
	v_add_u32_sdwa v38, v38, v38 dst_sel:DWORD dst_unused:UNUSED_PAD src0_sel:WORD_1 src1_sel:WORD_0
	v_and_b32_e32 v37, 0xffff, v39
	v_lshrrev_b32_e32 v39, 16, v39
	v_add3_u32 v37, v38, v37, v39
	v_sub_u32_e32 v37, 64, v37
	s_nop 1
	v_add_u32_dpp v37, v37, v37 quad_perm:[1,0,3,2] row_mask:0xf bank_mask:0xf bound_ctrl:1
	s_nop 1
	v_add_u32_dpp v37, v37, v37 quad_perm:[2,3,0,1] row_mask:0xf bank_mask:0xf bound_ctrl:1
	s_nop 1
	v_add_u32_dpp v37, v37, v37 row_half_mirror row_mask:0xf bank_mask:0xf bound_ctrl:1
	s_nop 1
	v_add_u32_dpp v37, v37, v37 row_mirror row_mask:0xf bank_mask:0xf bound_ctrl:1
	v_mov_b32_e32 v38, v37
	s_nop 1
	v_permlane16_swap_b32_e32 v38, v37
	s_waitcnt lgkmcnt(0)
	v_add_u32_e32 v37, v37, v38
	v_cmp_lt_i32_e32 vcc, s88, v37
	v_add_u32_e32 v38, -1, v36
	s_nop 0
	v_cndmask_b32_e32 v35, v38, v35, vcc
	v_cndmask_b32_e32 v0, v0, v36, vcc
	v_cmp_eq_u32_e32 vcc, s33, v37
	s_nop 1
	v_cndmask_b32_e32 v35, v35, v36, vcc
	v_cmp_eq_u32_e32 vcc, v0, v35
	s_cmp_eq_u64 vcc, exec
	s_cselect_b64 s[0:1], -1, 0
	v_subrev_co_u32_e32 v34, vcc, 1, v34
	s_or_b64 s[0:1], s[0:1], vcc
	s_andn2_b64 vcc, exec, s[0:1]
	s_cbranch_vccnz .LBB0_640
; __device__ __forceinline__ unsigned pk_flag_gt(unsigned k2, unsigned T2, unsigned one2) { unsigned t; asm volatile("v_pk_sub_u16 %0, %1, %2 clamp\n\tv_pk_min_u16 %0, %0, %3" : "=&v"(t) : "v"(k2), "v"(T2), "v"(one2)); return t; }
; template <int NCH>
; __device__ __forceinline__ void idx_select(const unsigned short* sc, unsigned* bits, size_t tok0, int tid) {
;     ...
;     const unsigned T = lo, T2 = T | (T << 16);
;     unsigned gm[NCH], em[NCH]; int cgt = 0;
; #pragma unroll
;     for (int i = 0; i < NCH; ++i) { unsigned g8 = 0u, e8 = 0u;
; #pragma unroll
;         for (int w = 0; w < 4; ++w) { const unsigned g2 = pk_flag_gt(kw[4 * i + w], T2, one2), l2 = pk_flag_gt(T2, kw[4 * i + w], one2), e2 = one2 - g2 - l2;
;             g8 |= ((g2 | (g2 >> 15)) & 3u) << (2 * w); e8 |= ((e2 | (e2 >> 15)) & 3u) << (2 * w); }
;         gm[i] = g8; em[i] = e8; cgt += __builtin_popcount(g8); }
	v_lshl_or_b32 v0, v0, 16, v0
	v_pk_sub_u16 v34, v6, v0 clamp
	v_pk_min_u16 v34, v34, v235
	v_pk_sub_u16 v35, v0, v6 clamp
	v_pk_min_u16 v35, v35, v235
	s_waitcnt vmcnt(0)
	v_and_b32_e32 v81, 32, v182
	v_add_u32_e32 v35, v34, v35
	v_sub_u32_e32 v35, 0x10001, v35
	v_lshrrev_b32_e32 v36, 15, v34
	v_bitop3_b32 v34, v36, 3, v34 bitop3:0xc8
	v_lshrrev_b32_e32 v36, 15, v35
	v_bitop3_b32 v35, v36, 3, v35 bitop3:0xc8
	v_pk_sub_u16 v36, v7, v0 clamp
	v_pk_min_u16 v36, v36, v235
	v_pk_sub_u16 v37, v0, v7 clamp
	v_pk_min_u16 v37, v37, v235
	v_cmp_eq_u32_e64 s[6:7], 0, v81
	v_lshrrev_b32_e32 v38, 15, v36
	v_add_u32_e32 v37, v36, v37
	v_or_b32_e32 v36, v38, v36
	v_sub_u32_e32 v37, 0x10001, v37
	v_lshlrev_b32_e32 v36, 2, v36
	v_and_or_b32 v34, v36, 12, v34
	v_lshrrev_b32_e32 v36, 15, v37
	v_or_b32_e32 v36, v36, v37
	v_lshlrev_b32_e32 v36, 2, v36
	v_and_or_b32 v35, v36, 12, v35
	v_pk_sub_u16 v36, v8, v0 clamp
	v_pk_min_u16 v36, v36, v235
	v_pk_sub_u16 v37, v0, v8 clamp
	v_pk_min_u16 v37, v37, v235
	v_cmp_ne_u32_e64 s[8:9], 0, v81
	v_add_u32_e32 v37, v36, v37
	v_sub_u32_e32 v37, 0x10001, v37
	v_lshrrev_b32_e32 v38, 15, v36
	v_or_b32_e32 v36, v38, v36
	v_lshrrev_b32_e32 v38, 15, v37
	v_or_b32_e32 v37, v38, v37
	v_pk_sub_u16 v38, v9, v0 clamp
	v_pk_min_u16 v38, v38, v235
	v_pk_sub_u16 v39, v0, v9 clamp
	v_pk_min_u16 v39, v39, v235
	v_lshlrev_b32_e32 v36, 4, v36
	v_lshrrev_b32_e32 v40, 15, v38
	v_add_u32_e32 v39, v38, v39
	v_or_b32_e32 v38, v40, v38
	v_lshlrev_b32_e32 v38, 6, v38
	v_and_b32_e32 v36, 48, v36
	v_sub_u32_e32 v39, 0x10001, v39
	v_and_b32_e32 v38, 0xc0, v38
	v_or3_b32 v72, v34, v36, v38
	v_lshrrev_b32_e32 v34, 15, v39
	v_or_b32_e32 v34, v34, v39
	v_lshlrev_b32_e32 v37, 4, v37
	v_lshlrev_b32_e32 v34, 6, v34
	v_and_b32_e32 v37, 48, v37
	v_and_b32_e32 v34, 0xc0, v34
	v_pk_sub_u16 v67, v2, v0 clamp
	v_pk_min_u16 v67, v67, v235
	v_pk_sub_u16 v73, v0, v2 clamp
	v_pk_min_u16 v73, v73, v235
	v_pk_sub_u16 v74, v3, v0 clamp
	v_pk_min_u16 v74, v74, v235
	v_pk_sub_u16 v75, v0, v3 clamp
	v_pk_min_u16 v75, v75, v235
	v_pk_sub_u16 v76, v4, v0 clamp
	v_pk_min_u16 v76, v76, v235
	v_pk_sub_u16 v77, v0, v4 clamp
	v_pk_min_u16 v77, v77, v235
	v_pk_sub_u16 v78, v5, v0 clamp
	v_pk_min_u16 v78, v78, v235
	v_pk_sub_u16 v79, v0, v5 clamp
	v_pk_min_u16 v79, v79, v235
	s_nop 0
	v_lshrrev_b32_e32 v36, 15, v74
	v_pk_sub_u16 v61, v30, v0 clamp
	v_pk_min_u16 v61, v61, v235
	v_pk_sub_u16 v62, v0, v30 clamp
	v_pk_min_u16 v62, v62, v235
	v_pk_sub_u16 v63, v31, v0 clamp
	v_pk_min_u16 v63, v63, v235
	v_pk_sub_u16 v64, v0, v31 clamp
	v_pk_min_u16 v64, v64, v235
	v_pk_sub_u16 v65, v32, v0 clamp
	v_pk_min_u16 v65, v65, v235
	v_pk_sub_u16 v69, v0, v32 clamp
	v_pk_min_u16 v69, v69, v235
	v_pk_sub_u16 v70, v33, v0 clamp
	v_pk_min_u16 v70, v70, v235
	v_pk_sub_u16 v71, v0, v33 clamp
	v_pk_min_u16 v71, v71, v235
	s_nop 0
	v_lshrrev_b32_e32 v31, 15, v63
	v_pk_sub_u16 v52, v26, v0 clamp
	v_pk_min_u16 v52, v52, v235
	v_pk_sub_u16 v53, v0, v26 clamp
	v_pk_min_u16 v53, v53, v235
	v_pk_sub_u16 v54, v27, v0 clamp
	v_pk_min_u16 v54, v54, v235
	v_pk_sub_u16 v55, v0, v27 clamp
	v_pk_min_u16 v55, v55, v235
	v_or3_b32 v80, v35, v37, v34
	v_lshrrev_b32_e32 v27, 15, v54
	v_lshrrev_b32_e32 v35, 15, v67
	v_or_b32_e32 v36, v36, v74
	v_lshrrev_b32_e32 v30, 15, v61
	v_or_b32_e32 v31, v31, v63
	v_lshrrev_b32_e32 v26, 15, v52
	v_or_b32_e32 v27, v27, v54
	v_bitop3_b32 v35, v35, 3, v67 bitop3:0xc8
	v_lshlrev_b32_e32 v36, 2, v36
	v_bitop3_b32 v30, v30, 3, v61 bitop3:0xc8
	v_lshlrev_b32_e32 v31, 2, v31
	v_bitop3_b32 v26, v26, 3, v52 bitop3:0xc8
	v_lshlrev_b32_e32 v27, 2, v27
	v_and_or_b32 v35, v36, 12, v35
	v_lshrrev_b32_e32 v36, 15, v76
	v_lshrrev_b32_e32 v37, 15, v78
	v_and_or_b32 v30, v31, 12, v30
	v_lshrrev_b32_e32 v31, 15, v65
	v_lshrrev_b32_e32 v32, 15, v70
	v_and_or_b32 v26, v27, 12, v26
	v_pk_sub_u16 v56, v28, v0 clamp
	v_pk_min_u16 v56, v56, v235
	v_pk_sub_u16 v57, v0, v28 clamp
	v_pk_min_u16 v57, v57, v235
	v_pk_sub_u16 v58, v29, v0 clamp
	v_pk_min_u16 v58, v58, v235
	v_or_b32_e32 v36, v36, v76
	v_lshrrev_b32_e32 v27, 15, v56
	v_lshrrev_b32_e32 v28, 15, v58
	v_or_b32_e32 v37, v37, v78
	v_or_b32_e32 v31, v31, v65
	v_or_b32_e32 v32, v32, v70
	v_or_b32_e32 v27, v27, v56
	v_or_b32_e32 v28, v28, v58
	v_lshlrev_b32_e32 v36, 4, v36
	v_lshlrev_b32_e32 v37, 6, v37
	v_lshlrev_b32_e32 v31, 4, v31
	v_lshlrev_b32_e32 v32, 6, v32
	v_lshlrev_b32_e32 v27, 4, v27
	v_lshlrev_b32_e32 v28, 6, v28
	v_and_b32_e32 v36, 48, v36
	v_and_b32_e32 v37, 0xc0, v37
	v_and_b32_e32 v31, 48, v31
	v_and_b32_e32 v32, 0xc0, v32
	v_and_b32_e32 v27, 48, v27
	v_and_b32_e32 v28, 0xc0, v28
	v_bcnt_u32_b32 v34, v72, 0
	v_or3_b32 v60, v35, v36, v37
	v_or3_b32 v51, v30, v31, v32
	v_or3_b32 v42, v26, v27, v28
	v_bcnt_u32_b32 v34, v60, v34
	v_bcnt_u32_b32 v30, v51, 0
	v_bcnt_u32_b32 v26, v42, 0
	v_pk_sub_u16 v59, v0, v29 clamp
	v_pk_min_u16 v59, v59, v235
	v_add3_u32 v26, v34, v30, v26
	v_pk_sub_u16 v43, v22, v0 clamp
	v_pk_min_u16 v43, v43, v235
	v_pk_sub_u16 v44, v0, v22 clamp
	v_pk_min_u16 v44, v44, v235
	v_pk_sub_u16 v45, v23, v0 clamp
	v_pk_min_u16 v45, v45, v235
	v_pk_sub_u16 v46, v0, v23 clamp
	v_pk_min_u16 v46, v46, v235
	v_pk_sub_u16 v47, v24, v0 clamp
	v_pk_min_u16 v47, v47, v235
	v_pk_sub_u16 v48, v0, v24 clamp
	v_pk_min_u16 v48, v48, v235
	v_pk_sub_u16 v49, v25, v0 clamp
	v_pk_min_u16 v49, v49, v235
	v_pk_sub_u16 v50, v0, v25 clamp
	v_pk_min_u16 v50, v50, v235
	s_nop 0
	v_lshrrev_b32_e32 v23, 15, v45
	v_pk_sub_u16 v33, v18, v0 clamp
	v_pk_min_u16 v33, v33, v235
	v_pk_sub_u16 v34, v0, v18 clamp
	v_pk_min_u16 v34, v34, v235
	v_pk_sub_u16 v35, v19, v0 clamp
	v_pk_min_u16 v35, v35, v235
	v_pk_sub_u16 v36, v0, v19 clamp
	v_pk_min_u16 v36, v36, v235
; __device__ __forceinline__ int red32(int v) {
;     v += __builtin_amdgcn_mov_dpp(v, 0xB1, 0xf, 0xf, true);
;     v += __builtin_amdgcn_mov_dpp(v, 0x4E, 0xf, 0xf, true);
;     v += __builtin_amdgcn_mov_dpp(v, 0x141, 0xf, 0xf, true);
;     v += __builtin_amdgcn_mov_dpp(v, 0x140, 0xf, 0xf, true);
;     v += __builtin_amdgcn_ds_swizzle(v, 0x401F);
;     return v;
; }
; __device__ __forceinline__ unsigned ltu(unsigned a, unsigned b) { unsigned d; asm volatile("v_sub_u32 %0, %1, %2\n\tv_lshrrev_b32 %0, 31, %0" : "=v"(d) : "v"(a), "v"(b)); return d; }
; __device__ __forceinline__ unsigned pk_flag_gt(unsigned k2, unsigned T2, unsigned one2) { unsigned t; asm volatile("v_pk_sub_u16 %0, %1, %2 clamp\n\tv_pk_min_u16 %0, %0, %3" : "=&v"(t) : "v"(k2), "v"(T2), "v"(one2)); return t; }
; __device__ __forceinline__ int scan32_incl(int x, int lane) {
;     x += __builtin_amdgcn_update_dpp(0, x, 0x111, 0xf, 0xf, true);
;     x += __builtin_amdgcn_update_dpp(0, x, 0x112, 0xf, 0xf, true);
; template <int NCH>
; __device__ __forceinline__ void idx_select(const unsigned short* sc, unsigned* bits, size_t tok0, int tid) {
;     ...
;     for (int i = 0; i < NCH; ++i) { unsigned g8 = 0u, e8 = 0u;
; #pragma unroll
;         for (int w = 0; w < 4; ++w) { const unsigned g2 = pk_flag_gt(kw[4 * i + w], T2, one2), l2 = pk_flag_gt(T2, kw[4 * i + w], one2), e2 = one2 - g2 - l2;
;             g8 |= ((g2 | (g2 >> 15)) & 3u) << (2 * w); e8 |= ((e2 | (e2 >> 15)) & 3u) << (2 * w); }
;         gm[i] = g8; em[i] = e8; cgt += __builtin_popcount(g8); }
;     const int need = 256 - red32(cgt);
;     int carry = 0;
;     unsigned char* brow = (unsigned char*)(bits + (tok0 + row) * 128);
; #pragma unroll
;     for (int i = 0; i < NCH; ++i) { const int ec = __builtin_popcount(em[i]); const int incl = scan32_incl(ec, lane);
;         const int quota = need - carry - (incl - ec);
;         unsigned se = (quota >= ec) ? em[i] : 0u;
;         if (__any(quota > 0 && quota < ec)) { unsigned m = em[i], r = 0u;
; #pragma unroll
;             for (int t = 0; t < 8; ++t) { const unsigned b = m & (0u - m); if (t < quota) r |= b; m ^= b; }
;             if (quota > 0 && quota < ec) se = r; }
;         carry += (lane & 32) ? __builtin_amdgcn_readlane(incl, 63) : __builtin_amdgcn_readlane(incl, 31);
;         brow[i * 32 + j] = (unsigned char)(gm[i] | se); }
	v_lshrrev_b32_e32 v22, 15, v43
	v_lshrrev_b32_e32 v19, 15, v35
	v_or_b32_e32 v23, v23, v45
	v_lshrrev_b32_e32 v18, 15, v33
	v_or_b32_e32 v19, v19, v35
	v_bitop3_b32 v22, v22, 3, v43 bitop3:0xc8
	v_lshlrev_b32_e32 v23, 2, v23
	v_bitop3_b32 v18, v18, 3, v33 bitop3:0xc8
	v_lshlrev_b32_e32 v19, 2, v19
	v_and_or_b32 v22, v23, 12, v22
	v_lshrrev_b32_e32 v23, 15, v47
	v_lshrrev_b32_e32 v24, 15, v49
	v_and_or_b32 v18, v19, 12, v18
	v_pk_sub_u16 v37, v20, v0 clamp
	v_pk_min_u16 v37, v37, v235
	v_pk_sub_u16 v38, v0, v20 clamp
	v_pk_min_u16 v38, v38, v235
	v_pk_sub_u16 v39, v21, v0 clamp
	v_pk_min_u16 v39, v39, v235
	v_or_b32_e32 v23, v23, v47
	v_lshrrev_b32_e32 v19, 15, v37
	v_lshrrev_b32_e32 v20, 15, v39
	v_or_b32_e32 v24, v24, v49
	v_or_b32_e32 v19, v19, v37
	v_or_b32_e32 v20, v20, v39
	v_lshlrev_b32_e32 v23, 4, v23
	v_lshlrev_b32_e32 v24, 6, v24
	v_lshlrev_b32_e32 v19, 4, v19
	v_lshlrev_b32_e32 v20, 6, v20
	v_and_b32_e32 v23, 48, v23
	v_and_b32_e32 v24, 0xc0, v24
	v_and_b32_e32 v19, 48, v19
	v_and_b32_e32 v20, 0xc0, v20
	v_or3_b32 v32, v22, v23, v24
	v_or3_b32 v23, v18, v19, v20
	v_bcnt_u32_b32 v22, v32, 0
	v_bcnt_u32_b32 v18, v23, 0
	v_pk_sub_u16 v40, v0, v21 clamp
	v_pk_min_u16 v40, v40, v235
	v_add3_u32 v41, v26, v22, v18
	v_pk_sub_u16 v24, v14, v0 clamp
	v_pk_min_u16 v24, v24, v235
	v_pk_sub_u16 v25, v0, v14 clamp
	v_pk_min_u16 v25, v25, v235
	v_pk_sub_u16 v26, v15, v0 clamp
	v_pk_min_u16 v26, v26, v235
	v_pk_sub_u16 v27, v0, v15 clamp
	v_pk_min_u16 v27, v27, v235
	v_pk_sub_u16 v28, v16, v0 clamp
	v_pk_min_u16 v28, v28, v235
	v_pk_sub_u16 v29, v0, v16 clamp
	v_pk_min_u16 v29, v29, v235
	s_nop 0
	v_lshrrev_b32_e32 v14, 15, v24
	v_lshrrev_b32_e32 v15, 15, v26
	v_or_b32_e32 v15, v15, v26
	v_bitop3_b32 v14, v14, 3, v24 bitop3:0xc8
	v_lshlrev_b32_e32 v15, 2, v15
	v_and_or_b32 v14, v15, 12, v14
	v_lshrrev_b32_e32 v15, 15, v28
	v_pk_sub_u16 v30, v17, v0 clamp
	v_pk_min_u16 v30, v30, v235
	v_or_b32_e32 v15, v15, v28
	v_lshrrev_b32_e32 v16, 15, v30
	v_or_b32_e32 v16, v16, v30
	v_lshlrev_b32_e32 v15, 4, v15
	v_lshlrev_b32_e32 v16, 6, v16
	v_and_b32_e32 v15, 48, v15
	v_and_b32_e32 v16, 0xc0, v16
	v_pk_sub_u16 v31, v0, v17 clamp
	v_pk_min_u16 v31, v31, v235
	v_or3_b32 v14, v14, v15, v16
	v_pk_sub_u16 v15, v10, v0 clamp
	v_pk_min_u16 v15, v15, v235
	v_pk_sub_u16 v16, v0, v10 clamp
	v_pk_min_u16 v16, v16, v235
	v_pk_sub_u16 v17, v11, v0 clamp
	v_pk_min_u16 v17, v17, v235
	v_pk_sub_u16 v18, v0, v11 clamp
	v_pk_min_u16 v18, v18, v235
	v_pk_sub_u16 v19, v12, v0 clamp
	v_pk_min_u16 v19, v19, v235
	v_pk_sub_u16 v20, v0, v12 clamp
	v_pk_min_u16 v20, v20, v235
	s_nop 0
	v_lshrrev_b32_e32 v10, 15, v15
	v_lshrrev_b32_e32 v11, 15, v17
	v_or_b32_e32 v11, v11, v17
	v_bitop3_b32 v10, v10, 3, v15 bitop3:0xc8
	v_lshlrev_b32_e32 v11, 2, v11
	v_and_or_b32 v10, v11, 12, v10
	v_lshrrev_b32_e32 v11, 15, v19
	v_pk_sub_u16 v21, v13, v0 clamp
	v_pk_min_u16 v21, v21, v235
	v_pk_sub_u16 v22, v0, v13 clamp
	v_pk_min_u16 v22, v22, v235
	v_or_b32_e32 v11, v11, v19
	v_lshrrev_b32_e32 v0, 15, v21
	v_or_b32_e32 v0, v0, v21
	v_lshlrev_b32_e32 v11, 4, v11
	v_lshlrev_b32_e32 v0, 6, v0
	v_and_b32_e32 v11, 48, v11
	v_and_b32_e32 v0, 0xc0, v0
	v_or3_b32 v0, v10, v11, v0
	v_bcnt_u32_b32 v82, v14, 0
	v_bcnt_u32_b32 v10, v0, 0
	v_add3_u32 v10, v41, v82, v10
	v_and_b32_e32 v12, 16, v182
	v_cmp_eq_u32_e64 s[4:5], 0, v12
	v_add_u32_dpp v10, v10, v10 quad_perm:[1,0,3,2] row_mask:0xf bank_mask:0xf bound_ctrl:1
	v_bcnt_u32_b32 v12, v80, 0
	v_bfe_i32 v13, v182, 4, 1
	v_add_u32_dpp v10, v10, v10 quad_perm:[2,3,0,1] row_mask:0xf bank_mask:0xf bound_ctrl:1
	s_nop 1
	v_add_u32_dpp v10, v10, v10 row_half_mirror row_mask:0xf bank_mask:0xf bound_ctrl:1
	s_nop 1
	v_add_u32_dpp v10, v10, v10 row_mirror row_mask:0xf bank_mask:0xf bound_ctrl:1
	v_mov_b32_e32 v11, v10
	s_nop 1
	v_permlane16_swap_b32_e32 v11, v10
	s_waitcnt lgkmcnt(0)
	v_add_u32_e32 v41, v10, v11
	v_mov_b32_dpp v10, v12 row_shr:1 row_mask:0xf bank_mask:0xf bound_ctrl:1
	v_bcnt_u32_b32 v10, v80, v10
	s_nop 1
	v_add_u32_dpp v10, v10, v10 row_shr:2 row_mask:0xf bank_mask:0xf bound_ctrl:1
	s_nop 1
	v_add_u32_dpp v10, v10, v10 row_shr:4 row_mask:0xf bank_mask:0xf bound_ctrl:1
	s_nop 1
	v_add_u32_dpp v10, v10, v10 row_shr:8 row_mask:0xf bank_mask:0xf bound_ctrl:1
	s_nop 0
	v_readlane_b32 s0, v10, 15
	v_readlane_b32 s1, v10, 47
	s_nop 0
	v_mov_b32_e32 v82, s0
	v_mov_b32_e32 v11, s1
	v_cndmask_b32_e64 v11, v11, v82, s[6:7]
	v_and_b32_e32 v11, v13, v11
	v_add_u32_e32 v10, v11, v10
	v_or_b32_e32 v11, 0x100, v12
	v_add_u32_e32 v13, v41, v10
	v_sub_u32_e32 v11, v11, v13
	v_cmp_lt_i32_e64 s[0:1], v11, v12
	v_cmp_lt_i32_e64 s[10:11], 0, v11
	s_and_b64 vcc, s[10:11], s[0:1]
	v_cndmask_b32_e64 v12, v80, 0, s[0:1]
	s_cbranch_vccz .LBB0_643
	v_sub_u32_e32 v13, 0, v80
	v_and_b32_e32 v81, v80, v13
	v_bitop3_b32 v13, v80, v80, v13 bitop3:0x6c
	v_sub_u32_e32 v83, 0, v13
	v_cndmask_b32_e64 v82, 0, v81, s[10:11]
	v_bitop3_b32 v84, v81, v83, v80 bitop3:0x48
	v_cmp_lt_i32_e32 vcc, 1, v11
	v_bitop3_b32 v81, v81, v80, v83 bitop3:0x14
	v_sub_u32_e32 v83, 0, v81
	v_cndmask_b32_e32 v85, 0, v84, vcc
	v_or_b32_e32 v82, v85, v82
	v_bitop3_b32 v85, v84, v83, v13 bitop3:0x48
	v_bitop3_b32 v13, v84, v13, v83 bitop3:0x14
	v_sub_u32_e32 v83, 0, v13
	v_bitop3_b32 v84, v85, v83, v81 bitop3:0x48
	v_bitop3_b32 v81, v85, v81, v83 bitop3:0x14
	v_cmp_lt_i32_e32 vcc, 2, v11
	v_sub_u32_e32 v83, 0, v81
	s_nop 0
	v_cndmask_b32_e32 v86, 0, v85, vcc
	v_bitop3_b32 v85, v84, v83, v13 bitop3:0x48
	v_bitop3_b32 v13, v84, v13, v83 bitop3:0x14
	v_cmp_lt_i32_e32 vcc, 3, v11
	v_sub_u32_e32 v83, 0, v13
	s_nop 0
	v_cndmask_b32_e32 v87, 0, v84, vcc
	v_bitop3_b32 v84, v85, v83, v81 bitop3:0x48
	v_bitop3_b32 v81, v85, v81, v83 bitop3:0x14
	v_cmp_lt_i32_e32 vcc, 4, v11
	v_sub_u32_e32 v83, 0, v81
	v_or3_b32 v82, v82, v86, v87
	v_cndmask_b32_e32 v86, 0, v85, vcc
	v_cmp_lt_i32_e32 vcc, 5, v11
	v_bitop3_b32 v85, v84, v83, v13 bitop3:0x48
	v_bitop3_b32 v13, v84, v13, v83 bitop3:0x14
	v_cndmask_b32_e32 v87, 0, v84, vcc
	v_cmp_lt_i32_e32 vcc, 6, v11
	v_sub_u32_e32 v13, 0, v13
	v_or3_b32 v82, v82, v86, v87
	v_cndmask_b32_e32 v86, 0, v85, vcc
	v_bitop3_b32 v13, v85, v13, v81 bitop3:0x48
	v_cmp_lt_i32_e32 vcc, 7, v11
	s_nop 1
	v_cndmask_b32_e32 v11, 0, v13, vcc
	v_or3_b32 v11, v82, v86, v11
	v_cndmask_b32_e64 v11, v80, v11, s[0:1]
	v_cndmask_b32_e64 v12, v12, v11, s[10:11]

; __device__ __forceinline__ unsigned pk_flag_gt(unsigned k2, unsigned T2, unsigned one2) { unsigned t; asm volatile("v_pk_sub_u16 %0, %1, %2 clamp\n\tv_pk_min_u16 %0, %0, %3" : "=&v"(t) : "v"(k2), "v"(T2), "v"(one2)); return t; }
; __device__ __forceinline__ void pk_cnt_lt(unsigned& acc, unsigned k2, unsigned mid2, unsigned one2) {
;     unsigned t; asm volatile("v_pk_sub_u16 %0, %2, %3 clamp\n\tv_pk_min_u16 %0, %0, %4\n\tv_pk_add_u16 %1, %1, %0" : "=&v"(t), "+v"(acc) : "v"(mid2), "v"(k2), "v"(one2));
; }
; __device__ __forceinline__ int red32(int v) {
;     v += __builtin_amdgcn_mov_dpp(v, 0xB1, 0xf, 0xf, true);
;     v += __builtin_amdgcn_mov_dpp(v, 0x4E, 0xf, 0xf, true);
;     v += __builtin_amdgcn_mov_dpp(v, 0x141, 0xf, 0xf, true);
;     v += __builtin_amdgcn_mov_dpp(v, 0x140, 0xf, 0xf, true);
;     v += __builtin_amdgcn_ds_swizzle(v, 0x401F);
;     return v;
; }
; template <int NCH>
; __device__ __forceinline__ void idx_select(const unsigned short* sc, unsigned* bits, size_t tok0, int tid) {
;     ...
; #pragma unroll 1
;     for (int it = 0; it < 16; ++it) { const unsigned mid = (lo + hi_ + 1u) >> 1, mid2 = mid | (mid << 16);
;         unsigned c2a = 0u, c2b = 0u;
; #pragma unroll
;         for (int i = 0; i < 4 * NCH; i += 2) { pk_cnt_lt(c2a, kw[i], mid2, one2); pk_cnt_lt(c2b, kw[i + 1], mid2, one2); }
;         int cnt = 8 * NCH - (int)((c2a & 0xFFFFu) + (c2a >> 16) + (c2b & 0xFFFFu) + (c2b >> 16));
;         cnt = red32(cnt);
;         if (cnt >= 256) lo = mid; else hi_ = mid - 1u;
;         if (cnt == 256) hi_ = mid;
;         if (__all(lo == hi_)) break; }
;     const unsigned T = lo, T2 = T | (T << 16);
;     unsigned gm[NCH], em[NCH]; int cgt = 0;
; #pragma unroll
;     for (int i = 0; i < NCH; ++i) { unsigned g8 = 0u, e8 = 0u;
; #pragma unroll
;         for (int w = 0; w < 4; ++w) { const unsigned g2 = pk_flag_gt(kw[4 * i + w], T2, one2), l2 = pk_flag_gt(T2, kw[4 * i + w], one2), e2 = one2 - g2 - l2;
;             g8 |= ((g2 | (g2 >> 15)) & 3u) << (2 * w); e8 |= ((e2 | (e2 >> 15)) & 3u) << (2 * w); }
;         gm[i] = g8; em[i] = e8; cgt += __builtin_popcount(g8); }
.LBB0_691:
	v_add3_u32 v28, v0, v27, 1
	v_lshrrev_b32_e32 v28, 1, v28
	v_mov_b32_e32 v30, 0
	v_lshl_or_b32 v29, v28, 16, v28
	s_waitcnt lgkmcnt(5)
	v_pk_sub_u16 v31, v29, v6 clamp
	v_pk_min_u16 v31, v31, v235
	v_pk_add_u16 v30, v30, v31
	s_nop 0
	v_mov_b32_e32 v31, 0
	v_pk_sub_u16 v32, v29, v7 clamp
	v_pk_min_u16 v32, v32, v235
	v_pk_add_u16 v31, v31, v32
	v_pk_sub_u16 v32, v29, v8 clamp
	v_pk_min_u16 v32, v32, v235
	v_pk_add_u16 v30, v30, v32
	v_pk_sub_u16 v32, v29, v9 clamp
	v_pk_min_u16 v32, v32, v235
	v_pk_add_u16 v31, v31, v32
	s_waitcnt lgkmcnt(4)
	v_pk_sub_u16 v32, v29, v2 clamp
	v_pk_min_u16 v32, v32, v235
	v_pk_add_u16 v30, v30, v32
	v_pk_sub_u16 v32, v29, v3 clamp
	v_pk_min_u16 v32, v32, v235
	v_pk_add_u16 v31, v31, v32
	v_pk_sub_u16 v32, v29, v4 clamp
	v_pk_min_u16 v32, v32, v235
	v_pk_add_u16 v30, v30, v32
	v_pk_sub_u16 v32, v29, v5 clamp
	v_pk_min_u16 v32, v32, v235
	v_pk_add_u16 v31, v31, v32
	s_waitcnt lgkmcnt(3)
	v_pk_sub_u16 v32, v29, v22 clamp
	v_pk_min_u16 v32, v32, v235
	v_pk_add_u16 v30, v30, v32
	v_pk_sub_u16 v32, v29, v23 clamp
	v_pk_min_u16 v32, v32, v235
	v_pk_add_u16 v31, v31, v32
	v_pk_sub_u16 v32, v29, v24 clamp
	v_pk_min_u16 v32, v32, v235
	v_pk_add_u16 v30, v30, v32
	v_pk_sub_u16 v32, v29, v25 clamp
	v_pk_min_u16 v32, v32, v235
	v_pk_add_u16 v31, v31, v32
	s_waitcnt lgkmcnt(2)
	v_pk_sub_u16 v32, v29, v18 clamp
	v_pk_min_u16 v32, v32, v235
	v_pk_add_u16 v30, v30, v32
	v_pk_sub_u16 v32, v29, v19 clamp
	v_pk_min_u16 v32, v32, v235
	v_pk_add_u16 v31, v31, v32
	v_pk_sub_u16 v32, v29, v20 clamp
	v_pk_min_u16 v32, v32, v235
	v_pk_add_u16 v30, v30, v32
	v_pk_sub_u16 v32, v29, v21 clamp
	v_pk_min_u16 v32, v32, v235
	v_pk_add_u16 v31, v31, v32
	s_waitcnt lgkmcnt(1)
	v_pk_sub_u16 v32, v29, v14 clamp
	v_pk_min_u16 v32, v32, v235
	v_pk_add_u16 v30, v30, v32
	v_pk_sub_u16 v32, v29, v15 clamp
	v_pk_min_u16 v32, v32, v235
	v_pk_add_u16 v31, v31, v32
	v_pk_sub_u16 v32, v29, v16 clamp
	v_pk_min_u16 v32, v32, v235
	v_pk_add_u16 v30, v30, v32
	v_pk_sub_u16 v32, v29, v17 clamp
	v_pk_min_u16 v32, v32, v235
	v_pk_add_u16 v31, v31, v32
	s_waitcnt lgkmcnt(0)
	v_pk_sub_u16 v32, v29, v10 clamp
	v_pk_min_u16 v32, v32, v235
	v_pk_add_u16 v30, v30, v32
	v_pk_sub_u16 v32, v29, v11 clamp
	v_pk_min_u16 v32, v32, v235
	v_pk_add_u16 v31, v31, v32
	v_pk_sub_u16 v32, v29, v12 clamp
	v_pk_min_u16 v32, v32, v235
	v_pk_add_u16 v30, v30, v32
	v_pk_sub_u16 v32, v29, v13 clamp
	v_pk_min_u16 v32, v32, v235
	v_pk_add_u16 v31, v31, v32
	v_add_u32_sdwa v30, v30, v30 dst_sel:DWORD dst_unused:UNUSED_PAD src0_sel:WORD_1 src1_sel:WORD_0
	v_and_b32_e32 v29, 0xffff, v31
	v_lshrrev_b32_e32 v31, 16, v31
	v_add3_u32 v29, v30, v29, v31
	v_sub_u32_e32 v29, 48, v29
	s_nop 1
	v_add_u32_dpp v29, v29, v29 quad_perm:[1,0,3,2] row_mask:0xf bank_mask:0xf bound_ctrl:1
	s_nop 1
	v_add_u32_dpp v29, v29, v29 quad_perm:[2,3,0,1] row_mask:0xf bank_mask:0xf bound_ctrl:1
	s_nop 1
	v_add_u32_dpp v29, v29, v29 row_half_mirror row_mask:0xf bank_mask:0xf bound_ctrl:1
	s_nop 1
	v_add_u32_dpp v29, v29, v29 row_mirror row_mask:0xf bank_mask:0xf bound_ctrl:1
	v_mov_b32_e32 v30, v29
	s_nop 1
	v_permlane16_swap_b32_e32 v30, v29
	s_waitcnt lgkmcnt(0)
	v_add_u32_e32 v29, v29, v30
	v_cmp_lt_i32_e32 vcc, s88, v29
	v_add_u32_e32 v30, -1, v28
	s_nop 0
	v_cndmask_b32_e32 v27, v30, v27, vcc
	v_cndmask_b32_e32 v0, v0, v28, vcc
	v_cmp_eq_u32_e32 vcc, s33, v29
	s_nop 1
	v_cndmask_b32_e32 v27, v27, v28, vcc
	v_cmp_eq_u32_e32 vcc, v0, v27
	s_cmp_eq_u64 vcc, exec
	s_cselect_b64 s[0:1], -1, 0
	v_subrev_co_u32_e32 v26, vcc, 1, v26
	s_or_b64 s[0:1], s[0:1], vcc
	s_andn2_b64 vcc, exec, s[0:1]
	s_cbranch_vccnz .LBB0_691
	v_lshl_or_b32 v0, v0, 16, v0
	v_pk_sub_u16 v26, v6, v0 clamp
	v_pk_min_u16 v26, v26, v235
	v_pk_sub_u16 v27, v0, v6 clamp
	v_pk_min_u16 v27, v27, v235
	v_and_b32_e32 v61, 32, v182
	v_add_u32_e32 v27, v26, v27
	v_sub_u32_e32 v27, 0x10001, v27
	v_lshrrev_b32_e32 v28, 15, v26
	v_bitop3_b32 v26, v28, 3, v26 bitop3:0xc8
	v_lshrrev_b32_e32 v28, 15, v27
	v_bitop3_b32 v27, v28, 3, v27 bitop3:0xc8
	v_pk_sub_u16 v28, v7, v0 clamp
	v_pk_min_u16 v28, v28, v235
	v_pk_sub_u16 v29, v0, v7 clamp
	v_pk_min_u16 v29, v29, v235
	v_cmp_eq_u32_e64 s[6:7], 0, v61
	v_lshrrev_b32_e32 v30, 15, v28
	v_add_u32_e32 v29, v28, v29
	v_or_b32_e32 v28, v30, v28
	v_sub_u32_e32 v29, 0x10001, v29
	v_lshlrev_b32_e32 v28, 2, v28
	v_and_or_b32 v26, v28, 12, v26
	v_lshrrev_b32_e32 v28, 15, v29
	v_or_b32_e32 v28, v28, v29
	v_lshlrev_b32_e32 v28, 2, v28
	v_and_or_b32 v27, v28, 12, v27
	v_pk_sub_u16 v28, v8, v0 clamp
	v_pk_min_u16 v28, v28, v235
	v_pk_sub_u16 v29, v0, v8 clamp
	v_pk_min_u16 v29, v29, v235
	v_cmp_ne_u32_e64 s[8:9], 0, v61
	v_add_u32_e32 v29, v28, v29
	v_sub_u32_e32 v29, 0x10001, v29
	v_lshrrev_b32_e32 v30, 15, v28
	v_or_b32_e32 v28, v30, v28
	v_lshrrev_b32_e32 v30, 15, v29
	v_or_b32_e32 v29, v30, v29
	v_pk_sub_u16 v30, v9, v0 clamp
	v_pk_min_u16 v30, v30, v235
	v_pk_sub_u16 v31, v0, v9 clamp
	v_pk_min_u16 v31, v31, v235
	v_lshlrev_b32_e32 v28, 4, v28
	v_lshrrev_b32_e32 v32, 15, v30
	v_add_u32_e32 v31, v30, v31
	v_or_b32_e32 v30, v32, v30
	v_lshlrev_b32_e32 v30, 6, v30
	v_and_b32_e32 v28, 48, v28
	v_sub_u32_e32 v31, 0x10001, v31
	v_and_b32_e32 v30, 0xc0, v30
	v_or3_b32 v51, v26, v28, v30
	v_lshrrev_b32_e32 v26, 15, v31
	v_or_b32_e32 v26, v26, v31
	v_lshlrev_b32_e32 v29, 4, v29
	v_lshlrev_b32_e32 v26, 6, v26
	v_and_b32_e32 v29, 48, v29
	v_and_b32_e32 v26, 0xc0, v26
	v_pk_sub_u16 v52, v2, v0 clamp
	v_pk_min_u16 v52, v52, v235
	v_pk_sub_u16 v53, v0, v2 clamp
	v_pk_min_u16 v53, v53, v235
	v_pk_sub_u16 v54, v3, v0 clamp
	v_pk_min_u16 v54, v54, v235
	v_pk_sub_u16 v55, v0, v3 clamp
	v_pk_min_u16 v55, v55, v235
; __device__ __forceinline__ int red32(int v) {
;     v += __builtin_amdgcn_mov_dpp(v, 0xB1, 0xf, 0xf, true);
;     v += __builtin_amdgcn_mov_dpp(v, 0x4E, 0xf, 0xf, true);
;     v += __builtin_amdgcn_mov_dpp(v, 0x141, 0xf, 0xf, true);
;     v += __builtin_amdgcn_mov_dpp(v, 0x140, 0xf, 0xf, true);
;     v += __builtin_amdgcn_ds_swizzle(v, 0x401F);
;     return v;
; }
; __device__ __forceinline__ unsigned ltu(unsigned a, unsigned b) { unsigned d; asm volatile("v_sub_u32 %0, %1, %2\n\tv_lshrrev_b32 %0, 31, %0" : "=v"(d) : "v"(a), "v"(b)); return d; }
; __device__ __forceinline__ unsigned pk_flag_gt(unsigned k2, unsigned T2, unsigned one2) { unsigned t; asm volatile("v_pk_sub_u16 %0, %1, %2 clamp\n\tv_pk_min_u16 %0, %0, %3" : "=&v"(t) : "v"(k2), "v"(T2), "v"(one2)); return t; }
; __device__ __forceinline__ int scan32_incl(int x, int lane) {
;     x += __builtin_amdgcn_update_dpp(0, x, 0x111, 0xf, 0xf, true);
;     x += __builtin_amdgcn_update_dpp(0, x, 0x112, 0xf, 0xf, true);
;     x += __builtin_amdgcn_update_dpp(0, x, 0x114, 0xf, 0xf, true);
;     x += __builtin_amdgcn_update_dpp(0, x, 0x118, 0xf, 0xf, true);
;     const int r15 = __builtin_amdgcn_readlane(x, 15), r47 = __builtin_amdgcn_readlane(x, 47);
;     x += (lane & 16) ? ((lane & 32) ? r47 : r15) : 0;
;     return x;
; }
; template <int NCH>
; __device__ __forceinline__ void idx_select(const unsigned short* sc, unsigned* bits, size_t tok0, int tid) {
;     ...
;     for (int i = 0; i < NCH; ++i) { unsigned g8 = 0u, e8 = 0u;
; #pragma unroll
;         for (int w = 0; w < 4; ++w) { const unsigned g2 = pk_flag_gt(kw[4 * i + w], T2, one2), l2 = pk_flag_gt(T2, kw[4 * i + w], one2), e2 = one2 - g2 - l2;
;             g8 |= ((g2 | (g2 >> 15)) & 3u) << (2 * w); e8 |= ((e2 | (e2 >> 15)) & 3u) << (2 * w); }
;         gm[i] = g8; em[i] = e8; cgt += __builtin_popcount(g8); }
;     const int need = 256 - red32(cgt);
;     int carry = 0;
;     unsigned char* brow = (unsigned char*)(bits + (tok0 + row) * 128);
; #pragma unroll
;     for (int i = 0; i < NCH; ++i) { const int ec = __builtin_popcount(em[i]); const int incl = scan32_incl(ec, lane);
;         const int quota = need - carry - (incl - ec);
;         unsigned se = (quota >= ec) ? em[i] : 0u;
	v_pk_sub_u16 v56, v4, v0 clamp
	v_pk_min_u16 v56, v56, v235
	v_pk_sub_u16 v57, v0, v4 clamp
	v_pk_min_u16 v57, v57, v235
	v_pk_sub_u16 v58, v5, v0 clamp
	v_pk_min_u16 v58, v58, v235
	v_pk_sub_u16 v59, v0, v5 clamp
	v_pk_min_u16 v59, v59, v235
	s_nop 0
	v_lshrrev_b32_e32 v28, 15, v54
	v_pk_sub_u16 v43, v22, v0 clamp
	v_pk_min_u16 v43, v43, v235
	v_pk_sub_u16 v44, v0, v22 clamp
	v_pk_min_u16 v44, v44, v235
	v_pk_sub_u16 v45, v23, v0 clamp
	v_pk_min_u16 v45, v45, v235
	v_pk_sub_u16 v46, v0, v23 clamp
	v_pk_min_u16 v46, v46, v235
	v_pk_sub_u16 v47, v24, v0 clamp
	v_pk_min_u16 v47, v47, v235
	v_pk_sub_u16 v48, v0, v24 clamp
	v_pk_min_u16 v48, v48, v235
	v_pk_sub_u16 v49, v25, v0 clamp
	v_pk_min_u16 v49, v49, v235
	v_pk_sub_u16 v50, v0, v25 clamp
	v_pk_min_u16 v50, v50, v235
	s_nop 0
	v_lshrrev_b32_e32 v23, 15, v45
	v_pk_sub_u16 v33, v18, v0 clamp
	v_pk_min_u16 v33, v33, v235
	v_pk_sub_u16 v34, v0, v18 clamp
	v_pk_min_u16 v34, v34, v235
	v_pk_sub_u16 v35, v19, v0 clamp
	v_pk_min_u16 v35, v35, v235
	v_pk_sub_u16 v36, v0, v19 clamp
	v_pk_min_u16 v36, v36, v235
	v_or3_b32 v60, v27, v29, v26
	v_lshrrev_b32_e32 v19, 15, v35
	v_lshrrev_b32_e32 v27, 15, v52
	v_or_b32_e32 v28, v28, v54
	v_lshrrev_b32_e32 v22, 15, v43
	v_or_b32_e32 v23, v23, v45
	v_lshrrev_b32_e32 v18, 15, v33
	v_or_b32_e32 v19, v19, v35
	v_bitop3_b32 v27, v27, 3, v52 bitop3:0xc8
	v_lshlrev_b32_e32 v28, 2, v28
	v_bitop3_b32 v22, v22, 3, v43 bitop3:0xc8
	v_lshlrev_b32_e32 v23, 2, v23
	v_bitop3_b32 v18, v18, 3, v33 bitop3:0xc8
	v_lshlrev_b32_e32 v19, 2, v19
	v_and_or_b32 v27, v28, 12, v27
	v_lshrrev_b32_e32 v28, 15, v56
	v_lshrrev_b32_e32 v29, 15, v58
	v_and_or_b32 v22, v23, 12, v22
	v_lshrrev_b32_e32 v23, 15, v47
	v_lshrrev_b32_e32 v24, 15, v49
	v_and_or_b32 v18, v19, 12, v18
	v_pk_sub_u16 v37, v20, v0 clamp
	v_pk_min_u16 v37, v37, v235
	v_pk_sub_u16 v38, v0, v20 clamp
	v_pk_min_u16 v38, v38, v235
	v_pk_sub_u16 v39, v21, v0 clamp
	v_pk_min_u16 v39, v39, v235
	v_or_b32_e32 v28, v28, v56
	v_lshrrev_b32_e32 v19, 15, v37
	v_lshrrev_b32_e32 v20, 15, v39
	v_or_b32_e32 v29, v29, v58
	v_or_b32_e32 v23, v23, v47
	v_or_b32_e32 v24, v24, v49
	v_or_b32_e32 v19, v19, v37
	v_or_b32_e32 v20, v20, v39
	v_lshlrev_b32_e32 v28, 4, v28
	v_lshlrev_b32_e32 v29, 6, v29
	v_lshlrev_b32_e32 v23, 4, v23
	v_lshlrev_b32_e32 v24, 6, v24
	v_lshlrev_b32_e32 v19, 4, v19
	v_lshlrev_b32_e32 v20, 6, v20
	v_and_b32_e32 v28, 48, v28
	v_and_b32_e32 v29, 0xc0, v29
	v_and_b32_e32 v23, 48, v23
	v_and_b32_e32 v24, 0xc0, v24
	v_and_b32_e32 v19, 48, v19
	v_and_b32_e32 v20, 0xc0, v20
	v_bcnt_u32_b32 v26, v51, 0
	v_or3_b32 v42, v27, v28, v29
	v_or3_b32 v32, v22, v23, v24
	v_or3_b32 v23, v18, v19, v20
	v_bcnt_u32_b32 v26, v42, v26
	v_bcnt_u32_b32 v22, v32, 0
	v_bcnt_u32_b32 v18, v23, 0
	v_pk_sub_u16 v40, v0, v21 clamp
	v_pk_min_u16 v40, v40, v235
	v_add3_u32 v41, v26, v22, v18
	v_pk_sub_u16 v24, v14, v0 clamp
	v_pk_min_u16 v24, v24, v235
	v_pk_sub_u16 v25, v0, v14 clamp
	v_pk_min_u16 v25, v25, v235
	v_pk_sub_u16 v26, v15, v0 clamp
	v_pk_min_u16 v26, v26, v235
	v_pk_sub_u16 v27, v0, v15 clamp
	v_pk_min_u16 v27, v27, v235
	v_pk_sub_u16 v28, v16, v0 clamp
	v_pk_min_u16 v28, v28, v235
	v_pk_sub_u16 v29, v0, v16 clamp
	v_pk_min_u16 v29, v29, v235
	s_nop 0
	v_lshrrev_b32_e32 v14, 15, v24
	v_lshrrev_b32_e32 v15, 15, v26
	v_or_b32_e32 v15, v15, v26
	v_bitop3_b32 v14, v14, 3, v24 bitop3:0xc8
	v_lshlrev_b32_e32 v15, 2, v15
	v_and_or_b32 v14, v15, 12, v14
	v_lshrrev_b32_e32 v15, 15, v28
	v_pk_sub_u16 v30, v17, v0 clamp
	v_pk_min_u16 v30, v30, v235
	v_or_b32_e32 v15, v15, v28
	v_lshrrev_b32_e32 v16, 15, v30
	v_or_b32_e32 v16, v16, v30
	v_lshlrev_b32_e32 v15, 4, v15
	v_lshlrev_b32_e32 v16, 6, v16
	v_and_b32_e32 v15, 48, v15
	v_and_b32_e32 v16, 0xc0, v16
	v_pk_sub_u16 v31, v0, v17 clamp
	v_pk_min_u16 v31, v31, v235
	v_or3_b32 v14, v14, v15, v16
	v_pk_sub_u16 v15, v10, v0 clamp
	v_pk_min_u16 v15, v15, v235
	v_pk_sub_u16 v16, v0, v10 clamp
	v_pk_min_u16 v16, v16, v235
	v_pk_sub_u16 v17, v11, v0 clamp
	v_pk_min_u16 v17, v17, v235
	v_pk_sub_u16 v18, v0, v11 clamp
	v_pk_min_u16 v18, v18, v235
	v_pk_sub_u16 v19, v12, v0 clamp
	v_pk_min_u16 v19, v19, v235
	v_pk_sub_u16 v20, v0, v12 clamp
	v_pk_min_u16 v20, v20, v235
	s_nop 0
	v_lshrrev_b32_e32 v10, 15, v15
	v_lshrrev_b32_e32 v11, 15, v17
	v_or_b32_e32 v11, v11, v17
	v_bitop3_b32 v10, v10, 3, v15 bitop3:0xc8
	v_lshlrev_b32_e32 v11, 2, v11
	v_and_or_b32 v10, v11, 12, v10
	v_lshrrev_b32_e32 v11, 15, v19
	v_pk_sub_u16 v21, v13, v0 clamp
	v_pk_min_u16 v21, v21, v235
	v_pk_sub_u16 v22, v0, v13 clamp
	v_pk_min_u16 v22, v22, v235
	v_or_b32_e32 v11, v11, v19
	v_lshrrev_b32_e32 v0, 15, v21
	v_or_b32_e32 v0, v0, v21
	v_lshlrev_b32_e32 v11, 4, v11
	v_lshlrev_b32_e32 v0, 6, v0
	v_and_b32_e32 v11, 48, v11
	v_and_b32_e32 v0, 0xc0, v0
	v_or3_b32 v0, v10, v11, v0
	v_bcnt_u32_b32 v62, v14, 0
	v_bcnt_u32_b32 v10, v0, 0
	v_add3_u32 v10, v41, v62, v10
	v_and_b32_e32 v12, 16, v182
	v_cmp_eq_u32_e64 s[4:5], 0, v12
	v_add_u32_dpp v10, v10, v10 quad_perm:[1,0,3,2] row_mask:0xf bank_mask:0xf bound_ctrl:1
	v_bcnt_u32_b32 v12, v60, 0
	v_bfe_i32 v13, v182, 4, 1
	v_add_u32_dpp v10, v10, v10 quad_perm:[2,3,0,1] row_mask:0xf bank_mask:0xf bound_ctrl:1
	s_nop 1
	v_add_u32_dpp v10, v10, v10 row_half_mirror row_mask:0xf bank_mask:0xf bound_ctrl:1
	s_nop 1
	v_add_u32_dpp v10, v10, v10 row_mirror row_mask:0xf bank_mask:0xf bound_ctrl:1
	v_mov_b32_e32 v11, v10
	s_nop 1
	v_permlane16_swap_b32_e32 v11, v10
	s_waitcnt lgkmcnt(0)
	v_add_u32_e32 v41, v10, v11
	v_mov_b32_dpp v10, v12 row_shr:1 row_mask:0xf bank_mask:0xf bound_ctrl:1
	v_bcnt_u32_b32 v10, v60, v10
	s_nop 1
	v_add_u32_dpp v10, v10, v10 row_shr:2 row_mask:0xf bank_mask:0xf bound_ctrl:1
	s_nop 1
	v_add_u32_dpp v10, v10, v10 row_shr:4 row_mask:0xf bank_mask:0xf bound_ctrl:1
	s_nop 1
	v_add_u32_dpp v10, v10, v10 row_shr:8 row_mask:0xf bank_mask:0xf bound_ctrl:1
	s_nop 0
	v_readlane_b32 s0, v10, 15
	v_readlane_b32 s1, v10, 47
	s_nop 0
	v_mov_b32_e32 v62, s0
	v_mov_b32_e32 v11, s1
	v_cndmask_b32_e64 v11, v11, v62, s[6:7]
	v_and_b32_e32 v11, v13, v11
	v_add_u32_e32 v10, v11, v10
	v_or_b32_e32 v11, 0x100, v12
	v_add_u32_e32 v13, v41, v10
	v_sub_u32_e32 v11, v11, v13
	v_cmp_lt_i32_e64 s[0:1], v11, v12
	v_cmp_lt_i32_e64 s[10:11], 0, v11
	s_and_b64 vcc, s[10:11], s[0:1]
	v_cndmask_b32_e64 v12, v60, 0, s[0:1]
	s_cbranch_vccz .LBB0_694
; template <int NCH>
; __device__ __forceinline__ void idx_select(const unsigned short* sc, unsigned* bits, size_t tok0, int tid) {
;     ...
;         if (__any(quota > 0 && quota < ec)) { unsigned m = em[i], r = 0u;
; #pragma unroll
;             for (int t = 0; t < 8; ++t) { const unsigned b = m & (0u - m); if (t < quota) r |= b; m ^= b; }
;             if (quota > 0 && quota < ec) se = r; }
	v_sub_u32_e32 v13, 0, v60
	v_and_b32_e32 v61, v60, v13
	v_bitop3_b32 v13, v60, v60, v13 bitop3:0x6c
	v_sub_u32_e32 v63, 0, v13
	v_cndmask_b32_e64 v62, 0, v61, s[10:11]
	v_bitop3_b32 v64, v61, v63, v60 bitop3:0x48
	v_cmp_lt_i32_e32 vcc, 1, v11
	v_bitop3_b32 v61, v61, v60, v63 bitop3:0x14
	v_sub_u32_e32 v63, 0, v61
	v_cndmask_b32_e32 v65, 0, v64, vcc
	v_or_b32_e32 v62, v65, v62
	v_bitop3_b32 v65, v64, v63, v13 bitop3:0x48
	v_bitop3_b32 v13, v64, v13, v63 bitop3:0x14
	v_sub_u32_e32 v63, 0, v13
	v_bitop3_b32 v64, v65, v63, v61 bitop3:0x48
	v_bitop3_b32 v61, v65, v61, v63 bitop3:0x14
	v_cmp_lt_i32_e32 vcc, 2, v11
	v_sub_u32_e32 v63, 0, v61
	s_nop 0
	v_cndmask_b32_e32 v67, 0, v65, vcc
	v_bitop3_b32 v65, v64, v63, v13 bitop3:0x48
	v_bitop3_b32 v13, v64, v13, v63 bitop3:0x14
	v_cmp_lt_i32_e32 vcc, 3, v11
	v_sub_u32_e32 v63, 0, v13
	s_nop 0
	v_cndmask_b32_e32 v69, 0, v64, vcc
	v_bitop3_b32 v64, v65, v63, v61 bitop3:0x48
	v_bitop3_b32 v61, v65, v61, v63 bitop3:0x14
	v_cmp_lt_i32_e32 vcc, 4, v11
	v_sub_u32_e32 v63, 0, v61
	v_or3_b32 v62, v62, v67, v69
	v_cndmask_b32_e32 v67, 0, v65, vcc
	v_cmp_lt_i32_e32 vcc, 5, v11
	v_bitop3_b32 v65, v64, v63, v13 bitop3:0x48
	v_bitop3_b32 v13, v64, v13, v63 bitop3:0x14
	v_cndmask_b32_e32 v69, 0, v64, vcc
	v_cmp_lt_i32_e32 vcc, 6, v11
	v_sub_u32_e32 v13, 0, v13
	v_or3_b32 v62, v62, v67, v69
	v_cndmask_b32_e32 v67, 0, v65, vcc
	v_bitop3_b32 v13, v65, v13, v61 bitop3:0x48
	v_cmp_lt_i32_e32 vcc, 7, v11
	s_nop 1
	v_cndmask_b32_e32 v11, 0, v13, vcc
	v_or3_b32 v11, v62, v67, v11
	v_cndmask_b32_e64 v11, v60, v11, s[0:1]
	v_cndmask_b32_e64 v12, v12, v11, s[10:11]

; __device__ __forceinline__ unsigned pk_flag_gt(unsigned k2, unsigned T2, unsigned one2) { unsigned t; asm volatile("v_pk_sub_u16 %0, %1, %2 clamp\n\tv_pk_min_u16 %0, %0, %3" : "=&v"(t) : "v"(k2), "v"(T2), "v"(one2)); return t; }
; __device__ __forceinline__ void pk_cnt_lt(unsigned& acc, unsigned k2, unsigned mid2, unsigned one2) {
;     unsigned t; asm volatile("v_pk_sub_u16 %0, %2, %3 clamp\n\tv_pk_min_u16 %0, %0, %4\n\tv_pk_add_u16 %1, %1, %0" : "=&v"(t), "+v"(acc) : "v"(mid2), "v"(k2), "v"(one2));
; }
; __device__ __forceinline__ int red32(int v) {
;     v += __builtin_amdgcn_mov_dpp(v, 0xB1, 0xf, 0xf, true);
;     v += __builtin_amdgcn_mov_dpp(v, 0x4E, 0xf, 0xf, true);
;     v += __builtin_amdgcn_mov_dpp(v, 0x141, 0xf, 0xf, true);
;     v += __builtin_amdgcn_mov_dpp(v, 0x140, 0xf, 0xf, true);
;     v += __builtin_amdgcn_ds_swizzle(v, 0x401F);
;     return v;
; }
; template <int NCH>
; __device__ __forceinline__ void idx_select(const unsigned short* sc, unsigned* bits, size_t tok0, int tid) {
;     ...
; #pragma unroll 1
;     for (int it = 0; it < 16; ++it) { const unsigned mid = (lo + hi_ + 1u) >> 1, mid2 = mid | (mid << 16);
;         unsigned c2a = 0u, c2b = 0u;
; #pragma unroll
;         for (int i = 0; i < 4 * NCH; i += 2) { pk_cnt_lt(c2a, kw[i], mid2, one2); pk_cnt_lt(c2b, kw[i + 1], mid2, one2); }
;         int cnt = 8 * NCH - (int)((c2a & 0xFFFFu) + (c2a >> 16) + (c2b & 0xFFFFu) + (c2b >> 16));
;         cnt = red32(cnt);
;         if (cnt >= 256) lo = mid; else hi_ = mid - 1u;
;         if (cnt == 256) hi_ = mid;
;         if (__all(lo == hi_)) break; }
;     const unsigned T = lo, T2 = T | (T << 16);
;     unsigned gm[NCH], em[NCH]; int cgt = 0;
; #pragma unroll
;     for (int i = 0; i < NCH; ++i) { unsigned g8 = 0u, e8 = 0u;
; #pragma unroll
;         for (int w = 0; w < 4; ++w) { const unsigned g2 = pk_flag_gt(kw[4 * i + w], T2, one2), l2 = pk_flag_gt(T2, kw[4 * i + w], one2), e2 = one2 - g2 - l2;
;             g8 |= ((g2 | (g2 >> 15)) & 3u) << (2 * w); e8 |= ((e2 | (e2 >> 15)) & 3u) << (2 * w); }
;         gm[i] = g8; em[i] = e8; cgt += __builtin_popcount(g8); }
.LBB0_729:
	v_add3_u32 v20, v0, v19, 1
	v_lshrrev_b32_e32 v20, 1, v20
	v_mov_b32_e32 v22, 0
	v_lshl_or_b32 v21, v20, 16, v20
	s_waitcnt lgkmcnt(3)
	v_pk_sub_u16 v23, v21, v6 clamp
	v_pk_min_u16 v23, v23, v235
	v_pk_add_u16 v22, v22, v23
	s_nop 0
	v_mov_b32_e32 v23, 0
	v_pk_sub_u16 v24, v21, v7 clamp
	v_pk_min_u16 v24, v24, v235
	v_pk_add_u16 v23, v23, v24
	v_pk_sub_u16 v24, v21, v8 clamp
	v_pk_min_u16 v24, v24, v235
	v_pk_add_u16 v22, v22, v24
	v_pk_sub_u16 v24, v21, v9 clamp
	v_pk_min_u16 v24, v24, v235
	v_pk_add_u16 v23, v23, v24
	s_waitcnt lgkmcnt(2)
	v_pk_sub_u16 v24, v21, v2 clamp
	v_pk_min_u16 v24, v24, v235
	v_pk_add_u16 v22, v22, v24
	v_pk_sub_u16 v24, v21, v3 clamp
	v_pk_min_u16 v24, v24, v235
	v_pk_add_u16 v23, v23, v24
	v_pk_sub_u16 v24, v21, v4 clamp
	v_pk_min_u16 v24, v24, v235
	v_pk_add_u16 v22, v22, v24
	v_pk_sub_u16 v24, v21, v5 clamp
	v_pk_min_u16 v24, v24, v235
	v_pk_add_u16 v23, v23, v24
	s_waitcnt lgkmcnt(1)
	v_pk_sub_u16 v24, v21, v14 clamp
	v_pk_min_u16 v24, v24, v235
	v_pk_add_u16 v22, v22, v24
	v_pk_sub_u16 v24, v21, v15 clamp
	v_pk_min_u16 v24, v24, v235
	v_pk_add_u16 v23, v23, v24
	v_pk_sub_u16 v24, v21, v16 clamp
	v_pk_min_u16 v24, v24, v235
	v_pk_add_u16 v22, v22, v24
	v_pk_sub_u16 v24, v21, v17 clamp
	v_pk_min_u16 v24, v24, v235
	v_pk_add_u16 v23, v23, v24
	s_waitcnt lgkmcnt(0)
	v_pk_sub_u16 v24, v21, v10 clamp
	v_pk_min_u16 v24, v24, v235
	v_pk_add_u16 v22, v22, v24
	v_pk_sub_u16 v24, v21, v11 clamp
	v_pk_min_u16 v24, v24, v235
	v_pk_add_u16 v23, v23, v24
	v_pk_sub_u16 v24, v21, v12 clamp
	v_pk_min_u16 v24, v24, v235
	v_pk_add_u16 v22, v22, v24
	v_pk_sub_u16 v24, v21, v13 clamp
	v_pk_min_u16 v24, v24, v235
	v_pk_add_u16 v23, v23, v24
	v_add_u32_sdwa v22, v22, v22 dst_sel:DWORD dst_unused:UNUSED_PAD src0_sel:WORD_1 src1_sel:WORD_0
	v_and_b32_e32 v21, 0xffff, v23
	v_lshrrev_b32_e32 v23, 16, v23
	v_add3_u32 v21, v22, v21, v23
	v_sub_u32_e32 v21, 32, v21
	s_nop 1
	v_add_u32_dpp v21, v21, v21 quad_perm:[1,0,3,2] row_mask:0xf bank_mask:0xf bound_ctrl:1
	s_nop 1
	v_add_u32_dpp v21, v21, v21 quad_perm:[2,3,0,1] row_mask:0xf bank_mask:0xf bound_ctrl:1
	s_nop 1
	v_add_u32_dpp v21, v21, v21 row_half_mirror row_mask:0xf bank_mask:0xf bound_ctrl:1
	s_nop 1
	v_add_u32_dpp v21, v21, v21 row_mirror row_mask:0xf bank_mask:0xf bound_ctrl:1
	v_mov_b32_e32 v22, v21
	s_nop 1
	v_permlane16_swap_b32_e32 v22, v21
	s_waitcnt lgkmcnt(0)
	v_add_u32_e32 v21, v21, v22
	v_cmp_lt_i32_e32 vcc, s88, v21
	v_add_u32_e32 v22, -1, v20
	s_nop 0
	v_cndmask_b32_e32 v19, v22, v19, vcc
	v_cndmask_b32_e32 v0, v0, v20, vcc
	v_cmp_eq_u32_e32 vcc, s33, v21
	s_nop 1
	v_cndmask_b32_e32 v19, v19, v20, vcc
	v_cmp_eq_u32_e32 vcc, v0, v19
	s_cmp_eq_u64 vcc, exec
	s_cselect_b64 s[0:1], -1, 0
	v_subrev_co_u32_e32 v18, vcc, 1, v18
	s_or_b64 s[0:1], s[0:1], vcc
	s_andn2_b64 vcc, exec, s[0:1]
	s_cbranch_vccnz .LBB0_729
	v_lshl_or_b32 v0, v0, 16, v0
	v_pk_sub_u16 v18, v6, v0 clamp
	v_pk_min_u16 v18, v18, v235
	v_pk_sub_u16 v19, v0, v6 clamp
	v_pk_min_u16 v19, v19, v235
	v_and_b32_e32 v43, 32, v182
	v_add_u32_e32 v19, v18, v19
	v_sub_u32_e32 v19, 0x10001, v19
	v_lshrrev_b32_e32 v20, 15, v18
	v_bitop3_b32 v18, v20, 3, v18 bitop3:0xc8
	v_lshrrev_b32_e32 v20, 15, v19
	v_bitop3_b32 v19, v20, 3, v19 bitop3:0xc8
	v_pk_sub_u16 v20, v7, v0 clamp
	v_pk_min_u16 v20, v20, v235
	v_pk_sub_u16 v21, v0, v7 clamp
	v_pk_min_u16 v21, v21, v235
	v_cmp_eq_u32_e64 s[6:7], 0, v43
	v_lshrrev_b32_e32 v22, 15, v20
	v_add_u32_e32 v21, v20, v21
	v_or_b32_e32 v20, v22, v20
	v_sub_u32_e32 v21, 0x10001, v21
	v_lshlrev_b32_e32 v20, 2, v20
	v_and_or_b32 v18, v20, 12, v18
	v_lshrrev_b32_e32 v20, 15, v21
	v_or_b32_e32 v20, v20, v21
	v_lshlrev_b32_e32 v20, 2, v20
	v_and_or_b32 v19, v20, 12, v19
	v_pk_sub_u16 v20, v8, v0 clamp
	v_pk_min_u16 v20, v20, v235
	v_pk_sub_u16 v21, v0, v8 clamp
	v_pk_min_u16 v21, v21, v235
	v_cmp_ne_u32_e64 s[8:9], 0, v43
	v_add_u32_e32 v21, v20, v21
	v_sub_u32_e32 v21, 0x10001, v21
	v_lshrrev_b32_e32 v22, 15, v20
	v_or_b32_e32 v20, v22, v20
	v_lshrrev_b32_e32 v22, 15, v21
	v_or_b32_e32 v21, v22, v21
	v_pk_sub_u16 v22, v9, v0 clamp
	v_pk_min_u16 v22, v22, v235
	v_pk_sub_u16 v23, v0, v9 clamp
	v_pk_min_u16 v23, v23, v235
	v_lshlrev_b32_e32 v20, 4, v20
	v_lshrrev_b32_e32 v24, 15, v22
	v_add_u32_e32 v23, v22, v23
	v_or_b32_e32 v22, v24, v22
	v_lshlrev_b32_e32 v22, 6, v22
	v_and_b32_e32 v20, 48, v20
	v_sub_u32_e32 v23, 0x10001, v23
	v_and_b32_e32 v22, 0xc0, v22
	v_or3_b32 v32, v18, v20, v22
	v_lshrrev_b32_e32 v18, 15, v23
	v_or_b32_e32 v18, v18, v23
	v_lshlrev_b32_e32 v21, 4, v21
	v_lshlrev_b32_e32 v18, 6, v18
	v_and_b32_e32 v21, 48, v21
	v_and_b32_e32 v18, 0xc0, v18
	v_pk_sub_u16 v33, v2, v0 clamp
	v_pk_min_u16 v33, v33, v235
	v_pk_sub_u16 v34, v0, v2 clamp
	v_pk_min_u16 v34, v34, v235
	v_pk_sub_u16 v35, v3, v0 clamp
	v_pk_min_u16 v35, v35, v235
	v_or3_b32 v41, v19, v21, v18
	v_lshrrev_b32_e32 v20, 15, v35
	v_lshrrev_b32_e32 v19, 15, v33
	v_pk_sub_u16 v36, v0, v3 clamp
	v_pk_min_u16 v36, v36, v235
	v_or_b32_e32 v20, v20, v35
	v_pk_sub_u16 v37, v4, v0 clamp
	v_pk_min_u16 v37, v37, v235
	v_pk_sub_u16 v38, v0, v4 clamp
	v_pk_min_u16 v38, v38, v235
	v_pk_sub_u16 v39, v5, v0 clamp
	v_pk_min_u16 v39, v39, v235
	v_pk_sub_u16 v40, v0, v5 clamp
	v_pk_min_u16 v40, v40, v235
	v_pk_sub_u16 v24, v14, v0 clamp
	v_pk_min_u16 v24, v24, v235
	v_pk_sub_u16 v25, v0, v14 clamp
	v_pk_min_u16 v25, v25, v235
; __device__ __forceinline__ int red32(int v) {
;     v += __builtin_amdgcn_mov_dpp(v, 0xB1, 0xf, 0xf, true);
;     v += __builtin_amdgcn_mov_dpp(v, 0x4E, 0xf, 0xf, true);
;     v += __builtin_amdgcn_mov_dpp(v, 0x141, 0xf, 0xf, true);
;     v += __builtin_amdgcn_mov_dpp(v, 0x140, 0xf, 0xf, true);
;     v += __builtin_amdgcn_ds_swizzle(v, 0x401F);
;     return v;
; }
; __device__ __forceinline__ unsigned ltu(unsigned a, unsigned b) { unsigned d; asm volatile("v_sub_u32 %0, %1, %2\n\tv_lshrrev_b32 %0, 31, %0" : "=v"(d) : "v"(a), "v"(b)); return d; }
; __device__ __forceinline__ unsigned pk_flag_gt(unsigned k2, unsigned T2, unsigned one2) { unsigned t; asm volatile("v_pk_sub_u16 %0, %1, %2 clamp\n\tv_pk_min_u16 %0, %0, %3" : "=&v"(t) : "v"(k2), "v"(T2), "v"(one2)); return t; }
; __device__ __forceinline__ int scan32_incl(int x, int lane) {
;     x += __builtin_amdgcn_update_dpp(0, x, 0x111, 0xf, 0xf, true);
;     x += __builtin_amdgcn_update_dpp(0, x, 0x112, 0xf, 0xf, true);
; template <int NCH>
; __device__ __forceinline__ void idx_select(const unsigned short* sc, unsigned* bits, size_t tok0, int tid) {
;     ...
;     for (int i = 0; i < NCH; ++i) { unsigned g8 = 0u, e8 = 0u;
; #pragma unroll
;         for (int w = 0; w < 4; ++w) { const unsigned g2 = pk_flag_gt(kw[4 * i + w], T2, one2), l2 = pk_flag_gt(T2, kw[4 * i + w], one2), e2 = one2 - g2 - l2;
;             g8 |= ((g2 | (g2 >> 15)) & 3u) << (2 * w); e8 |= ((e2 | (e2 >> 15)) & 3u) << (2 * w); }
;         gm[i] = g8; em[i] = e8; cgt += __builtin_popcount(g8); }
;     const int need = 256 - red32(cgt);
;     int carry = 0;
;     unsigned char* brow = (unsigned char*)(bits + (tok0 + row) * 128);
; #pragma unroll
;     for (int i = 0; i < NCH; ++i) { const int ec = __builtin_popcount(em[i]); const int incl = scan32_incl(ec, lane);
;         const int quota = need - carry - (incl - ec);
;         unsigned se = (quota >= ec) ? em[i] : 0u;
;         if (__any(quota > 0 && quota < ec)) { unsigned m = em[i], r = 0u;
; #pragma unroll
;             for (int t = 0; t < 8; ++t) { const unsigned b = m & (0u - m); if (t < quota) r |= b; m ^= b; }
;             if (quota > 0 && quota < ec) se = r; }
;         carry += (lane & 32) ? __builtin_amdgcn_readlane(incl, 63) : __builtin_amdgcn_readlane(incl, 31);
;         brow[i * 32 + j] = (unsigned char)(gm[i] | se); }
	v_pk_sub_u16 v26, v15, v0 clamp
	v_pk_min_u16 v26, v26, v235
	v_pk_sub_u16 v27, v0, v15 clamp
	v_pk_min_u16 v27, v27, v235
	v_bitop3_b32 v19, v19, 3, v33 bitop3:0xc8
	v_lshrrev_b32_e32 v15, 15, v26
	v_lshlrev_b32_e32 v20, 2, v20
	v_lshrrev_b32_e32 v14, 15, v24
	v_or_b32_e32 v15, v15, v26
	v_and_or_b32 v19, v20, 12, v19
	v_lshrrev_b32_e32 v20, 15, v37
	v_lshrrev_b32_e32 v21, 15, v39
	v_bitop3_b32 v14, v14, 3, v24 bitop3:0xc8
	v_lshlrev_b32_e32 v15, 2, v15
	v_or_b32_e32 v20, v20, v37
	v_or_b32_e32 v21, v21, v39
	v_and_or_b32 v14, v15, 12, v14
	v_pk_sub_u16 v28, v16, v0 clamp
	v_pk_min_u16 v28, v28, v235
	v_pk_sub_u16 v29, v0, v16 clamp
	v_pk_min_u16 v29, v29, v235
	v_pk_sub_u16 v30, v17, v0 clamp
	v_pk_min_u16 v30, v30, v235
	v_lshlrev_b32_e32 v20, 4, v20
	v_lshrrev_b32_e32 v15, 15, v28
	v_lshrrev_b32_e32 v16, 15, v30
	v_lshlrev_b32_e32 v21, 6, v21
	v_or_b32_e32 v15, v15, v28
	v_or_b32_e32 v16, v16, v30
	v_and_b32_e32 v20, 48, v20
	v_and_b32_e32 v21, 0xc0, v21
	v_lshlrev_b32_e32 v15, 4, v15
	v_lshlrev_b32_e32 v16, 6, v16
	v_bcnt_u32_b32 v18, v32, 0
	v_or3_b32 v23, v19, v20, v21
	v_and_b32_e32 v15, 48, v15
	v_and_b32_e32 v16, 0xc0, v16
	v_bcnt_u32_b32 v42, v23, v18
	v_pk_sub_u16 v31, v0, v17 clamp
	v_pk_min_u16 v31, v31, v235
	v_or3_b32 v14, v14, v15, v16
	v_pk_sub_u16 v15, v10, v0 clamp
	v_pk_min_u16 v15, v15, v235
	v_pk_sub_u16 v16, v0, v10 clamp
	v_pk_min_u16 v16, v16, v235
	v_pk_sub_u16 v17, v11, v0 clamp
	v_pk_min_u16 v17, v17, v235
	v_pk_sub_u16 v18, v0, v11 clamp
	v_pk_min_u16 v18, v18, v235
	v_pk_sub_u16 v19, v12, v0 clamp
	v_pk_min_u16 v19, v19, v235
	v_pk_sub_u16 v20, v0, v12 clamp
	v_pk_min_u16 v20, v20, v235
	s_nop 0
	v_lshrrev_b32_e32 v10, 15, v15
	v_lshrrev_b32_e32 v11, 15, v17
	v_or_b32_e32 v11, v11, v17
	v_bitop3_b32 v10, v10, 3, v15 bitop3:0xc8
	v_lshlrev_b32_e32 v11, 2, v11
	v_and_or_b32 v10, v11, 12, v10
	v_lshrrev_b32_e32 v11, 15, v19
	v_pk_sub_u16 v21, v13, v0 clamp
	v_pk_min_u16 v21, v21, v235
	v_pk_sub_u16 v22, v0, v13 clamp
	v_pk_min_u16 v22, v22, v235
	v_or_b32_e32 v11, v11, v19
	v_lshrrev_b32_e32 v0, 15, v21
	v_or_b32_e32 v0, v0, v21
	v_lshlrev_b32_e32 v11, 4, v11
	v_lshlrev_b32_e32 v0, 6, v0
	v_and_b32_e32 v11, 48, v11
	v_and_b32_e32 v0, 0xc0, v0
	v_or3_b32 v0, v10, v11, v0
	v_bcnt_u32_b32 v44, v14, 0
	v_bcnt_u32_b32 v10, v0, 0
	v_add3_u32 v10, v42, v44, v10
	v_and_b32_e32 v12, 16, v182
	v_cmp_eq_u32_e64 s[4:5], 0, v12
	v_add_u32_dpp v10, v10, v10 quad_perm:[1,0,3,2] row_mask:0xf bank_mask:0xf bound_ctrl:1
	v_bcnt_u32_b32 v12, v41, 0
	v_bfe_i32 v13, v182, 4, 1
	v_add_u32_dpp v10, v10, v10 quad_perm:[2,3,0,1] row_mask:0xf bank_mask:0xf bound_ctrl:1
	s_nop 1
	v_add_u32_dpp v10, v10, v10 row_half_mirror row_mask:0xf bank_mask:0xf bound_ctrl:1
	s_nop 1
	v_add_u32_dpp v10, v10, v10 row_mirror row_mask:0xf bank_mask:0xf bound_ctrl:1
	v_mov_b32_e32 v11, v10
	s_nop 1
	v_permlane16_swap_b32_e32 v11, v10
	s_waitcnt lgkmcnt(0)
	v_add_u32_e32 v42, v10, v11
	v_mov_b32_dpp v10, v12 row_shr:1 row_mask:0xf bank_mask:0xf bound_ctrl:1
	v_bcnt_u32_b32 v10, v41, v10
	s_nop 1
	v_add_u32_dpp v10, v10, v10 row_shr:2 row_mask:0xf bank_mask:0xf bound_ctrl:1
	s_nop 1
	v_add_u32_dpp v10, v10, v10 row_shr:4 row_mask:0xf bank_mask:0xf bound_ctrl:1
	s_nop 1
	v_add_u32_dpp v10, v10, v10 row_shr:8 row_mask:0xf bank_mask:0xf bound_ctrl:1
	s_nop 0
	v_readlane_b32 s0, v10, 15
	v_readlane_b32 s1, v10, 47
	s_nop 0
	v_mov_b32_e32 v44, s0
	v_mov_b32_e32 v11, s1
	v_cndmask_b32_e64 v11, v11, v44, s[6:7]
	v_and_b32_e32 v11, v13, v11
	v_add_u32_e32 v10, v11, v10
	v_or_b32_e32 v11, 0x100, v12
	v_add_u32_e32 v13, v42, v10
	v_sub_u32_e32 v11, v11, v13
	v_cmp_lt_i32_e64 s[0:1], v11, v12
	v_cmp_lt_i32_e64 s[10:11], 0, v11
	s_and_b64 vcc, s[10:11], s[0:1]
	v_cndmask_b32_e64 v12, v41, 0, s[0:1]
	s_cbranch_vccz .LBB0_732
	v_sub_u32_e32 v13, 0, v41
	v_and_b32_e32 v43, v41, v13
	v_bitop3_b32 v13, v41, v41, v13 bitop3:0x6c
	v_sub_u32_e32 v45, 0, v13
	v_cndmask_b32_e64 v44, 0, v43, s[10:11]
	v_bitop3_b32 v46, v43, v45, v41 bitop3:0x48
	v_cmp_lt_i32_e32 vcc, 1, v11
	v_bitop3_b32 v43, v43, v41, v45 bitop3:0x14
	v_sub_u32_e32 v45, 0, v43
	v_cndmask_b32_e32 v47, 0, v46, vcc
	v_or_b32_e32 v44, v47, v44
	v_bitop3_b32 v47, v46, v45, v13 bitop3:0x48
	v_bitop3_b32 v13, v46, v13, v45 bitop3:0x14
	v_sub_u32_e32 v45, 0, v13
	v_bitop3_b32 v46, v47, v45, v43 bitop3:0x48
	v_bitop3_b32 v43, v47, v43, v45 bitop3:0x14
	v_cmp_lt_i32_e32 vcc, 2, v11
	v_sub_u32_e32 v45, 0, v43
	s_nop 0
	v_cndmask_b32_e32 v48, 0, v47, vcc
	v_bitop3_b32 v47, v46, v45, v13 bitop3:0x48
	v_bitop3_b32 v13, v46, v13, v45 bitop3:0x14
	v_cmp_lt_i32_e32 vcc, 3, v11
	v_sub_u32_e32 v45, 0, v13
	s_nop 0
	v_cndmask_b32_e32 v49, 0, v46, vcc
	v_bitop3_b32 v46, v47, v45, v43 bitop3:0x48
	v_bitop3_b32 v43, v47, v43, v45 bitop3:0x14
	v_cmp_lt_i32_e32 vcc, 4, v11
	v_sub_u32_e32 v45, 0, v43
	v_or3_b32 v44, v44, v48, v49
	v_cndmask_b32_e32 v48, 0, v47, vcc
	v_cmp_lt_i32_e32 vcc, 5, v11
	v_bitop3_b32 v47, v46, v45, v13 bitop3:0x48
	v_bitop3_b32 v13, v46, v13, v45 bitop3:0x14
	v_cndmask_b32_e32 v49, 0, v46, vcc
	v_cmp_lt_i32_e32 vcc, 6, v11
	v_sub_u32_e32 v13, 0, v13
	v_or3_b32 v44, v44, v48, v49
	v_cndmask_b32_e32 v48, 0, v47, vcc
	v_bitop3_b32 v13, v47, v13, v43 bitop3:0x48
	v_cmp_lt_i32_e32 vcc, 7, v11
	s_nop 1
	v_cndmask_b32_e32 v11, 0, v13, vcc
	v_or3_b32 v11, v44, v48, v11
	v_cndmask_b32_e64 v11, v41, v11, s[0:1]
	v_cndmask_b32_e64 v12, v12, v11, s[10:11]

; __device__ __forceinline__ void pk_cnt_lt(unsigned& acc, unsigned k2, unsigned mid2, unsigned one2) {
;     unsigned t; asm volatile("v_pk_sub_u16 %0, %2, %3 clamp\n\tv_pk_min_u16 %0, %0, %4\n\tv_pk_add_u16 %1, %1, %0" : "=&v"(t), "+v"(acc) : "v"(mid2), "v"(k2), "v"(one2));
; }
; template <int NCH>
; __device__ __forceinline__ void idx_select(const unsigned short* sc, unsigned* bits, size_t tok0, int tid) {
;     ...
; #pragma unroll 1
;     for (int it = 0; it < 16; ++it) { const unsigned mid = (lo + hi_ + 1u) >> 1, mid2 = mid | (mid << 16);
;         unsigned c2a = 0u, c2b = 0u;
; #pragma unroll
;         for (int i = 0; i < 4 * NCH; i += 2) { pk_cnt_lt(c2a, kw[i], mid2, one2); pk_cnt_lt(c2b, kw[i + 1], mid2, one2); }
;         int cnt = 8 * NCH - (int)((c2a & 0xFFFFu) + (c2a >> 16) + (c2b & 0xFFFFu) + (c2b >> 16));
;         cnt = red32(cnt);
;         if (cnt >= 256) lo = mid; else hi_ = mid - 1u;
;         if (cnt == 256) hi_ = mid;
.LBB0_756:
	v_add3_u32 v69, v0, v68, 1
	v_lshrrev_b32_e32 v69, 1, v69
	s_waitcnt vmcnt(2)
	v_mov_b32_e32 v71, 0
	v_lshl_or_b32 v70, v69, 16, v69
	s_waitcnt lgkmcnt(14)
	v_pk_sub_u16 v72, v70, v6 clamp
	v_pk_min_u16 v72, v72, v235
	v_pk_add_u16 v71, v71, v72
	s_nop 0
	v_mov_b32_e32 v72, 0
	v_pk_sub_u16 v73, v70, v7 clamp
	v_pk_min_u16 v73, v73, v235
	v_pk_add_u16 v72, v72, v73
	v_pk_sub_u16 v73, v70, v8 clamp
	v_pk_min_u16 v73, v73, v235
	v_pk_add_u16 v71, v71, v73
	v_pk_sub_u16 v73, v70, v9 clamp
	v_pk_min_u16 v73, v73, v235
	v_pk_add_u16 v72, v72, v73
	v_pk_sub_u16 v73, v70, v2 clamp
	v_pk_min_u16 v73, v73, v235
	v_pk_add_u16 v71, v71, v73
	v_pk_sub_u16 v73, v70, v3 clamp
	v_pk_min_u16 v73, v73, v235
	v_pk_add_u16 v72, v72, v73
	v_pk_sub_u16 v73, v70, v4 clamp
	v_pk_min_u16 v73, v73, v235
	v_pk_add_u16 v71, v71, v73
	v_pk_sub_u16 v73, v70, v5 clamp
	v_pk_min_u16 v73, v73, v235
	v_pk_add_u16 v72, v72, v73
	s_waitcnt lgkmcnt(13)
	v_pk_sub_u16 v73, v70, v62 clamp
	v_pk_min_u16 v73, v73, v235
	v_pk_add_u16 v71, v71, v73
	v_pk_sub_u16 v73, v70, v63 clamp
	v_pk_min_u16 v73, v73, v235
	v_pk_add_u16 v72, v72, v73
	v_pk_sub_u16 v73, v70, v64 clamp
	v_pk_min_u16 v73, v73, v235
	v_pk_add_u16 v71, v71, v73
	v_pk_sub_u16 v73, v70, v65 clamp
	v_pk_min_u16 v73, v73, v235
	v_pk_add_u16 v72, v72, v73
	s_waitcnt lgkmcnt(12)
	v_pk_sub_u16 v73, v70, v58 clamp
	v_pk_min_u16 v73, v73, v235
	v_pk_add_u16 v71, v71, v73
	v_pk_sub_u16 v73, v70, v59 clamp
	v_pk_min_u16 v73, v73, v235
	v_pk_add_u16 v72, v72, v73
	v_pk_sub_u16 v73, v70, v60 clamp
	v_pk_min_u16 v73, v73, v235
	v_pk_add_u16 v71, v71, v73
	v_pk_sub_u16 v73, v70, v61 clamp
	v_pk_min_u16 v73, v73, v235
	v_pk_add_u16 v72, v72, v73
	s_waitcnt lgkmcnt(11)
	v_pk_sub_u16 v73, v70, v54 clamp
	v_pk_min_u16 v73, v73, v235
	v_pk_add_u16 v71, v71, v73
	v_pk_sub_u16 v73, v70, v55 clamp
	v_pk_min_u16 v73, v73, v235
	v_pk_add_u16 v72, v72, v73
	v_pk_sub_u16 v73, v70, v56 clamp
	v_pk_min_u16 v73, v73, v235
	v_pk_add_u16 v71, v71, v73
	v_pk_sub_u16 v73, v70, v57 clamp
	v_pk_min_u16 v73, v73, v235
	v_pk_add_u16 v72, v72, v73
	s_waitcnt lgkmcnt(10)
	v_pk_sub_u16 v73, v70, v50 clamp
	v_pk_min_u16 v73, v73, v235
	v_pk_add_u16 v71, v71, v73
	v_pk_sub_u16 v73, v70, v51 clamp
	v_pk_min_u16 v73, v73, v235
	v_pk_add_u16 v72, v72, v73
	v_pk_sub_u16 v73, v70, v52 clamp
	v_pk_min_u16 v73, v73, v235
	v_pk_add_u16 v71, v71, v73
	v_pk_sub_u16 v73, v70, v53 clamp
	v_pk_min_u16 v73, v73, v235
	v_pk_add_u16 v72, v72, v73
	s_waitcnt lgkmcnt(9)
	v_pk_sub_u16 v73, v70, v46 clamp
	v_pk_min_u16 v73, v73, v235
	v_pk_add_u16 v71, v71, v73
	v_pk_sub_u16 v73, v70, v47 clamp
	v_pk_min_u16 v73, v73, v235
	v_pk_add_u16 v72, v72, v73
	v_pk_sub_u16 v73, v70, v48 clamp
	v_pk_min_u16 v73, v73, v235
	v_pk_add_u16 v71, v71, v73
	v_pk_sub_u16 v73, v70, v49 clamp
	v_pk_min_u16 v73, v73, v235
	v_pk_add_u16 v72, v72, v73
	s_waitcnt lgkmcnt(8)
	v_pk_sub_u16 v73, v70, v42 clamp
	v_pk_min_u16 v73, v73, v235
	v_pk_add_u16 v71, v71, v73
	v_pk_sub_u16 v73, v70, v43 clamp
	v_pk_min_u16 v73, v73, v235
	v_pk_add_u16 v72, v72, v73
	v_pk_sub_u16 v73, v70, v44 clamp
	v_pk_min_u16 v73, v73, v235
	v_pk_add_u16 v71, v71, v73
	v_pk_sub_u16 v73, v70, v45 clamp
	v_pk_min_u16 v73, v73, v235
	v_pk_add_u16 v72, v72, v73
	s_waitcnt lgkmcnt(7)
	v_pk_sub_u16 v73, v70, v38 clamp
	v_pk_min_u16 v73, v73, v235
	v_pk_add_u16 v71, v71, v73
	v_pk_sub_u16 v73, v70, v39 clamp
	v_pk_min_u16 v73, v73, v235
	v_pk_add_u16 v72, v72, v73
	v_pk_sub_u16 v73, v70, v40 clamp
	v_pk_min_u16 v73, v73, v235
	v_pk_add_u16 v71, v71, v73
	v_pk_sub_u16 v73, v70, v41 clamp
	v_pk_min_u16 v73, v73, v235
	v_pk_add_u16 v72, v72, v73
	s_waitcnt lgkmcnt(6)
	v_pk_sub_u16 v73, v70, v34 clamp
	v_pk_min_u16 v73, v73, v235
	v_pk_add_u16 v71, v71, v73
	v_pk_sub_u16 v73, v70, v35 clamp
	v_pk_min_u16 v73, v73, v235
	v_pk_add_u16 v72, v72, v73
	v_pk_sub_u16 v73, v70, v36 clamp
	v_pk_min_u16 v73, v73, v235
	v_pk_add_u16 v71, v71, v73
	v_pk_sub_u16 v73, v70, v37 clamp
	v_pk_min_u16 v73, v73, v235
	v_pk_add_u16 v72, v72, v73
	s_waitcnt lgkmcnt(5)
	v_pk_sub_u16 v73, v70, v30 clamp
	v_pk_min_u16 v73, v73, v235
	v_pk_add_u16 v71, v71, v73
	v_pk_sub_u16 v73, v70, v31 clamp
	v_pk_min_u16 v73, v73, v235
	v_pk_add_u16 v72, v72, v73
	v_pk_sub_u16 v73, v70, v32 clamp
	v_pk_min_u16 v73, v73, v235
	v_pk_add_u16 v71, v71, v73
	v_pk_sub_u16 v73, v70, v33 clamp
	v_pk_min_u16 v73, v73, v235
	v_pk_add_u16 v72, v72, v73
	s_waitcnt lgkmcnt(4)
	v_pk_sub_u16 v73, v70, v26 clamp
	v_pk_min_u16 v73, v73, v235
	v_pk_add_u16 v71, v71, v73
	v_pk_sub_u16 v73, v70, v27 clamp
	v_pk_min_u16 v73, v73, v235
	v_pk_add_u16 v72, v72, v73
	v_pk_sub_u16 v73, v70, v28 clamp
	v_pk_min_u16 v73, v73, v235
	v_pk_add_u16 v71, v71, v73
	v_pk_sub_u16 v73, v70, v29 clamp
	v_pk_min_u16 v73, v73, v235
	v_pk_add_u16 v72, v72, v73
	s_waitcnt lgkmcnt(3)
	v_pk_sub_u16 v73, v70, v22 clamp
	v_pk_min_u16 v73, v73, v235
	v_pk_add_u16 v71, v71, v73
	v_pk_sub_u16 v73, v70, v23 clamp
	v_pk_min_u16 v73, v73, v235
	v_pk_add_u16 v72, v72, v73
	v_pk_sub_u16 v73, v70, v24 clamp
	v_pk_min_u16 v73, v73, v235
	v_pk_add_u16 v71, v71, v73
	v_pk_sub_u16 v73, v70, v25 clamp
	v_pk_min_u16 v73, v73, v235
	v_pk_add_u16 v72, v72, v73
	s_waitcnt lgkmcnt(2)
	v_pk_sub_u16 v73, v70, v18 clamp
	v_pk_min_u16 v73, v73, v235
	v_pk_add_u16 v71, v71, v73
	v_pk_sub_u16 v73, v70, v19 clamp
	v_pk_min_u16 v73, v73, v235
	v_pk_add_u16 v72, v72, v73
	v_pk_sub_u16 v73, v70, v20 clamp
	v_pk_min_u16 v73, v73, v235
	v_pk_add_u16 v71, v71, v73
	v_pk_sub_u16 v73, v70, v21 clamp
	v_pk_min_u16 v73, v73, v235
	v_pk_add_u16 v72, v72, v73
	s_waitcnt lgkmcnt(1)
; __device__ __forceinline__ unsigned pk_flag_gt(unsigned k2, unsigned T2, unsigned one2) { unsigned t; asm volatile("v_pk_sub_u16 %0, %1, %2 clamp\n\tv_pk_min_u16 %0, %0, %3" : "=&v"(t) : "v"(k2), "v"(T2), "v"(one2)); return t; }
; __device__ __forceinline__ int red32(int v) {
;     v += __builtin_amdgcn_mov_dpp(v, 0xB1, 0xf, 0xf, true);
;     v += __builtin_amdgcn_mov_dpp(v, 0x4E, 0xf, 0xf, true);
;     v += __builtin_amdgcn_mov_dpp(v, 0x141, 0xf, 0xf, true);
;     v += __builtin_amdgcn_mov_dpp(v, 0x140, 0xf, 0xf, true);
;     v += __builtin_amdgcn_ds_swizzle(v, 0x401F);
;     return v;
; }
; template <int NCH>
; __device__ __forceinline__ void idx_select(const unsigned short* sc, unsigned* bits, size_t tok0, int tid) {
;     ...
; #pragma unroll 1
;     for (int it = 0; it < 16; ++it) { const unsigned mid = (lo + hi_ + 1u) >> 1, mid2 = mid | (mid << 16);
;         unsigned c2a = 0u, c2b = 0u;
; #pragma unroll
;         for (int i = 0; i < 4 * NCH; i += 2) { pk_cnt_lt(c2a, kw[i], mid2, one2); pk_cnt_lt(c2b, kw[i + 1], mid2, one2); }
;         int cnt = 8 * NCH - (int)((c2a & 0xFFFFu) + (c2a >> 16) + (c2b & 0xFFFFu) + (c2b >> 16));
;         cnt = red32(cnt);
;         if (cnt >= 256) lo = mid; else hi_ = mid - 1u;
;         if (cnt == 256) hi_ = mid;
;         if (__all(lo == hi_)) break; }
;     const unsigned T = lo, T2 = T | (T << 16);
;     unsigned gm[NCH], em[NCH]; int cgt = 0;
; #pragma unroll
;     for (int i = 0; i < NCH; ++i) { unsigned g8 = 0u, e8 = 0u;
; #pragma unroll
;         for (int w = 0; w < 4; ++w) { const unsigned g2 = pk_flag_gt(kw[4 * i + w], T2, one2), l2 = pk_flag_gt(T2, kw[4 * i + w], one2), e2 = one2 - g2 - l2;
;             g8 |= ((g2 | (g2 >> 15)) & 3u) << (2 * w); e8 |= ((e2 | (e2 >> 15)) & 3u) << (2 * w); }
;         gm[i] = g8; em[i] = e8; cgt += __builtin_popcount(g8); }
	v_pk_sub_u16 v73, v70, v14 clamp
	v_pk_min_u16 v73, v73, v235
	v_pk_add_u16 v71, v71, v73
	v_pk_sub_u16 v73, v70, v15 clamp
	v_pk_min_u16 v73, v73, v235
	v_pk_add_u16 v72, v72, v73
	v_pk_sub_u16 v73, v70, v16 clamp
	v_pk_min_u16 v73, v73, v235
	v_pk_add_u16 v71, v71, v73
	v_pk_sub_u16 v73, v70, v17 clamp
	v_pk_min_u16 v73, v73, v235
	v_pk_add_u16 v72, v72, v73
	s_waitcnt lgkmcnt(0)
	v_pk_sub_u16 v73, v70, v10 clamp
	v_pk_min_u16 v73, v73, v235
	v_pk_add_u16 v71, v71, v73
	v_pk_sub_u16 v73, v70, v11 clamp
	v_pk_min_u16 v73, v73, v235
	v_pk_add_u16 v72, v72, v73
	v_pk_sub_u16 v73, v70, v12 clamp
	v_pk_min_u16 v73, v73, v235
	v_pk_add_u16 v71, v71, v73
	v_pk_sub_u16 v73, v70, v13 clamp
	v_pk_min_u16 v73, v73, v235
	v_pk_add_u16 v72, v72, v73
	v_add_u32_sdwa v71, v71, v71 dst_sel:DWORD dst_unused:UNUSED_PAD src0_sel:WORD_1 src1_sel:WORD_0
	v_and_b32_e32 v70, 0xffff, v72
	v_lshrrev_b32_e32 v72, 16, v72
	v_add3_u32 v70, v71, v70, v72
	v_sub_u32_e32 v70, 0x80, v70
	s_nop 1
	v_add_u32_dpp v70, v70, v70 quad_perm:[1,0,3,2] row_mask:0xf bank_mask:0xf bound_ctrl:1
	s_nop 1
	v_add_u32_dpp v70, v70, v70 quad_perm:[2,3,0,1] row_mask:0xf bank_mask:0xf bound_ctrl:1
	s_nop 1
	v_add_u32_dpp v70, v70, v70 row_half_mirror row_mask:0xf bank_mask:0xf bound_ctrl:1
	s_nop 1
	v_add_u32_dpp v70, v70, v70 row_mirror row_mask:0xf bank_mask:0xf bound_ctrl:1
	v_mov_b32_e32 v71, v70
	s_nop 1
	v_permlane16_swap_b32_e32 v71, v70
	s_waitcnt lgkmcnt(0)
	v_add_u32_e32 v70, v70, v71
	v_cmp_lt_i32_e32 vcc, s88, v70
	v_add_u32_e32 v71, -1, v69
	s_nop 0
	v_cndmask_b32_e32 v68, v71, v68, vcc
	v_cndmask_b32_e32 v0, v0, v69, vcc
	v_cmp_eq_u32_e32 vcc, s33, v70
	s_nop 1
	v_cndmask_b32_e32 v68, v68, v69, vcc
	v_cmp_eq_u32_e32 vcc, v0, v68
	s_cmp_eq_u64 vcc, exec
	s_cselect_b64 s[0:1], -1, 0
	v_subrev_co_u32_e32 v67, vcc, 1, v67
	s_or_b64 s[0:1], s[0:1], vcc
	s_andn2_b64 vcc, exec, s[0:1]
	s_cbranch_vccnz .LBB0_756
	v_lshl_or_b32 v0, v0, 16, v0
	v_pk_sub_u16 v67, v6, v0 clamp
	v_pk_min_u16 v67, v67, v235
	v_pk_sub_u16 v68, v0, v6 clamp
	v_pk_min_u16 v68, v68, v235
	v_and_b32_e32 v150, 32, v182
	v_add_u32_e32 v68, v67, v68
	v_sub_u32_e32 v68, 0x10001, v68
	v_lshrrev_b32_e32 v69, 15, v67
	v_bitop3_b32 v67, v69, 3, v67 bitop3:0xc8
	v_lshrrev_b32_e32 v69, 15, v68
	v_bitop3_b32 v68, v69, 3, v68 bitop3:0xc8
	v_pk_sub_u16 v69, v7, v0 clamp
	v_pk_min_u16 v69, v69, v235
	v_pk_sub_u16 v70, v0, v7 clamp
	v_pk_min_u16 v70, v70, v235
	v_cmp_eq_u32_e64 s[6:7], 0, v150
	v_lshrrev_b32_e32 v71, 15, v69
	v_add_u32_e32 v70, v69, v70
	v_or_b32_e32 v69, v71, v69
	v_sub_u32_e32 v70, 0x10001, v70
	v_lshlrev_b32_e32 v69, 2, v69
	v_and_or_b32 v67, v69, 12, v67
	v_lshrrev_b32_e32 v69, 15, v70
	v_or_b32_e32 v69, v69, v70
	v_lshlrev_b32_e32 v69, 2, v69
	v_and_or_b32 v68, v69, 12, v68
	v_pk_sub_u16 v69, v8, v0 clamp
	v_pk_min_u16 v69, v69, v235
	v_pk_sub_u16 v70, v0, v8 clamp
	v_pk_min_u16 v70, v70, v235
	v_cmp_ne_u32_e64 s[8:9], 0, v150
	v_add_u32_e32 v70, v69, v70
	v_sub_u32_e32 v70, 0x10001, v70
	v_lshrrev_b32_e32 v71, 15, v69
	v_or_b32_e32 v69, v71, v69
	v_lshrrev_b32_e32 v71, 15, v70
	v_or_b32_e32 v70, v71, v70
	v_pk_sub_u16 v71, v9, v0 clamp
	v_pk_min_u16 v71, v71, v235
	v_pk_sub_u16 v72, v0, v9 clamp
	v_pk_min_u16 v72, v72, v235
	v_lshlrev_b32_e32 v69, 4, v69
	v_lshrrev_b32_e32 v73, 15, v71
	v_add_u32_e32 v72, v71, v72
	v_or_b32_e32 v71, v73, v71
	v_lshlrev_b32_e32 v71, 6, v71
	v_and_b32_e32 v69, 48, v69
	v_sub_u32_e32 v72, 0x10001, v72
	v_and_b32_e32 v71, 0xc0, v71
	v_or3_b32 v141, v67, v69, v71
	v_lshrrev_b32_e32 v67, 15, v72
	v_or_b32_e32 v67, v67, v72
	v_lshlrev_b32_e32 v70, 4, v70
	v_lshlrev_b32_e32 v67, 6, v67
	v_and_b32_e32 v70, 48, v70
	v_and_b32_e32 v67, 0xc0, v67
	v_or3_b32 v149, v68, v70, v67
	v_pk_sub_u16 v67, v2, v0 clamp
	v_pk_min_u16 v67, v67, v235
	v_pk_sub_u16 v142, v0, v2 clamp
	v_pk_min_u16 v142, v142, v235
	v_pk_sub_u16 v143, v3, v0 clamp
	v_pk_min_u16 v143, v143, v235
	v_pk_sub_u16 v144, v0, v3 clamp
	v_pk_min_u16 v144, v144, v235
	v_pk_sub_u16 v145, v4, v0 clamp
	v_pk_min_u16 v145, v145, v235
	v_pk_sub_u16 v146, v0, v4 clamp
	v_pk_min_u16 v146, v146, v235
	v_pk_sub_u16 v147, v5, v0 clamp
	v_pk_min_u16 v147, v147, v235
	v_pk_sub_u16 v148, v0, v5 clamp
	v_pk_min_u16 v148, v148, v235
	s_nop 0
	v_lshrrev_b32_e32 v70, 15, v143
	v_pk_sub_u16 v133, v62, v0 clamp
	v_pk_min_u16 v133, v133, v235
	v_pk_sub_u16 v134, v0, v62 clamp
	v_pk_min_u16 v134, v134, v235
	v_pk_sub_u16 v135, v63, v0 clamp
	v_pk_min_u16 v135, v135, v235
	v_pk_sub_u16 v136, v0, v63 clamp
	v_pk_min_u16 v136, v136, v235
	v_pk_sub_u16 v137, v64, v0 clamp
	v_pk_min_u16 v137, v137, v235
	v_pk_sub_u16 v138, v0, v64 clamp
	v_pk_min_u16 v138, v138, v235
	v_pk_sub_u16 v139, v65, v0 clamp
	v_pk_min_u16 v139, v139, v235
	v_pk_sub_u16 v140, v0, v65 clamp
	v_pk_min_u16 v140, v140, v235
	s_nop 0
	v_lshrrev_b32_e32 v63, 15, v135
	v_pk_sub_u16 v124, v58, v0 clamp
	v_pk_min_u16 v124, v124, v235
	v_pk_sub_u16 v125, v0, v58 clamp
	v_pk_min_u16 v125, v125, v235
	v_pk_sub_u16 v126, v59, v0 clamp
	v_pk_min_u16 v126, v126, v235
	v_pk_sub_u16 v127, v0, v59 clamp
	v_pk_min_u16 v127, v127, v235
	v_lshrrev_b32_e32 v69, 15, v67
	v_lshrrev_b32_e32 v59, 15, v126
	v_or_b32_e32 v70, v70, v143
	v_lshrrev_b32_e32 v62, 15, v133
	v_or_b32_e32 v63, v63, v135
	v_lshrrev_b32_e32 v58, 15, v124
	v_or_b32_e32 v59, v59, v126
	v_pk_sub_u16 v128, v60, v0 clamp
	v_pk_min_u16 v128, v128, v235
	v_pk_sub_u16 v129, v0, v60 clamp
	v_pk_min_u16 v129, v129, v235
	v_pk_sub_u16 v130, v61, v0 clamp
	v_pk_min_u16 v130, v130, v235
	v_pk_sub_u16 v131, v0, v61 clamp
	v_pk_min_u16 v131, v131, v235
	v_pk_sub_u16 v115, v54, v0 clamp
	v_pk_min_u16 v115, v115, v235
	v_pk_sub_u16 v116, v0, v54 clamp
; __device__ __forceinline__ unsigned pk_flag_gt(unsigned k2, unsigned T2, unsigned one2) { unsigned t; asm volatile("v_pk_sub_u16 %0, %1, %2 clamp\n\tv_pk_min_u16 %0, %0, %3" : "=&v"(t) : "v"(k2), "v"(T2), "v"(one2)); return t; }
; template <int NCH>
; __device__ __forceinline__ void idx_select(const unsigned short* sc, unsigned* bits, size_t tok0, int tid) {
;     ...
;     const unsigned T = lo, T2 = T | (T << 16);
;     unsigned gm[NCH], em[NCH]; int cgt = 0;
; #pragma unroll
;     for (int i = 0; i < NCH; ++i) { unsigned g8 = 0u, e8 = 0u;
; #pragma unroll
;         for (int w = 0; w < 4; ++w) { const unsigned g2 = pk_flag_gt(kw[4 * i + w], T2, one2), l2 = pk_flag_gt(T2, kw[4 * i + w], one2), e2 = one2 - g2 - l2;
;             g8 |= ((g2 | (g2 >> 15)) & 3u) << (2 * w); e8 |= ((e2 | (e2 >> 15)) & 3u) << (2 * w); }
;         gm[i] = g8; em[i] = e8; cgt += __builtin_popcount(g8); }
	v_pk_min_u16 v116, v116, v235
	v_pk_sub_u16 v117, v55, v0 clamp
	v_pk_min_u16 v117, v117, v235
	v_pk_sub_u16 v118, v0, v55 clamp
	v_pk_min_u16 v118, v118, v235
	v_pk_sub_u16 v119, v56, v0 clamp
	v_pk_min_u16 v119, v119, v235
	v_pk_sub_u16 v120, v0, v56 clamp
	v_pk_min_u16 v120, v120, v235
	v_pk_sub_u16 v121, v57, v0 clamp
	v_pk_min_u16 v121, v121, v235
	v_pk_sub_u16 v122, v0, v57 clamp
	v_pk_min_u16 v122, v122, v235
	s_nop 0
	v_lshrrev_b32_e32 v55, 15, v117
	v_pk_sub_u16 v106, v50, v0 clamp
	v_pk_min_u16 v106, v106, v235
	v_pk_sub_u16 v107, v0, v50 clamp
	v_pk_min_u16 v107, v107, v235
	v_pk_sub_u16 v108, v51, v0 clamp
	v_pk_min_u16 v108, v108, v235
	v_pk_sub_u16 v109, v0, v51 clamp
	v_pk_min_u16 v109, v109, v235
	v_bitop3_b32 v69, v69, 3, v67 bitop3:0xc8
	v_lshrrev_b32_e32 v51, 15, v108
	v_lshlrev_b32_e32 v70, 2, v70
	v_bitop3_b32 v62, v62, 3, v133 bitop3:0xc8
	v_lshlrev_b32_e32 v63, 2, v63
	v_bitop3_b32 v58, v58, 3, v124 bitop3:0xc8
	v_lshlrev_b32_e32 v59, 2, v59
	v_lshrrev_b32_e32 v54, 15, v115
	v_or_b32_e32 v55, v55, v117
	v_lshrrev_b32_e32 v50, 15, v106
	v_or_b32_e32 v51, v51, v108
	v_pk_sub_u16 v110, v52, v0 clamp
	v_pk_min_u16 v110, v110, v235
	v_pk_sub_u16 v111, v0, v52 clamp
	v_pk_min_u16 v111, v111, v235
	v_pk_sub_u16 v112, v53, v0 clamp
	v_pk_min_u16 v112, v112, v235
	v_pk_sub_u16 v113, v0, v53 clamp
	v_pk_min_u16 v113, v113, v235
	v_pk_sub_u16 v97, v46, v0 clamp
	v_pk_min_u16 v97, v97, v235
	v_pk_sub_u16 v98, v0, v46 clamp
	v_pk_min_u16 v98, v98, v235
	v_pk_sub_u16 v99, v47, v0 clamp
	v_pk_min_u16 v99, v99, v235
	v_pk_sub_u16 v100, v0, v47 clamp
	v_pk_min_u16 v100, v100, v235
	v_pk_sub_u16 v101, v48, v0 clamp
	v_pk_min_u16 v101, v101, v235
	v_pk_sub_u16 v102, v0, v48 clamp
	v_pk_min_u16 v102, v102, v235
	v_pk_sub_u16 v103, v49, v0 clamp
	v_pk_min_u16 v103, v103, v235
	v_pk_sub_u16 v104, v0, v49 clamp
	v_pk_min_u16 v104, v104, v235
	s_nop 0
	v_lshrrev_b32_e32 v47, 15, v99
	v_pk_sub_u16 v88, v42, v0 clamp
	v_pk_min_u16 v88, v88, v235
	v_pk_sub_u16 v89, v0, v42 clamp
	v_pk_min_u16 v89, v89, v235
	v_pk_sub_u16 v90, v43, v0 clamp
	v_pk_min_u16 v90, v90, v235
	v_pk_sub_u16 v91, v0, v43 clamp
	v_pk_min_u16 v91, v91, v235
	v_and_or_b32 v69, v70, 12, v69
	v_lshrrev_b32_e32 v43, 15, v90
	v_lshrrev_b32_e32 v70, 15, v145
	v_lshrrev_b32_e32 v71, 15, v147
	v_and_or_b32 v62, v63, 12, v62
	v_lshrrev_b32_e32 v63, 15, v137
	v_lshrrev_b32_e32 v64, 15, v139
	v_and_or_b32 v58, v59, 12, v58
	v_lshrrev_b32_e32 v59, 15, v128
	v_lshrrev_b32_e32 v60, 15, v130
	v_bitop3_b32 v54, v54, 3, v115 bitop3:0xc8
	v_lshlrev_b32_e32 v55, 2, v55
	v_bitop3_b32 v50, v50, 3, v106 bitop3:0xc8
	v_lshlrev_b32_e32 v51, 2, v51
	v_lshrrev_b32_e32 v46, 15, v97
	v_or_b32_e32 v47, v47, v99
	v_lshrrev_b32_e32 v42, 15, v88
	v_or_b32_e32 v43, v43, v90
	v_or_b32_e32 v70, v70, v145
	v_or_b32_e32 v71, v71, v147
	v_or_b32_e32 v63, v63, v137
	v_or_b32_e32 v64, v64, v139
	v_or_b32_e32 v59, v59, v128
	v_or_b32_e32 v60, v60, v130
	v_and_or_b32 v54, v55, 12, v54
	v_lshrrev_b32_e32 v55, 15, v119
	v_lshrrev_b32_e32 v56, 15, v121
	v_and_or_b32 v50, v51, 12, v50
	v_lshrrev_b32_e32 v51, 15, v110
	v_lshrrev_b32_e32 v52, 15, v112
	v_bitop3_b32 v46, v46, 3, v97 bitop3:0xc8
	v_lshlrev_b32_e32 v47, 2, v47
	v_bitop3_b32 v42, v42, 3, v88 bitop3:0xc8
	v_lshlrev_b32_e32 v43, 2, v43
	v_lshlrev_b32_e32 v70, 4, v70
	v_lshlrev_b32_e32 v71, 6, v71
	v_lshlrev_b32_e32 v63, 4, v63
	v_lshlrev_b32_e32 v64, 6, v64
	v_lshlrev_b32_e32 v59, 4, v59
	v_lshlrev_b32_e32 v60, 6, v60
	v_or_b32_e32 v55, v55, v119
	v_or_b32_e32 v56, v56, v121
	v_or_b32_e32 v51, v51, v110
	v_or_b32_e32 v52, v52, v112
	v_and_or_b32 v46, v47, 12, v46
	v_lshrrev_b32_e32 v47, 15, v101
	v_lshrrev_b32_e32 v48, 15, v103
	v_and_or_b32 v42, v43, 12, v42
	v_pk_sub_u16 v92, v44, v0 clamp
	v_pk_min_u16 v92, v92, v235
	v_pk_sub_u16 v93, v0, v44 clamp
	v_pk_min_u16 v93, v93, v235
	v_pk_sub_u16 v94, v45, v0 clamp
	v_pk_min_u16 v94, v94, v235
	v_and_b32_e32 v70, 48, v70
	v_lshrrev_b32_e32 v43, 15, v92
	v_lshrrev_b32_e32 v44, 15, v94
	v_and_b32_e32 v71, 0xc0, v71
	v_and_b32_e32 v63, 48, v63
	v_and_b32_e32 v64, 0xc0, v64
	v_and_b32_e32 v59, 48, v59
	v_and_b32_e32 v60, 0xc0, v60
	v_lshlrev_b32_e32 v55, 4, v55
	v_lshlrev_b32_e32 v56, 6, v56
	v_lshlrev_b32_e32 v51, 4, v51
	v_lshlrev_b32_e32 v52, 6, v52
	v_or_b32_e32 v47, v47, v101
	v_or_b32_e32 v48, v48, v103
	v_or_b32_e32 v43, v43, v92
	v_or_b32_e32 v44, v44, v94
	v_bcnt_u32_b32 v68, v141, 0
	v_or3_b32 v132, v69, v70, v71
	v_or3_b32 v123, v62, v63, v64
	v_or3_b32 v114, v58, v59, v60
	v_and_b32_e32 v55, 48, v55
	v_and_b32_e32 v56, 0xc0, v56
	v_and_b32_e32 v51, 48, v51
	v_and_b32_e32 v52, 0xc0, v52
	v_lshlrev_b32_e32 v47, 4, v47
	v_lshlrev_b32_e32 v48, 6, v48
	v_lshlrev_b32_e32 v43, 4, v43
	v_lshlrev_b32_e32 v44, 6, v44
	v_bcnt_u32_b32 v68, v132, v68
	v_bcnt_u32_b32 v62, v123, 0
	v_bcnt_u32_b32 v58, v114, 0
	v_or3_b32 v105, v54, v55, v56
	v_or3_b32 v96, v50, v51, v52
	v_and_b32_e32 v47, 48, v47
	v_and_b32_e32 v48, 0xc0, v48
	v_and_b32_e32 v43, 48, v43
	v_and_b32_e32 v44, 0xc0, v44
	v_add3_u32 v58, v68, v62, v58
	v_bcnt_u32_b32 v54, v105, 0
	v_bcnt_u32_b32 v50, v96, 0
	v_or3_b32 v87, v46, v47, v48
	s_waitcnt vmcnt(0)
; __device__ __forceinline__ unsigned pk_flag_gt(unsigned k2, unsigned T2, unsigned one2) { unsigned t; asm volatile("v_pk_sub_u16 %0, %1, %2 clamp\n\tv_pk_min_u16 %0, %0, %3" : "=&v"(t) : "v"(k2), "v"(T2), "v"(one2)); return t; }
; template <int NCH>
; __device__ __forceinline__ void idx_select(const unsigned short* sc, unsigned* bits, size_t tok0, int tid) {
;     ...
;     const unsigned T = lo, T2 = T | (T << 16);
;     unsigned gm[NCH], em[NCH]; int cgt = 0;
; #pragma unroll
;     for (int i = 0; i < NCH; ++i) { unsigned g8 = 0u, e8 = 0u;
; #pragma unroll
;         for (int w = 0; w < 4; ++w) { const unsigned g2 = pk_flag_gt(kw[4 * i + w], T2, one2), l2 = pk_flag_gt(T2, kw[4 * i + w], one2), e2 = one2 - g2 - l2;
;             g8 |= ((g2 | (g2 >> 15)) & 3u) << (2 * w); e8 |= ((e2 | (e2 >> 15)) & 3u) << (2 * w); }
;         gm[i] = g8; em[i] = e8; cgt += __builtin_popcount(g8); }
	v_or3_b32 v78, v42, v43, v44
	v_add3_u32 v50, v58, v54, v50
	v_bcnt_u32_b32 v46, v87, 0
	v_pk_sub_u16 v95, v0, v45 clamp
	v_pk_min_u16 v95, v95, v235
	v_bcnt_u32_b32 v42, v78, 0
	v_pk_sub_u16 v79, v38, v0 clamp
	v_pk_min_u16 v79, v79, v235
	v_pk_sub_u16 v80, v0, v38 clamp
	v_pk_min_u16 v80, v80, v235
	v_pk_sub_u16 v81, v39, v0 clamp
	v_pk_min_u16 v81, v81, v235
	v_pk_sub_u16 v82, v0, v39 clamp
	v_pk_min_u16 v82, v82, v235
	v_pk_sub_u16 v83, v40, v0 clamp
	v_pk_min_u16 v83, v83, v235
	v_pk_sub_u16 v84, v0, v40 clamp
	v_pk_min_u16 v84, v84, v235
	v_pk_sub_u16 v85, v41, v0 clamp
	v_pk_min_u16 v85, v85, v235
	v_pk_sub_u16 v86, v0, v41 clamp
	v_pk_min_u16 v86, v86, v235
	s_nop 0
	v_lshrrev_b32_e32 v39, 15, v81
	v_pk_sub_u16 v70, v34, v0 clamp
	v_pk_min_u16 v70, v70, v235
	v_pk_sub_u16 v71, v0, v34 clamp
	v_pk_min_u16 v71, v71, v235
	v_pk_sub_u16 v72, v35, v0 clamp
	v_pk_min_u16 v72, v72, v235
	v_pk_sub_u16 v73, v0, v35 clamp
	v_pk_min_u16 v73, v73, v235
	v_add3_u32 v42, v50, v46, v42
	v_lshrrev_b32_e32 v35, 15, v72
	v_lshrrev_b32_e32 v38, 15, v79
	v_or_b32_e32 v39, v39, v81
	v_lshrrev_b32_e32 v34, 15, v70
	v_or_b32_e32 v35, v35, v72
	v_pk_sub_u16 v74, v36, v0 clamp
	v_pk_min_u16 v74, v74, v235
	v_pk_sub_u16 v75, v0, v36 clamp
	v_pk_min_u16 v75, v75, v235
	v_pk_sub_u16 v76, v37, v0 clamp
	v_pk_min_u16 v76, v76, v235
	v_pk_sub_u16 v77, v0, v37 clamp
	v_pk_min_u16 v77, v77, v235
	v_pk_sub_u16 v59, v30, v0 clamp
	v_pk_min_u16 v59, v59, v235
	v_pk_sub_u16 v60, v0, v30 clamp
	v_pk_min_u16 v60, v60, v235
	v_pk_sub_u16 v61, v31, v0 clamp
	v_pk_min_u16 v61, v61, v235
	v_pk_sub_u16 v62, v0, v31 clamp
	v_pk_min_u16 v62, v62, v235
	v_pk_sub_u16 v63, v32, v0 clamp
	v_pk_min_u16 v63, v63, v235
	v_pk_sub_u16 v64, v0, v32 clamp
	v_pk_min_u16 v64, v64, v235
	v_pk_sub_u16 v65, v33, v0 clamp
	v_pk_min_u16 v65, v65, v235
	v_pk_sub_u16 v68, v0, v33 clamp
	v_pk_min_u16 v68, v68, v235
	s_nop 0
	v_lshrrev_b32_e32 v31, 15, v61
	v_pk_sub_u16 v50, v26, v0 clamp
	v_pk_min_u16 v50, v50, v235
	v_pk_sub_u16 v51, v0, v26 clamp
	v_pk_min_u16 v51, v51, v235
	v_pk_sub_u16 v52, v27, v0 clamp
	v_pk_min_u16 v52, v52, v235
	v_pk_sub_u16 v53, v0, v27 clamp
	v_pk_min_u16 v53, v53, v235
	v_bitop3_b32 v38, v38, 3, v79 bitop3:0xc8
	v_lshrrev_b32_e32 v27, 15, v52
	v_lshlrev_b32_e32 v39, 2, v39
	v_bitop3_b32 v34, v34, 3, v70 bitop3:0xc8
	v_lshlrev_b32_e32 v35, 2, v35
	v_lshrrev_b32_e32 v30, 15, v59
	v_or_b32_e32 v31, v31, v61
	v_lshrrev_b32_e32 v26, 15, v50
	v_or_b32_e32 v27, v27, v52
	v_and_or_b32 v38, v39, 12, v38
	v_lshrrev_b32_e32 v39, 15, v83
	v_lshrrev_b32_e32 v40, 15, v85
	v_and_or_b32 v34, v35, 12, v34
	v_lshrrev_b32_e32 v35, 15, v74
	v_lshrrev_b32_e32 v36, 15, v76
	v_bitop3_b32 v30, v30, 3, v59 bitop3:0xc8
	v_lshlrev_b32_e32 v31, 2, v31
	v_bitop3_b32 v26, v26, 3, v50 bitop3:0xc8
	v_lshlrev_b32_e32 v27, 2, v27
	v_or_b32_e32 v39, v39, v83
	v_or_b32_e32 v40, v40, v85
	v_or_b32_e32 v35, v35, v74
	v_or_b32_e32 v36, v36, v76
	v_and_or_b32 v30, v31, 12, v30
	v_lshrrev_b32_e32 v31, 15, v63
	v_lshrrev_b32_e32 v32, 15, v65
	v_and_or_b32 v26, v27, 12, v26
	v_pk_sub_u16 v54, v28, v0 clamp
	v_pk_min_u16 v54, v54, v235
	v_pk_sub_u16 v55, v0, v28 clamp
	v_pk_min_u16 v55, v55, v235
	v_pk_sub_u16 v56, v29, v0 clamp
	v_pk_min_u16 v56, v56, v235
	v_lshlrev_b32_e32 v39, 4, v39
	v_lshrrev_b32_e32 v27, 15, v54
	v_lshrrev_b32_e32 v28, 15, v56
	v_lshlrev_b32_e32 v40, 6, v40
	v_lshlrev_b32_e32 v35, 4, v35
	v_lshlrev_b32_e32 v36, 6, v36
	v_or_b32_e32 v31, v31, v63
	v_or_b32_e32 v32, v32, v65
	v_or_b32_e32 v27, v27, v54
	v_or_b32_e32 v28, v28, v56
	v_and_b32_e32 v39, 48, v39
	v_and_b32_e32 v40, 0xc0, v40
	v_and_b32_e32 v35, 48, v35
	v_and_b32_e32 v36, 0xc0, v36
	v_lshlrev_b32_e32 v31, 4, v31
	v_lshlrev_b32_e32 v32, 6, v32
	v_lshlrev_b32_e32 v27, 4, v27
	v_lshlrev_b32_e32 v28, 6, v28
	v_or3_b32 v69, v38, v39, v40
	v_or3_b32 v58, v34, v35, v36
	v_and_b32_e32 v31, 48, v31
	v_and_b32_e32 v32, 0xc0, v32
	v_and_b32_e32 v27, 48, v27
	v_and_b32_e32 v28, 0xc0, v28
	v_bcnt_u32_b32 v38, v69, 0
	v_bcnt_u32_b32 v34, v58, 0
	v_or3_b32 v49, v30, v31, v32
	v_or3_b32 v40, v26, v27, v28
	v_add3_u32 v34, v42, v38, v34
	v_bcnt_u32_b32 v30, v49, 0
	v_bcnt_u32_b32 v26, v40, 0
	v_pk_sub_u16 v57, v0, v29 clamp
	v_pk_min_u16 v57, v57, v235
	v_add3_u32 v26, v34, v30, v26
	v_pk_sub_u16 v41, v22, v0 clamp
	v_pk_min_u16 v41, v41, v235
	v_pk_sub_u16 v42, v0, v22 clamp
	v_pk_min_u16 v42, v42, v235
	v_pk_sub_u16 v43, v23, v0 clamp
	v_pk_min_u16 v43, v43, v235
	v_pk_sub_u16 v44, v0, v23 clamp
	v_pk_min_u16 v44, v44, v235
	v_pk_sub_u16 v45, v24, v0 clamp
	v_pk_min_u16 v45, v45, v235
	v_pk_sub_u16 v46, v0, v24 clamp
	v_pk_min_u16 v46, v46, v235
	v_pk_sub_u16 v47, v25, v0 clamp
	v_pk_min_u16 v47, v47, v235
	v_pk_sub_u16 v48, v0, v25 clamp
	v_pk_min_u16 v48, v48, v235
	s_nop 0
	v_lshrrev_b32_e32 v23, 15, v43
	v_pk_sub_u16 v32, v18, v0 clamp
	v_pk_min_u16 v32, v32, v235
	v_pk_sub_u16 v33, v0, v18 clamp
	v_pk_min_u16 v33, v33, v235
	v_pk_sub_u16 v34, v19, v0 clamp
	v_pk_min_u16 v34, v34, v235
	v_pk_sub_u16 v35, v0, v19 clamp
	v_pk_min_u16 v35, v35, v235
	v_lshrrev_b32_e32 v22, 15, v41
	v_lshrrev_b32_e32 v19, 15, v34
	v_or_b32_e32 v23, v23, v43
	v_lshrrev_b32_e32 v18, 15, v32
	v_or_b32_e32 v19, v19, v34
	v_bitop3_b32 v22, v22, 3, v41 bitop3:0xc8
	v_lshlrev_b32_e32 v23, 2, v23
	v_bitop3_b32 v18, v18, 3, v32 bitop3:0xc8
	v_lshlrev_b32_e32 v19, 2, v19
	v_and_or_b32 v22, v23, 12, v22
	v_lshrrev_b32_e32 v23, 15, v45
	v_lshrrev_b32_e32 v24, 15, v47
	v_and_or_b32 v18, v19, 12, v18
	v_pk_sub_u16 v36, v20, v0 clamp
	v_pk_min_u16 v36, v36, v235
	v_pk_sub_u16 v37, v0, v20 clamp
	v_pk_min_u16 v37, v37, v235
	v_pk_sub_u16 v38, v21, v0 clamp
; __device__ __forceinline__ int red32(int v) {
;     v += __builtin_amdgcn_mov_dpp(v, 0xB1, 0xf, 0xf, true);
;     v += __builtin_amdgcn_mov_dpp(v, 0x4E, 0xf, 0xf, true);
;     v += __builtin_amdgcn_mov_dpp(v, 0x141, 0xf, 0xf, true);
;     v += __builtin_amdgcn_mov_dpp(v, 0x140, 0xf, 0xf, true);
;     v += __builtin_amdgcn_ds_swizzle(v, 0x401F);
;     return v;
; }
; __device__ __forceinline__ unsigned ltu(unsigned a, unsigned b) { unsigned d; asm volatile("v_sub_u32 %0, %1, %2\n\tv_lshrrev_b32 %0, 31, %0" : "=v"(d) : "v"(a), "v"(b)); return d; }
; __device__ __forceinline__ unsigned pk_flag_gt(unsigned k2, unsigned T2, unsigned one2) { unsigned t; asm volatile("v_pk_sub_u16 %0, %1, %2 clamp\n\tv_pk_min_u16 %0, %0, %3" : "=&v"(t) : "v"(k2), "v"(T2), "v"(one2)); return t; }
; __device__ __forceinline__ int scan32_incl(int x, int lane) {
;     x += __builtin_amdgcn_update_dpp(0, x, 0x111, 0xf, 0xf, true);
;     x += __builtin_amdgcn_update_dpp(0, x, 0x112, 0xf, 0xf, true);
; template <int NCH>
; __device__ __forceinline__ void idx_select(const unsigned short* sc, unsigned* bits, size_t tok0, int tid) {
;     ...
;     for (int i = 0; i < NCH; ++i) { unsigned g8 = 0u, e8 = 0u;
; #pragma unroll
;         for (int w = 0; w < 4; ++w) { const unsigned g2 = pk_flag_gt(kw[4 * i + w], T2, one2), l2 = pk_flag_gt(T2, kw[4 * i + w], one2), e2 = one2 - g2 - l2;
;             g8 |= ((g2 | (g2 >> 15)) & 3u) << (2 * w); e8 |= ((e2 | (e2 >> 15)) & 3u) << (2 * w); }
;         gm[i] = g8; em[i] = e8; cgt += __builtin_popcount(g8); }
;     const int need = 256 - red32(cgt);
;     int carry = 0;
;     unsigned char* brow = (unsigned char*)(bits + (tok0 + row) * 128);
; #pragma unroll
;     for (int i = 0; i < NCH; ++i) { const int ec = __builtin_popcount(em[i]); const int incl = scan32_incl(ec, lane);
;         const int quota = need - carry - (incl - ec);
;         unsigned se = (quota >= ec) ? em[i] : 0u;
;         if (__any(quota > 0 && quota < ec)) { unsigned m = em[i], r = 0u;
; #pragma unroll
;             for (int t = 0; t < 8; ++t) { const unsigned b = m & (0u - m); if (t < quota) r |= b; m ^= b; }
;             if (quota > 0 && quota < ec) se = r; }
;         carry += (lane & 32) ? __builtin_amdgcn_readlane(incl, 63) : __builtin_amdgcn_readlane(incl, 31);
;         brow[i * 32 + j] = (unsigned char)(gm[i] | se); }
	v_pk_min_u16 v38, v38, v235
	v_or_b32_e32 v23, v23, v45
	v_lshrrev_b32_e32 v19, 15, v36
	v_lshrrev_b32_e32 v20, 15, v38
	v_or_b32_e32 v24, v24, v47
	v_or_b32_e32 v19, v19, v36
	v_or_b32_e32 v20, v20, v38
	v_lshlrev_b32_e32 v23, 4, v23
	v_lshlrev_b32_e32 v24, 6, v24
	v_lshlrev_b32_e32 v19, 4, v19
	v_lshlrev_b32_e32 v20, 6, v20
	v_and_b32_e32 v23, 48, v23
	v_and_b32_e32 v24, 0xc0, v24
	v_and_b32_e32 v19, 48, v19
	v_and_b32_e32 v20, 0xc0, v20
	v_or3_b32 v31, v22, v23, v24
	v_or3_b32 v22, v18, v19, v20
	v_bcnt_u32_b32 v23, v31, 0
	v_bcnt_u32_b32 v18, v22, 0
	v_pk_sub_u16 v39, v0, v21 clamp
	v_pk_min_u16 v39, v39, v235
	v_add3_u32 v151, v26, v23, v18
	v_pk_sub_u16 v23, v14, v0 clamp
	v_pk_min_u16 v23, v23, v235
	v_pk_sub_u16 v24, v0, v14 clamp
	v_pk_min_u16 v24, v24, v235
	v_pk_sub_u16 v25, v15, v0 clamp
	v_pk_min_u16 v25, v25, v235
	v_pk_sub_u16 v26, v0, v15 clamp
	v_pk_min_u16 v26, v26, v235
	v_pk_sub_u16 v27, v16, v0 clamp
	v_pk_min_u16 v27, v27, v235
	v_pk_sub_u16 v28, v0, v16 clamp
	v_pk_min_u16 v28, v28, v235
	s_nop 0
	v_lshrrev_b32_e32 v14, 15, v23
	v_lshrrev_b32_e32 v15, 15, v25
	v_or_b32_e32 v15, v15, v25
	v_bitop3_b32 v14, v14, 3, v23 bitop3:0xc8
	v_lshlrev_b32_e32 v15, 2, v15
	v_and_or_b32 v14, v15, 12, v14
	v_lshrrev_b32_e32 v15, 15, v27
	v_pk_sub_u16 v29, v17, v0 clamp
	v_pk_min_u16 v29, v29, v235
	v_or_b32_e32 v15, v15, v27
	v_lshrrev_b32_e32 v16, 15, v29
	v_or_b32_e32 v16, v16, v29
	v_lshlrev_b32_e32 v15, 4, v15
	v_lshlrev_b32_e32 v16, 6, v16
	v_and_b32_e32 v15, 48, v15
	v_and_b32_e32 v16, 0xc0, v16
	v_pk_sub_u16 v30, v0, v17 clamp
	v_pk_min_u16 v30, v30, v235
	v_or3_b32 v14, v14, v15, v16
	v_pk_sub_u16 v15, v10, v0 clamp
	v_pk_min_u16 v15, v15, v235
	v_pk_sub_u16 v16, v0, v10 clamp
	v_pk_min_u16 v16, v16, v235
	v_pk_sub_u16 v17, v11, v0 clamp
	v_pk_min_u16 v17, v17, v235
	v_pk_sub_u16 v18, v0, v11 clamp
	v_pk_min_u16 v18, v18, v235
	v_pk_sub_u16 v19, v12, v0 clamp
	v_pk_min_u16 v19, v19, v235
	v_pk_sub_u16 v20, v0, v12 clamp
	v_pk_min_u16 v20, v20, v235
	s_nop 0
	v_lshrrev_b32_e32 v10, 15, v15
	v_lshrrev_b32_e32 v11, 15, v17
	v_or_b32_e32 v11, v11, v17
	v_bitop3_b32 v10, v10, 3, v15 bitop3:0xc8
	v_lshlrev_b32_e32 v11, 2, v11
	v_and_or_b32 v10, v11, 12, v10
	v_lshrrev_b32_e32 v11, 15, v19
	v_pk_sub_u16 v12, v13, v0 clamp
	v_pk_min_u16 v12, v12, v235
	v_pk_sub_u16 v21, v0, v13 clamp
	v_pk_min_u16 v21, v21, v235
	v_or_b32_e32 v11, v11, v19
	v_lshrrev_b32_e32 v0, 15, v12
	v_or_b32_e32 v0, v0, v12
	v_lshlrev_b32_e32 v11, 4, v11
	v_lshlrev_b32_e32 v0, 6, v0
	v_and_b32_e32 v11, 48, v11
	v_and_b32_e32 v0, 0xc0, v0
	v_or3_b32 v0, v10, v11, v0
	v_bcnt_u32_b32 v152, v14, 0
	v_bcnt_u32_b32 v10, v0, 0
	v_add3_u32 v10, v151, v152, v10
	v_and_b32_e32 v13, 16, v182
	v_cmp_eq_u32_e64 s[4:5], 0, v13
	v_add_u32_dpp v10, v10, v10 quad_perm:[1,0,3,2] row_mask:0xf bank_mask:0xf bound_ctrl:1
	v_bfe_i32 v151, v182, 4, 1
	s_nop 0
	v_add_u32_dpp v10, v10, v10 quad_perm:[2,3,0,1] row_mask:0xf bank_mask:0xf bound_ctrl:1
	s_nop 1
	v_add_u32_dpp v10, v10, v10 row_half_mirror row_mask:0xf bank_mask:0xf bound_ctrl:1
	s_nop 1
	v_add_u32_dpp v10, v10, v10 row_mirror row_mask:0xf bank_mask:0xf bound_ctrl:1
	v_mov_b32_e32 v11, v10
	s_nop 1
	v_permlane16_swap_b32_e32 v11, v10
	s_waitcnt lgkmcnt(0)
	v_add_u32_e32 v13, v10, v11
	v_bcnt_u32_b32 v10, v149, 0
	s_nop 1
	v_mov_b32_dpp v11, v10 row_shr:1 row_mask:0xf bank_mask:0xf bound_ctrl:1
	v_bcnt_u32_b32 v11, v149, v11
	s_nop 1
	v_add_u32_dpp v11, v11, v11 row_shr:2 row_mask:0xf bank_mask:0xf bound_ctrl:1
	s_nop 1
	v_add_u32_dpp v11, v11, v11 row_shr:4 row_mask:0xf bank_mask:0xf bound_ctrl:1
	s_nop 1
	v_add_u32_dpp v11, v11, v11 row_shr:8 row_mask:0xf bank_mask:0xf bound_ctrl:1
	s_nop 0
	v_readlane_b32 s0, v11, 15
	v_readlane_b32 s1, v11, 47
	s_nop 0
	v_mov_b32_e32 v153, s0
	v_mov_b32_e32 v152, s1
	v_cndmask_b32_e64 v150, v152, v153, s[6:7]
	v_and_b32_e32 v150, v151, v150
	v_add_u32_e32 v11, v150, v11
	v_or_b32_e32 v150, 0x100, v10
	v_add_u32_e32 v151, v13, v11
	v_sub_u32_e32 v150, v150, v151
	v_cmp_lt_i32_e64 s[0:1], v150, v10
	v_cmp_lt_i32_e64 s[10:11], 0, v150
	s_and_b64 vcc, s[10:11], s[0:1]
	v_cndmask_b32_e64 v10, v149, 0, s[0:1]
	s_cbranch_vccz .LBB0_759
	v_sub_u32_e32 v151, 0, v149
	v_and_b32_e32 v152, v149, v151
	v_bitop3_b32 v151, v149, v149, v151 bitop3:0x6c
	v_sub_u32_e32 v154, 0, v151
	v_cndmask_b32_e64 v153, 0, v152, s[10:11]
	v_bitop3_b32 v155, v152, v154, v149 bitop3:0x48
	v_cmp_lt_i32_e32 vcc, 1, v150
	v_bitop3_b32 v152, v152, v149, v154 bitop3:0x14
	v_sub_u32_e32 v154, 0, v152
	v_cndmask_b32_e32 v156, 0, v155, vcc
	v_or_b32_e32 v153, v156, v153
	v_bitop3_b32 v156, v155, v154, v151 bitop3:0x48
	v_bitop3_b32 v151, v155, v151, v154 bitop3:0x14
	v_sub_u32_e32 v154, 0, v151
	v_bitop3_b32 v155, v156, v154, v152 bitop3:0x48
	v_bitop3_b32 v152, v156, v152, v154 bitop3:0x14
	v_cmp_lt_i32_e32 vcc, 2, v150
	v_sub_u32_e32 v154, 0, v152
	s_nop 0
	v_cndmask_b32_e32 v157, 0, v156, vcc
	v_bitop3_b32 v156, v155, v154, v151 bitop3:0x48
	v_bitop3_b32 v151, v155, v151, v154 bitop3:0x14
	v_cmp_lt_i32_e32 vcc, 3, v150
	v_sub_u32_e32 v154, 0, v151
	s_nop 0
	v_cndmask_b32_e32 v158, 0, v155, vcc
	v_bitop3_b32 v155, v156, v154, v152 bitop3:0x48
	v_bitop3_b32 v152, v156, v152, v154 bitop3:0x14
	v_cmp_lt_i32_e32 vcc, 4, v150
	v_sub_u32_e32 v154, 0, v152
	v_or3_b32 v153, v153, v157, v158
	v_cndmask_b32_e32 v157, 0, v156, vcc
	v_cmp_lt_i32_e32 vcc, 5, v150
	v_bitop3_b32 v156, v155, v154, v151 bitop3:0x48
	v_bitop3_b32 v151, v155, v151, v154 bitop3:0x14
	v_cndmask_b32_e32 v158, 0, v155, vcc
	v_cmp_lt_i32_e32 vcc, 6, v150
	v_sub_u32_e32 v151, 0, v151
	v_or3_b32 v153, v153, v157, v158
	v_cndmask_b32_e32 v157, 0, v156, vcc
	v_bitop3_b32 v151, v156, v151, v152 bitop3:0x48
	v_cmp_lt_i32_e32 vcc, 7, v150
	s_nop 1
	v_cndmask_b32_e32 v150, 0, v151, vcc
	v_or3_b32 v150, v153, v157, v150
	v_cndmask_b32_e64 v149, v149, v150, s[0:1]
	v_cndmask_b32_e64 v10, v10, v149, s[10:11]

; __device__ __forceinline__ void pk_cnt_lt(unsigned& acc, unsigned k2, unsigned mid2, unsigned one2) {
;     unsigned t; asm volatile("v_pk_sub_u16 %0, %2, %3 clamp\n\tv_pk_min_u16 %0, %0, %4\n\tv_pk_add_u16 %1, %1, %0" : "=&v"(t), "+v"(acc) : "v"(mid2), "v"(k2), "v"(one2));
; }
; __device__ __forceinline__ int red32(int v) {
;     v += __builtin_amdgcn_mov_dpp(v, 0xB1, 0xf, 0xf, true);
;     v += __builtin_amdgcn_mov_dpp(v, 0x4E, 0xf, 0xf, true);
;     v += __builtin_amdgcn_mov_dpp(v, 0x141, 0xf, 0xf, true);
;     v += __builtin_amdgcn_mov_dpp(v, 0x140, 0xf, 0xf, true);
;     v += __builtin_amdgcn_ds_swizzle(v, 0x401F);
;     return v;
; }
; template <int NCH>
; __device__ __forceinline__ void idx_select(const unsigned short* sc, unsigned* bits, size_t tok0, int tid) {
;     ...
; #pragma unroll 1
;     for (int it = 0; it < 16; ++it) { const unsigned mid = (lo + hi_ + 1u) >> 1, mid2 = mid | (mid << 16);
;         unsigned c2a = 0u, c2b = 0u;
; #pragma unroll
;         for (int i = 0; i < 4 * NCH; i += 2) { pk_cnt_lt(c2a, kw[i], mid2, one2); pk_cnt_lt(c2b, kw[i + 1], mid2, one2); }
;         int cnt = 8 * NCH - (int)((c2a & 0xFFFFu) + (c2a >> 16) + (c2b & 0xFFFFu) + (c2b >> 16));
;         cnt = red32(cnt);
;         if (cnt >= 256) lo = mid; else hi_ = mid - 1u;
;         if (cnt == 256) hi_ = mid;
;         if (__all(lo == hi_)) break; }
.LBB0_852:
	v_add3_u32 v12, v0, v11, 1
	v_lshrrev_b32_e32 v12, 1, v12
	v_mov_b32_e32 v14, 0
	v_lshl_or_b32 v13, v12, 16, v12
	s_waitcnt lgkmcnt(1)
	v_pk_sub_u16 v15, v13, v6 clamp
	v_pk_min_u16 v15, v15, v235
	v_pk_add_u16 v14, v14, v15
	s_nop 0
	v_mov_b32_e32 v15, 0
	v_pk_sub_u16 v16, v13, v7 clamp
	v_pk_min_u16 v16, v16, v235
	v_pk_add_u16 v15, v15, v16
	v_pk_sub_u16 v16, v13, v8 clamp
	v_pk_min_u16 v16, v16, v235
	v_pk_add_u16 v14, v14, v16
	v_pk_sub_u16 v16, v13, v9 clamp
	v_pk_min_u16 v16, v16, v235
	v_pk_add_u16 v15, v15, v16
	s_waitcnt lgkmcnt(0)
	v_pk_sub_u16 v16, v13, v2 clamp
	v_pk_min_u16 v16, v16, v235
	v_pk_add_u16 v14, v14, v16
	v_pk_sub_u16 v16, v13, v3 clamp
	v_pk_min_u16 v16, v16, v235
	v_pk_add_u16 v15, v15, v16
	v_pk_sub_u16 v16, v13, v4 clamp
	v_pk_min_u16 v16, v16, v235
	v_pk_add_u16 v14, v14, v16
	v_pk_sub_u16 v16, v13, v5 clamp
	v_pk_min_u16 v16, v16, v235
	v_pk_add_u16 v15, v15, v16
	v_add_u32_sdwa v14, v14, v14 dst_sel:DWORD dst_unused:UNUSED_PAD src0_sel:WORD_1 src1_sel:WORD_0
	v_and_b32_e32 v13, 0xffff, v15
	v_lshrrev_b32_e32 v15, 16, v15
	v_add3_u32 v13, v14, v13, v15
	v_sub_u32_e32 v13, 16, v13
	s_nop 1
	v_add_u32_dpp v13, v13, v13 quad_perm:[1,0,3,2] row_mask:0xf bank_mask:0xf bound_ctrl:1
	s_nop 1
	v_add_u32_dpp v13, v13, v13 quad_perm:[2,3,0,1] row_mask:0xf bank_mask:0xf bound_ctrl:1
	s_nop 1
	v_add_u32_dpp v13, v13, v13 row_half_mirror row_mask:0xf bank_mask:0xf bound_ctrl:1
	s_nop 1
	v_add_u32_dpp v13, v13, v13 row_mirror row_mask:0xf bank_mask:0xf bound_ctrl:1
	v_mov_b32_e32 v14, v13
	s_nop 1
	v_permlane16_swap_b32_e32 v14, v13
	s_waitcnt lgkmcnt(0)
	v_add_u32_e32 v13, v13, v14
	v_cmp_lt_i32_e32 vcc, s88, v13
	v_add_u32_e32 v14, -1, v12
	s_nop 0
	v_cndmask_b32_e32 v11, v14, v11, vcc
	v_cndmask_b32_e32 v0, v0, v12, vcc
	v_cmp_eq_u32_e32 vcc, s33, v13
	s_nop 1
	v_cndmask_b32_e32 v11, v11, v12, vcc
	v_cmp_eq_u32_e32 vcc, v0, v11
	s_cmp_eq_u64 vcc, exec
	s_cselect_b64 s[0:1], -1, 0
	v_subrev_co_u32_e32 v10, vcc, 1, v10
	s_or_b64 s[0:1], s[0:1], vcc
	s_andn2_b64 vcc, exec, s[0:1]
	s_cbranch_vccnz .LBB0_852
; __device__ __forceinline__ int red32(int v) {
;     v += __builtin_amdgcn_mov_dpp(v, 0xB1, 0xf, 0xf, true);
;     v += __builtin_amdgcn_mov_dpp(v, 0x4E, 0xf, 0xf, true);
;     v += __builtin_amdgcn_mov_dpp(v, 0x141, 0xf, 0xf, true);
;     v += __builtin_amdgcn_mov_dpp(v, 0x140, 0xf, 0xf, true);
;     v += __builtin_amdgcn_ds_swizzle(v, 0x401F);
;     return v;
; }
; __device__ __forceinline__ unsigned ltu(unsigned a, unsigned b) { unsigned d; asm volatile("v_sub_u32 %0, %1, %2\n\tv_lshrrev_b32 %0, 31, %0" : "=v"(d) : "v"(a), "v"(b)); return d; }
; __device__ __forceinline__ unsigned pk_flag_gt(unsigned k2, unsigned T2, unsigned one2) { unsigned t; asm volatile("v_pk_sub_u16 %0, %1, %2 clamp\n\tv_pk_min_u16 %0, %0, %3" : "=&v"(t) : "v"(k2), "v"(T2), "v"(one2)); return t; }
; __device__ __forceinline__ int scan32_incl(int x, int lane) {
;     x += __builtin_amdgcn_update_dpp(0, x, 0x111, 0xf, 0xf, true);
; template <int NCH>
; __device__ __forceinline__ void idx_select(const unsigned short* sc, unsigned* bits, size_t tok0, int tid) {
;     ...
;     const unsigned T = lo, T2 = T | (T << 16);
;     unsigned gm[NCH], em[NCH]; int cgt = 0;
; #pragma unroll
;     for (int i = 0; i < NCH; ++i) { unsigned g8 = 0u, e8 = 0u;
; #pragma unroll
;         for (int w = 0; w < 4; ++w) { const unsigned g2 = pk_flag_gt(kw[4 * i + w], T2, one2), l2 = pk_flag_gt(T2, kw[4 * i + w], one2), e2 = one2 - g2 - l2;
;             g8 |= ((g2 | (g2 >> 15)) & 3u) << (2 * w); e8 |= ((e2 | (e2 >> 15)) & 3u) << (2 * w); }
;         gm[i] = g8; em[i] = e8; cgt += __builtin_popcount(g8); }
;     const int need = 256 - red32(cgt);
;     int carry = 0;
;     unsigned char* brow = (unsigned char*)(bits + (tok0 + row) * 128);
; #pragma unroll
;     for (int i = 0; i < NCH; ++i) { const int ec = __builtin_popcount(em[i]); const int incl = scan32_incl(ec, lane);
;         const int quota = need - carry - (incl - ec);
;         unsigned se = (quota >= ec) ? em[i] : 0u;
;         if (__any(quota > 0 && quota < ec)) { unsigned m = em[i], r = 0u;
; #pragma unroll
;             for (int t = 0; t < 8; ++t) { const unsigned b = m & (0u - m); if (t < quota) r |= b; m ^= b; }
;             if (quota > 0 && quota < ec) se = r; }
;         carry += (lane & 32) ? __builtin_amdgcn_readlane(incl, 63) : __builtin_amdgcn_readlane(incl, 31);
;         brow[i * 32 + j] = (unsigned char)(gm[i] | se); }
	v_lshl_or_b32 v0, v0, 16, v0
	v_pk_sub_u16 v10, v6, v0 clamp
	v_pk_min_u16 v10, v10, v235
	v_pk_sub_u16 v11, v0, v6 clamp
	v_pk_min_u16 v11, v11, v235
	v_and_b32_e32 v14, 32, v182
	v_add_u32_e32 v6, v10, v11
	v_sub_u32_e32 v6, 0x10001, v6
	v_lshrrev_b32_e32 v11, 15, v10
	v_bitop3_b32 v10, v11, 3, v10 bitop3:0xc8
	v_lshrrev_b32_e32 v11, 15, v6
	v_bitop3_b32 v6, v11, 3, v6 bitop3:0xc8
	v_pk_sub_u16 v11, v7, v0 clamp
	v_pk_min_u16 v11, v11, v235
	v_pk_sub_u16 v12, v0, v7 clamp
	v_pk_min_u16 v12, v12, v235
	v_cmp_eq_u32_e64 s[6:7], 0, v14
	v_add_u32_e32 v7, v11, v12
	v_lshrrev_b32_e32 v12, 15, v11
	v_or_b32_e32 v11, v12, v11
	v_sub_u32_e32 v7, 0x10001, v7
	v_lshlrev_b32_e32 v11, 2, v11
	v_and_or_b32 v10, v11, 12, v10
	v_lshrrev_b32_e32 v11, 15, v7
	v_or_b32_e32 v7, v11, v7
	v_lshlrev_b32_e32 v7, 2, v7
	v_and_or_b32 v7, v7, 12, v6
	v_pk_sub_u16 v6, v8, v0 clamp
	v_pk_min_u16 v6, v6, v235
	v_pk_sub_u16 v11, v0, v8 clamp
	v_pk_min_u16 v11, v11, v235
	v_cmp_ne_u32_e64 s[8:9], 0, v14
	v_add_u32_e32 v8, v6, v11
	v_sub_u32_e32 v8, 0x10001, v8
	v_lshrrev_b32_e32 v11, 15, v6
	v_or_b32_e32 v6, v11, v6
	v_lshrrev_b32_e32 v11, 15, v8
	v_or_b32_e32 v8, v11, v8
	v_pk_sub_u16 v11, v9, v0 clamp
	v_pk_min_u16 v11, v11, v235
	v_pk_sub_u16 v12, v0, v9 clamp
	v_pk_min_u16 v12, v12, v235
	v_lshlrev_b32_e32 v6, 4, v6
	v_add_u32_e32 v9, v11, v12
	v_lshrrev_b32_e32 v12, 15, v11
	v_or_b32_e32 v11, v12, v11
	v_lshlrev_b32_e32 v11, 6, v11
	v_and_b32_e32 v6, 48, v6
	v_sub_u32_e32 v9, 0x10001, v9
	v_and_b32_e32 v11, 0xc0, v11
	v_or3_b32 v6, v10, v6, v11
	v_lshrrev_b32_e32 v10, 15, v9
	v_or_b32_e32 v9, v10, v9
	v_lshlrev_b32_e32 v8, 4, v8
	v_lshlrev_b32_e32 v9, 6, v9
	v_and_b32_e32 v8, 48, v8
	v_and_b32_e32 v9, 0xc0, v9
	v_or3_b32 v13, v7, v8, v9
	v_pk_sub_u16 v8, v2, v0 clamp
	v_pk_min_u16 v8, v8, v235
	v_pk_sub_u16 v9, v0, v2 clamp
	v_pk_min_u16 v9, v9, v235
	v_bcnt_u32_b32 v7, v6, 0
	v_lshrrev_b32_e32 v2, 15, v8
	v_bitop3_b32 v11, v2, 3, v8 bitop3:0xc8
	v_pk_sub_u16 v2, v3, v0 clamp
	v_pk_min_u16 v2, v2, v235
	v_pk_sub_u16 v10, v0, v3 clamp
	v_pk_min_u16 v10, v10, v235
	s_nop 0
	v_lshrrev_b32_e32 v3, 15, v2
	v_or_b32_e32 v3, v3, v2
	v_lshlrev_b32_e32 v3, 2, v3
	v_and_or_b32 v15, v3, 12, v11
	v_pk_sub_u16 v3, v4, v0 clamp
	v_pk_min_u16 v3, v3, v235
	v_pk_sub_u16 v11, v0, v4 clamp
	v_pk_min_u16 v11, v11, v235
	s_nop 0
	v_lshrrev_b32_e32 v4, 15, v3
	v_or_b32_e32 v4, v4, v3
	v_lshlrev_b32_e32 v4, 4, v4
	v_and_b32_e32 v16, 48, v4
	v_pk_sub_u16 v4, v5, v0 clamp
	v_pk_min_u16 v4, v4, v235
	v_pk_sub_u16 v12, v0, v5 clamp
	v_pk_min_u16 v12, v12, v235
	s_nop 0
	v_lshrrev_b32_e32 v0, 15, v4
	v_or_b32_e32 v0, v0, v4
	v_lshlrev_b32_e32 v0, 6, v0
	v_and_b32_e32 v0, 0xc0, v0
	v_or3_b32 v0, v15, v16, v0
	v_bcnt_u32_b32 v5, v0, v7
	v_and_b32_e32 v15, 16, v182
	v_cmp_eq_u32_e64 s[4:5], 0, v15
	v_add_u32_dpp v5, v5, v5 quad_perm:[1,0,3,2] row_mask:0xf bank_mask:0xf bound_ctrl:1
	v_bfe_i32 v16, v182, 4, 1
	s_nop 0
	v_add_u32_dpp v5, v5, v5 quad_perm:[2,3,0,1] row_mask:0xf bank_mask:0xf bound_ctrl:1
	s_nop 1
	v_add_u32_dpp v5, v5, v5 row_half_mirror row_mask:0xf bank_mask:0xf bound_ctrl:1
	s_nop 1
	v_add_u32_dpp v5, v5, v5 row_mirror row_mask:0xf bank_mask:0xf bound_ctrl:1
	v_mov_b32_e32 v7, v5
	s_nop 1
	v_permlane16_swap_b32_e32 v7, v5
	s_waitcnt lgkmcnt(0)
	v_add_u32_e32 v7, v5, v7
	v_bcnt_u32_b32 v5, v13, 0
	s_nop 1
	v_mov_b32_dpp v15, v5 row_shr:1 row_mask:0xf bank_mask:0xf bound_ctrl:1
	v_bcnt_u32_b32 v15, v13, v15
	s_nop 1
	v_add_u32_dpp v15, v15, v15 row_shr:2 row_mask:0xf bank_mask:0xf bound_ctrl:1
	s_nop 1
	v_add_u32_dpp v15, v15, v15 row_shr:4 row_mask:0xf bank_mask:0xf bound_ctrl:1
	s_nop 1
	v_add_u32_dpp v15, v15, v15 row_shr:8 row_mask:0xf bank_mask:0xf bound_ctrl:1
	s_nop 0
	v_readlane_b32 s0, v15, 15
	v_readlane_b32 s1, v15, 47
	s_nop 0
	v_mov_b32_e32 v18, s0
	v_mov_b32_e32 v17, s1
	v_cndmask_b32_e64 v14, v17, v18, s[6:7]
	v_and_b32_e32 v14, v16, v14
	v_add_u32_e32 v14, v14, v15
	v_or_b32_e32 v15, 0x100, v5
	v_add_u32_e32 v16, v7, v14
	v_sub_u32_e32 v15, v15, v16
	v_cmp_lt_i32_e64 s[0:1], v15, v5
	v_cmp_lt_i32_e64 s[10:11], 0, v15
	s_and_b64 vcc, s[10:11], s[0:1]
	v_cndmask_b32_e64 v5, v13, 0, s[0:1]
	s_cbranch_vccz .LBB0_855
	v_sub_u32_e32 v16, 0, v13
	v_and_b32_e32 v17, v13, v16
	v_bitop3_b32 v16, v13, v13, v16 bitop3:0x6c
	v_sub_u32_e32 v19, 0, v16
	v_cndmask_b32_e64 v18, 0, v17, s[10:11]
	v_bitop3_b32 v20, v17, v19, v13 bitop3:0x48
	v_cmp_lt_i32_e32 vcc, 1, v15
	v_bitop3_b32 v17, v17, v13, v19 bitop3:0x14
	v_sub_u32_e32 v19, 0, v17
	v_cndmask_b32_e32 v21, 0, v20, vcc
	v_or_b32_e32 v18, v21, v18
	v_bitop3_b32 v21, v20, v19, v16 bitop3:0x48
	v_bitop3_b32 v16, v20, v16, v19 bitop3:0x14
	v_sub_u32_e32 v19, 0, v16
	v_bitop3_b32 v20, v21, v19, v17 bitop3:0x48
	v_bitop3_b32 v17, v21, v17, v19 bitop3:0x14
	v_cmp_lt_i32_e32 vcc, 2, v15
	v_sub_u32_e32 v19, 0, v17
	s_nop 0
	v_cndmask_b32_e32 v22, 0, v21, vcc
	v_bitop3_b32 v21, v20, v19, v16 bitop3:0x48
	v_bitop3_b32 v16, v20, v16, v19 bitop3:0x14
	v_cmp_lt_i32_e32 vcc, 3, v15
	v_sub_u32_e32 v19, 0, v16
	s_nop 0
	v_cndmask_b32_e32 v23, 0, v20, vcc
	v_bitop3_b32 v20, v21, v19, v17 bitop3:0x48
	v_bitop3_b32 v17, v21, v17, v19 bitop3:0x14
	v_cmp_lt_i32_e32 vcc, 4, v15
	v_sub_u32_e32 v19, 0, v17
	v_or3_b32 v18, v18, v22, v23
	v_cndmask_b32_e32 v22, 0, v21, vcc
	v_cmp_lt_i32_e32 vcc, 5, v15
	v_bitop3_b32 v21, v20, v19, v16 bitop3:0x48
	v_bitop3_b32 v16, v20, v16, v19 bitop3:0x14
	v_cndmask_b32_e32 v23, 0, v20, vcc
	v_cmp_lt_i32_e32 vcc, 6, v15
	v_sub_u32_e32 v16, 0, v16
	v_or3_b32 v18, v18, v22, v23
	v_cndmask_b32_e32 v22, 0, v21, vcc
	v_bitop3_b32 v16, v21, v16, v17 bitop3:0x48
	v_cmp_lt_i32_e32 vcc, 7, v15
	s_nop 1
	v_cndmask_b32_e32 v15, 0, v16, vcc
	v_or3_b32 v15, v18, v22, v15
	v_cndmask_b32_e64 v13, v13, v15, s[0:1]
	v_cndmask_b32_e64 v5, v5, v13, s[10:11]
